# dn_intra prefetch waits relaxed; scan-loop store drain removed; V-cache conversion loads batched; barrier census loads batched; pool_diff rows loaded 8 at a time and warmup rows batched
# speedup vs baseline: 1.0275x; 1.0275x over previous
; __device__ __forceinline__ unsigned xb_ld(unsigned* p)              { return __hip_atomic_load(p, __ATOMIC_RELAXED, __HIP_MEMORY_SCOPE_AGENT); }
; __device__ __forceinline__ void xcd_barrier_complete(unsigned* bar, unsigned x, unsigned& nloc, unsigned& nx) {
;     const unsigned G = gridDim.x * gridDim.y * gridDim.z;
;     unsigned sum, cnt, mine, sp = 0u;
;     for (;;) {
;         sum = 0u; cnt = 0u; mine = 0u;
; #pragma unroll
;         for (unsigned j = 0; j < 16; ++j) { const unsigned c = xb_ld(&bar[XB_XCNT(j)]); sum += c; cnt += (c > 0u) ? 1u : 0u; mine = (j == x) ? c : mine; }
;         if (sum == G) break;
;         __builtin_amdgcn_s_sleep(1);
;         if ((++sp & 255u) == 0u) { if (xb_ld(&bar[XB_TMO])) break; if (sp > XB_SPIN_CAP) { atomicAdd(&bar[XB_TMO], 1u); break; } }
;     }
.LBB0_126:
	v_readlane_b32 s4, v254, 26
	v_readlane_b32 s5, v254, 27
	s_mov_b64 s[6:7], -1
	s_nop 4
	global_load_dword v0, v65, s[4:5] sc1
	v_readlane_b32 s4, v254, 28
	v_readlane_b32 s5, v254, 29
	s_nop 4
	global_load_dword v1, v65, s[4:5] sc1
	v_readlane_b32 s4, v254, 30
	v_readlane_b32 s5, v254, 31
	s_nop 4
	global_load_dword v2, v65, s[4:5] sc1
	v_readlane_b32 s4, v254, 32
	v_readlane_b32 s5, v254, 33
	s_nop 4
	global_load_dword v3, v65, s[4:5] sc1
	v_readlane_b32 s4, v254, 34
	v_readlane_b32 s5, v254, 35
	s_nop 4
	global_load_dword v4, v65, s[4:5] sc1
	v_readlane_b32 s4, v254, 36
	v_readlane_b32 s5, v254, 37
	s_nop 4
	global_load_dword v5, v65, s[4:5] sc1
	s_nop 4
	global_load_dword v6, v65, s[28:29] sc1
	v_readlane_b32 s4, v254, 43
	v_readlane_b32 s5, v254, 44
	s_nop 4
	global_load_dword v7, v65, s[4:5] sc1
	v_readlane_b32 s4, v252, 6
	v_readlane_b32 s5, v252, 7
	s_nop 4
	global_load_dword v8, v65, s[4:5] sc1
	v_readlane_b32 s4, v252, 8
	v_readlane_b32 s5, v252, 9
	s_nop 4
	global_load_dword v9, v65, s[4:5] sc1
	v_readlane_b32 s4, v252, 10
	v_readlane_b32 s5, v252, 11
	s_nop 4
	global_load_dword v10, v65, s[4:5] sc1
	v_readlane_b32 s4, v252, 12
	v_readlane_b32 s5, v252, 13
	s_nop 4
	global_load_dword v11, v65, s[4:5] sc1
	v_readlane_b32 s4, v252, 14
	v_readlane_b32 s5, v252, 15
	s_nop 4
	global_load_dword v12, v65, s[4:5] sc1
	v_readlane_b32 s4, v252, 16
	v_readlane_b32 s5, v252, 17
	s_nop 4
	global_load_dword v13, v65, s[4:5] sc1
	v_readlane_b32 s4, v252, 18
	v_readlane_b32 s5, v252, 19
	s_nop 4
	global_load_dword v14, v65, s[4:5] sc1
	v_readlane_b32 s4, v252, 20
	v_readlane_b32 s5, v252, 21
	s_nop 4
	global_load_dword v15, v65, s[4:5] sc1
	s_mov_b64 s[4:5], -1
	s_waitcnt vmcnt(0)
	v_add_u32_e32 v16, v1, v0
	v_add_u32_e32 v16, v16, v2
	v_add_u32_e32 v16, v16, v3
	v_add_u32_e32 v16, v16, v4
	v_add_u32_e32 v16, v16, v5
	v_add_u32_e32 v16, v16, v6
	v_add_u32_e32 v16, v16, v7
	v_add_u32_e32 v16, v16, v8
	v_add_u32_e32 v16, v16, v9
	v_add_u32_e32 v16, v16, v10
	v_add_u32_e32 v16, v16, v11
	v_add_u32_e32 v16, v16, v12
	v_add_u32_e32 v16, v16, v13
	v_add_u32_e32 v16, v16, v14
	v_add_u32_e32 v16, v16, v15
	v_cmp_eq_u32_e32 vcc, s12, v16
	s_cbranch_vccnz .LBB0_125
	s_and_b32 s4, s13, 0xff
	s_cmp_eq_u32 s4, 0
	s_mov_b64 s[4:5], -1
	s_mov_b64 s[10:11], -1
	s_sleep 1
	s_cbranch_scc1 .LBB0_130
	s_and_b64 vcc, exec, s[10:11]
	s_cbranch_vccz .LBB0_125

; DI int crow(int r, int hi) { return (r & 3) + 8 * (r >> 2) + 4 * hi; }
; DI void lds_barrier() { asm volatile("s_waitcnt lgkmcnt(0)" ::: "memory"); __builtin_amdgcn_s_barrier(); asm volatile("" ::: "memory"); }
; #define SC_WRITE_ST() do { _Pragma("unroll") for (int k2 = 0; k2 < 2; ++k2) { const int kb = ib * 2 + k2; _Pragma("unroll") for (int g = 0; g < 4; ++g) { u32x2 w2; w2.x = pk2(sacc[k2][4 * g], sacc[k2][4 * g + 1]); w2.y = pk2(sacc[k2][4 * g + 2], sacc[k2][4 * g + 3]); \
;         *(LAS u32x2*)(L + SC_ST + (db * 32 + n31) * 272 + (kb * 32 + 8 * g + 4 * hi) * 2) = w2; } } } while (0)
; DI void dn_scan(const Params& p, LAS unsigned char* L, int tid, int wave, int lane, int bid, int G) {
;     ...
;     const int strm = w >> 6, b = (w & 63) >> 3, h = w & 7, nsteps = strm ? 1 : 64, seg0 = strm ? 512 + b : b * 64;
;     const bf16_t* PRE = (const bf16_t*)(p.ws + WS_PRE); const bf16_t* Wb = (const bf16_t*)(p.ws + WS_W); const bf16_t* ATT = (const bf16_t*)(p.out + O_VP); const float* GL = (const float*)(p.ws + WS_GL); bf16_t* XNo = (bf16_t*)(p.ws + WS_XN);
;     const int n31 = lane & 31, hi = lane >> 5, ib = wave >> 2, db = wave & 3;
;     f32x16 sacc[2];
;     { const float* S0 = p.in[4] + (size_t)(b * 8 + h) * 16384;
; #pragma unroll
;       for (int k2 = 0; k2 < 2; ++k2) { const int kb = ib * 2 + k2;
; #pragma unroll
;           for (int e = 0; e < 16; ++e) sacc[k2][e] = strm ? S0[(kb * 32 + crow(e, hi)) * 128 + db * 32 + n31] : 0.f; } }
;     u32x4 rW[2], rQ[2], rK[2], rU[2], rA;
;     ...
;     SC_LOAD(0); SC_STORE(); SC_WRITE_ST();
;     float glast_n = GL[seg0 * 8 + h];
;     lds_barrier();
.LBB0_640:
	s_lshr_b32 s0, s11, 3
	s_bfe_u32 s1, s11, 0x30003
	s_lshl_b32 s4, s0, 6
	s_add_u32 s38, s26, 0x6a00000
	s_addc_u32 s39, s27, 0
	s_add_u32 s14, s26, 0x1f00000
	s_addc_u32 s15, s27, 0
	s_and_b32 s16, s11, 7
	s_or_b32 s5, s1, 0x200
	s_and_b64 s[0:1], exec, s[30:31]
	s_cselect_b32 s17, s4, s5
	s_add_u32 s6, s28, 0x10e70000
	s_addc_u32 s7, s29, 0
	s_lshl_b32 s18, s17, 6
	s_lshl_b32 s8, s16, 8
	v_lshlrev_b32_e32 v37, 4, v103
	s_add_u32 s4, s26, s8
	v_and_b32_e32 v64, 0xf0, v37
	s_addc_u32 s5, s27, 0
	v_lshl_add_u64 v[32:33], s[4:5], 0, v[64:65]
	s_mov_b64 s[0:1], 0x12d00000
	v_lshl_add_u64 v[106:107], v[32:33], 0, s[0:1]
	s_add_u32 s0, s38, s8
	v_or_b32_e32 v38, s18, v102
	v_mov_b64_e32 v[32:33], s[38:39]
	v_ashrrev_i32_e32 v105, 4, v103
	s_addc_u32 s1, s39, 0
	v_mad_u64_u32 v[32:33], s[38:39], v38, s3, v[32:33]
	v_add_u32_e32 v38, s18, v105
	v_ashrrev_i32_e32 v39, 31, v38
	v_lshl_add_u64 v[108:109], s[0:1], 0, v[64:65]
	v_lshlrev_b64 v[40:41], 11, v[38:39]
	v_lshl_add_u64 v[40:41], v[106:107], 0, v[40:41]
	v_mad_i64_i32 v[38:39], s[38:39], v38, s3, v[108:109]
	v_ashrrev_i32_e32 v42, 3, v103
	global_load_dwordx4 v[66:69], v[40:41], off
	global_load_dwordx4 v[70:73], v[38:39], off
	v_add_co_u32_e32 v38, vcc, s45, v38
	v_and_b32_e32 v110, -8, v42
	v_add_u32_e32 v43, 0x200, v103
	v_lshl_add_u64 v[32:33], v[32:33], 0, s[8:9]
	v_addc_co_u32_e32 v39, vcc, 0, v39, vcc
	v_ashrrev_i32_e32 v111, 31, v110
	v_ashrrev_i32_e32 v120, 4, v43
	v_lshl_add_u64 v[40:41], v[110:111], 1, v[32:33]
	global_load_dwordx4 v[74:77], v[38:39], off
	global_load_dwordx4 v[78:81], v[40:41], off offset:2048
	v_add_u32_e32 v38, s18, v120
	v_ashrrev_i32_e32 v39, 31, v38
	v_lshlrev_b64 v[40:41], 11, v[38:39]
	v_lshl_add_u64 v[40:41], v[106:107], 0, v[40:41]
	v_mad_i64_i32 v[38:39], s[38:39], v38, s3, v[108:109]
	global_load_dwordx4 v[82:85], v[40:41], off
	global_load_dwordx4 v[86:89], v[38:39], off
	v_ashrrev_i32_e32 v40, 3, v43
	v_and_b32_e32 v112, -8, v40
	v_add_co_u32_e32 v38, vcc, s45, v38
	v_ashrrev_i32_e32 v113, 31, v112
	s_lshl_b32 s8, s17, 3
	v_addc_co_u32_e32 v39, vcc, 0, v39, vcc
	v_lshl_add_u64 v[32:33], v[112:113], 1, v[32:33]
	s_or_b32 s8, s8, s16
	global_load_dwordx4 v[90:93], v[38:39], off
	global_load_dwordx4 v[94:97], v[32:33], off offset:2048
	s_lshl_b64 s[38:39], s[8:9], 13
	v_lshlrev_b32_e32 v32, 6, v42
	s_add_u32 s38, s6, s38
	v_ashrrev_i32_e32 v33, 31, v32
	s_addc_u32 s39, s7, s39
	v_lshlrev_b64 v[32:33], 1, v[32:33]
	v_lshl_add_u64 v[38:39], s[38:39], 0, v[32:33]
	v_and_b32_e32 v40, 0x70, v37
	v_mov_b32_e32 v41, v65
	v_lshl_add_u64 v[38:39], v[38:39], 0, v[40:41]
	global_load_dwordx4 v[98:101], v[38:39], off
	v_mul_lo_u32 v38, v105, s84
	v_add_u32_e32 v39, 0, v64
	s_movk_i32 s46, 0x90
	v_add_u32_e32 v121, v39, v38
	v_mul_lo_u32 v38, v120, s84
	s_lshl_b32 s18, s19, 7
	v_lshl_add_u32 v37, v102, 1, 0
	v_mul_lo_u32 v43, v110, s46
	v_add_u32_e32 v123, v39, v38
	v_mul_lo_u32 v38, v112, s46
	s_add_i32 s18, s18, 0
	v_add_u32_e32 v122, v37, v43
	v_add_u32_e32 v124, v37, v38
	v_mul_lo_u32 v37, v42, s46
	s_add_i32 s18, s18, 0x13800
	v_add_u32_e32 v37, 0, v37
	v_or_b32_e32 v125, s35, v34
	v_mov_b32_e32 v38, s18
	v_add_u32_e32 v126, v37, v40
	v_lshlrev_b32_e32 v37, 3, v35
	v_mad_u32_u24 v38, v125, s84, v38
	v_add_u32_e32 v127, v38, v37
	s_waitcnt vmcnt(0)
	v_cvt_pk_bf16_f32 v38, v0, v1
	v_cvt_pk_bf16_f32 v39, v2, v3
	v_cvt_pk_bf16_f32 v42, v4, v5
	v_cvt_pk_bf16_f32 v43, v6, v7
	s_waitcnt lgkmcnt(0)
	ds_write_b128 v121, v[66:69]
	ds_write_b128 v121, v[70:73] offset:17408
	ds_write_b128 v121, v[74:77] offset:62464
	ds_write_b16 v122, v78 offset:44032
	ds_write_b16_d16_hi v122, v78 offset:44176
	ds_write_b16 v122, v79 offset:44320
	ds_write_b16_d16_hi v122, v79 offset:44464
	ds_write_b16 v122, v80 offset:44608
	ds_write_b16_d16_hi v122, v80 offset:44752
	ds_write_b16 v122, v81 offset:44896
	ds_write_b16_d16_hi v122, v81 offset:45040
	ds_write_b128 v123, v[82:85]
	ds_write_b128 v123, v[86:89] offset:17408
	ds_write_b128 v123, v[90:93] offset:62464
	ds_write_b16 v124, v94 offset:44032
	ds_write_b16_d16_hi v124, v94 offset:44176
	ds_write_b16 v124, v95 offset:44320
	ds_write_b16_d16_hi v124, v95 offset:44464
	ds_write_b16 v124, v96 offset:44608
	ds_write_b16_d16_hi v124, v96 offset:44752
	ds_write_b16 v124, v97 offset:44896
	ds_write_b16_d16_hi v124, v97 offset:45040
	s_lshl_b64 s[38:39], s[8:9], 2
	s_add_u32 s38, s14, s38
	s_addc_u32 s39, s15, s39
	v_lshl_add_u64 v[32:33], s[6:7], 0, v[32:33]
	s_lshl_b32 s7, s19, 5
	v_lshl_add_u64 v[114:115], v[32:33], 0, v[40:41]
	v_or_b32_e32 v128, s7, v36
	s_lshl_b32 s8, s36, 6
	v_or_b32_e32 v32, s7, v34
	s_add_i32 s7, 0, 0x1c000
	ds_write_b128 v126, v[98:101] offset:34816
	ds_write2_b64 v127, v[38:39], v[42:43] offset1:2
	v_cvt_pk_bf16_f32 v38, v8, v9
	v_cvt_pk_bf16_f32 v39, v10, v11
	v_cvt_pk_bf16_f32 v42, v12, v13
	v_cvt_pk_bf16_f32 v43, v14, v15
	ds_write2_b64 v127, v[38:39], v[42:43] offset0:4 offset1:6
	v_cvt_pk_bf16_f32 v38, v16, v17
	v_cvt_pk_bf16_f32 v39, v18, v19
	v_cvt_pk_bf16_f32 v42, v20, v21
	v_cvt_pk_bf16_f32 v43, v22, v23
	ds_write2_b64 v127, v[38:39], v[42:43] offset0:8 offset1:10
	v_cvt_pk_bf16_f32 v38, v24, v25
	v_cvt_pk_bf16_f32 v39, v26, v27
	v_cvt_pk_bf16_f32 v42, v28, v29
	v_cvt_pk_bf16_f32 v43, v30, v31
	ds_write2_b64 v127, v[38:39], v[42:43] offset0:12 offset1:14
	v_mov_b64_e32 v[38:39], s[38:39]
	global_load_dword v118, v[38:39], off
	s_or_b32 s6, s16, 8
	s_add_i32 s8, s8, 0
	v_lshlrev_b32_e32 v129, 4, v35
	v_mov_b32_e32 v35, s7
	s_lshl_b32 s7, s35, 1
	v_mul_lo_u32 v33, v32, s84
	s_add_u32 s4, s4, s7
	v_lshlrev_b32_e32 v64, 1, v34
	v_add_u32_e32 v33, 0, v33
	v_lshlrev_b32_e32 v32, 7, v32
	s_addc_u32 s5, s5, 0
	v_sub_u32_e32 v36, v33, v32
	v_lshl_add_u64 v[32:33], s[4:5], 0, v[64:65]
	s_mov_b64 s[4:5], 0x2900000
	v_lshl_add_u64 v[116:117], v[32:33], 0, s[4:5]
	s_mul_i32 s4, s19, 0x2200
	s_waitcnt lgkmcnt(0)
	s_barrier
	v_mad_u32_u24 v130, v125, s46, v35
	v_or_b32_e32 v39, s34, v34
	v_mul_lo_u32 v32, v128, s84
	v_mov_b32_e32 v33, s4
	v_mul_u32_u24_e32 v38, 0x110, v125
	v_add_u32_e32 v35, s34, v130
	v_add_u32_e32 v40, 0, v129
	v_add3_u32 v64, s8, v64, v32
	v_mul_lo_u32 v32, v39, s46
	v_mad_u32_u24 v33, v34, s84, v33
	s_mov_b32 s18, 0
	v_add_u32_e32 v131, 0xf400, v64
	v_add3_u32 v132, v33, v129, 0
	v_add3_u32 v133, v38, v129, 0
	v_add_u32_e32 v134, v35, v37
	v_add_u32_e32 v135, v36, v129
	v_add_u32_e32 v136, v40, v32
	s_waitcnt vmcnt(0)
	s_branch .LBB0_642
; DI bf16_t f2bf(float f) { return (bf16_t)(pk2(f, 0.f) & 0xffffu); }
; DI int crow(int r, int hi) { return (r & 3) + 8 * (r >> 2) + 4 * hi; }
; DI void lds_barrier() { asm volatile("s_waitcnt lgkmcnt(0)" ::: "memory"); __builtin_amdgcn_s_barrier(); asm volatile("" ::: "memory"); }
; #define SC_WRITE_ST() do { _Pragma("unroll") for (int k2 = 0; k2 < 2; ++k2) { const int kb = ib * 2 + k2; _Pragma("unroll") for (int g = 0; g < 4; ++g) { u32x2 w2; w2.x = pk2(sacc[k2][4 * g], sacc[k2][4 * g + 1]); w2.y = pk2(sacc[k2][4 * g + 2], sacc[k2][4 * g + 3]); \
;         *(LAS u32x2*)(L + SC_ST + (db * 32 + n31) * 272 + (kb * 32 + 8 * g + 4 * hi) * 2) = w2; } } } while (0)
; DI void dn_scan(const Params& p, LAS unsigned char* L, int tid, int wave, int lane, int bid, int G) {
;     ...
;     for (int c = 0; c < nsteps; ++c) {
;         const int row0 = (seg0 + c) * 64; const float glast = glast_n;
;         if (c + 1 < nsteps) { SC_LOAD(c + 1); glast_n = GL[(seg0 + c + 1) * 8 + h]; }
;     ...
;         SC_WRITE_ST();
;         if (c + 1 < nsteps) SC_STORE();
; #pragma unroll
;         for (int e = 0; e < 16; ++e) XNo[(size_t)(row0 + ib * 32 + crow(e, hi)) * D + h * 128 + db * 32 + n31] = f2bf(oacc[e]);
;         lds_barrier();
.LBB0_641:
	v_lshl_add_u32 v48, s7, 6, v128
	v_ashrrev_i32_e32 v49, 31, v48
	v_lshlrev_b64 v[50:51], 11, v[48:49]
	s_nop 7
	v_cvt_pk_bf16_f32 v32, v32, s0
	v_lshl_add_u64 v[50:51], v[116:117], 0, v[50:51]
	global_store_short v[50:51], v32, off
	v_or_b32_e32 v32, 1, v48
	v_cvt_pk_bf16_f32 v49, v33, s0
	v_ashrrev_i32_e32 v33, 31, v32
	v_lshlrev_b64 v[32:33], 11, v[32:33]
	v_lshl_add_u64 v[32:33], v[116:117], 0, v[32:33]
	global_store_short v[32:33], v49, off
	v_or_b32_e32 v32, 2, v48
	v_ashrrev_i32_e32 v33, 31, v32
	v_lshlrev_b64 v[32:33], 11, v[32:33]
	v_cvt_pk_bf16_f32 v34, v34, s0
	v_lshl_add_u64 v[32:33], v[116:117], 0, v[32:33]
	global_store_short v[32:33], v34, off
	v_or_b32_e32 v32, 3, v48
	v_ashrrev_i32_e32 v33, 31, v32
	v_lshlrev_b64 v[32:33], 11, v[32:33]
	v_cvt_pk_bf16_f32 v34, v35, s0
	v_lshl_add_u64 v[32:33], v[116:117], 0, v[32:33]
	global_store_short v[32:33], v34, off
	v_or_b32_e32 v32, 8, v48
	v_ashrrev_i32_e32 v33, 31, v32
	v_lshlrev_b64 v[32:33], 11, v[32:33]
	v_cvt_pk_bf16_f32 v34, v36, s0
	v_lshl_add_u64 v[32:33], v[116:117], 0, v[32:33]
	global_store_short v[32:33], v34, off
	v_or_b32_e32 v32, 9, v48
	v_ashrrev_i32_e32 v33, 31, v32
	v_lshlrev_b64 v[32:33], 11, v[32:33]
	v_cvt_pk_bf16_f32 v34, v37, s0
	v_lshl_add_u64 v[32:33], v[116:117], 0, v[32:33]
	global_store_short v[32:33], v34, off
	v_or_b32_e32 v32, 10, v48
	v_ashrrev_i32_e32 v33, 31, v32
	v_lshlrev_b64 v[32:33], 11, v[32:33]
	v_cvt_pk_bf16_f32 v34, v38, s0
	v_lshl_add_u64 v[32:33], v[116:117], 0, v[32:33]
	global_store_short v[32:33], v34, off
	v_or_b32_e32 v32, 11, v48
	v_ashrrev_i32_e32 v33, 31, v32
	v_lshlrev_b64 v[32:33], 11, v[32:33]
	v_cvt_pk_bf16_f32 v34, v39, s0
	v_lshl_add_u64 v[32:33], v[116:117], 0, v[32:33]
	global_store_short v[32:33], v34, off
	v_or_b32_e32 v32, 16, v48
	v_ashrrev_i32_e32 v33, 31, v32
	v_lshlrev_b64 v[32:33], 11, v[32:33]
	v_cvt_pk_bf16_f32 v34, v40, s0
	v_lshl_add_u64 v[32:33], v[116:117], 0, v[32:33]
	global_store_short v[32:33], v34, off
	v_or_b32_e32 v32, 17, v48
	v_ashrrev_i32_e32 v33, 31, v32
	v_lshlrev_b64 v[32:33], 11, v[32:33]
	v_cvt_pk_bf16_f32 v34, v41, s0
	v_lshl_add_u64 v[32:33], v[116:117], 0, v[32:33]
	global_store_short v[32:33], v34, off
	v_or_b32_e32 v32, 18, v48
	v_ashrrev_i32_e32 v33, 31, v32
	v_lshlrev_b64 v[32:33], 11, v[32:33]
	v_cvt_pk_bf16_f32 v34, v42, s0
	v_lshl_add_u64 v[32:33], v[116:117], 0, v[32:33]
	global_store_short v[32:33], v34, off
	v_or_b32_e32 v32, 19, v48
	v_ashrrev_i32_e32 v33, 31, v32
	v_lshlrev_b64 v[32:33], 11, v[32:33]
	v_cvt_pk_bf16_f32 v34, v43, s0
	v_lshl_add_u64 v[32:33], v[116:117], 0, v[32:33]
	global_store_short v[32:33], v34, off
	v_or_b32_e32 v32, 24, v48
	v_ashrrev_i32_e32 v33, 31, v32
	v_lshlrev_b64 v[32:33], 11, v[32:33]
	v_cvt_pk_bf16_f32 v34, v44, s0
	v_lshl_add_u64 v[32:33], v[116:117], 0, v[32:33]
	global_store_short v[32:33], v34, off
	v_or_b32_e32 v32, 25, v48
	v_ashrrev_i32_e32 v33, 31, v32
	v_lshlrev_b64 v[32:33], 11, v[32:33]
	v_cvt_pk_bf16_f32 v34, v45, s0
	v_lshl_add_u64 v[32:33], v[116:117], 0, v[32:33]
	global_store_short v[32:33], v34, off
	v_or_b32_e32 v32, 26, v48
	v_ashrrev_i32_e32 v33, 31, v32
	v_lshlrev_b64 v[32:33], 11, v[32:33]
	v_cvt_pk_bf16_f32 v34, v46, s0
	v_lshl_add_u64 v[32:33], v[116:117], 0, v[32:33]
	global_store_short v[32:33], v34, off
	v_or_b32_e32 v32, 27, v48
	v_ashrrev_i32_e32 v33, 31, v32
	v_lshlrev_b64 v[32:33], 11, v[32:33]
	v_cvt_pk_bf16_f32 v34, v47, s0
	v_lshl_add_u64 v[32:33], v[116:117], 0, v[32:33]
	global_store_short v[32:33], v34, off
	s_waitcnt lgkmcnt(0)
	s_barrier
	s_cmp_eq_u32 s18, s13
	v_mov_b32_e32 v118, v137
	s_cbranch_scc1 .LBB0_648
.LBB0_642:
	s_add_i32 s7, s18, s17
	s_add_i32 s18, s18, 1
	s_cmp_lt_u32 s18, s13
	s_cselect_b64 s[4:5], -1, 0
	s_cmp_ge_u32 s18, s13
	s_waitcnt lgkmcnt(0)
	v_mov_b32_e32 v137, v118
	s_cbranch_scc1 .LBB0_644
	s_add_i32 s8, s18, s17
	s_lshl_b32 s19, s8, 6
	v_or_b32_e32 v34, s19, v102
	v_mov_b64_e32 v[32:33], s[0:1]
	v_mad_u64_u32 v[32:33], s[34:35], v34, s3, v[32:33]
	v_add_u32_e32 v34, s19, v105
	v_ashrrev_i32_e32 v35, 31, v34
	v_lshlrev_b64 v[36:37], 11, v[34:35]
	v_lshl_add_u64 v[36:37], v[106:107], 0, v[36:37]
	v_mad_i64_i32 v[34:35], s[34:35], v34, s3, v[108:109]
	global_load_dwordx4 v[66:69], v[36:37], off
	global_load_dwordx4 v[70:73], v[34:35], off
	v_add_co_u32_e32 v34, vcc, 0x1000, v34
	v_lshl_add_u64 v[36:37], v[110:111], 1, v[32:33]
	s_nop 0
	v_addc_co_u32_e32 v35, vcc, 0, v35, vcc
	global_load_dwordx4 v[74:77], v[34:35], off
	global_load_dwordx4 v[78:81], v[36:37], off offset:2048
	v_add_u32_e32 v34, s19, v120
	v_ashrrev_i32_e32 v35, 31, v34
	v_lshlrev_b64 v[36:37], 11, v[34:35]
	v_lshl_add_u64 v[36:37], v[106:107], 0, v[36:37]
	v_mad_i64_i32 v[34:35], s[34:35], v34, s3, v[108:109]
	s_lshl_b32 s8, s8, 3
	global_load_dwordx4 v[82:85], v[36:37], off
	global_load_dwordx4 v[86:89], v[34:35], off
	v_add_co_u32_e32 v34, vcc, s45, v34
	s_or_b32 s8, s8, s16
	s_nop 0
	v_addc_co_u32_e32 v35, vcc, 0, v35, vcc
	v_lshl_add_u64 v[32:33], v[112:113], 1, v[32:33]
	s_lshl_b64 s[34:35], s[8:9], 13
	s_lshl_b32 s8, s7, 3
	global_load_dwordx4 v[90:93], v[34:35], off
	global_load_dwordx4 v[94:97], v[32:33], off offset:2048
	v_lshl_add_u64 v[32:33], v[114:115], 0, s[34:35]
	s_add_i32 s34, s6, s8
	s_ashr_i32 s35, s34, 31
	s_lshl_b64 s[34:35], s[34:35], 2
	s_add_u32 s34, s14, s34
	s_addc_u32 s35, s15, s35
	global_load_dwordx4 v[98:101], v[32:33], off
	v_mov_b64_e32 v[32:33], s[34:35]
	global_load_dword v137, v[32:33], off

; #define LAS __attribute__((address_space(3)))
; DI unsigned pk2(float lo, float hi) { f32x2 v = {lo, hi}; bf16x2_t b = __builtin_convertvector(v, bf16x2_t); return __builtin_bit_cast(unsigned, b); }
; DI void sb_cache_convert(const Params& p, LAS float* scr  , int gtid, int NT, int gw, int NGW, int lane) {
;     ...
;     for (int it = gw; it < 8 * 16 * 32; it += NGW) { const int pb = it & 31, h = (it >> 5) & 15, b = it >> 9, p0 = pb * 64;
; #pragma unroll 8
;         for (int i = 0; i < 64; ++i) scr[i * 65 + lane] = __builtin_nontemporal_load(cv + ((size_t)b * PAST + p0 + i) * D + h * 64 + lane);
;         asm volatile("s_waitcnt lgkmcnt(0)" ::: "memory");
;         bf16_t* dst = VTS + ((size_t)(b * 16 + h) * 64 + lane) * LK + p0;
; #pragma unroll
;         for (int c = 0; c < 8; ++c) { const LAS float* s = scr + (8 * c) * 65 + lane; u32x4 o; o.x = pk2(s[0], s[65]); o.y = pk2(s[130], s[195]); o.z = pk2(s[260], s[325]); o.w = pk2(s[390], s[455]); *(u32x4*)(dst + 8 * c) = o; }
;         asm volatile("s_waitcnt lgkmcnt(0)" ::: "memory");
;     }
.LBB0_811:
	v_lshl_add_u64 v[6:7], v[2:3], 0, s[6:7]
	global_load_dword v44, v[6:7], off nt
	v_add_co_u32_e32 v8, vcc, 0x1000, v6
	s_nop 1
	v_addc_co_u32_e32 v9, vcc, 0, v7, vcc
	global_load_dword v45, v[8:9], off nt
	v_add_co_u32_e32 v8, vcc, 0x2000, v6
	s_nop 1
	v_addc_co_u32_e32 v9, vcc, 0, v7, vcc
	global_load_dword v46, v[8:9], off nt
	v_add_co_u32_e32 v8, vcc, 0x3000, v6
	s_nop 1
	v_addc_co_u32_e32 v9, vcc, 0, v7, vcc
	global_load_dword v47, v[8:9], off nt
	v_add_co_u32_e32 v8, vcc, 0x4000, v6
	s_nop 1
	v_addc_co_u32_e32 v9, vcc, 0, v7, vcc
	global_load_dword v48, v[8:9], off nt
	v_add_co_u32_e32 v8, vcc, 0x5000, v6
	s_nop 1
	v_addc_co_u32_e32 v9, vcc, 0, v7, vcc
	global_load_dword v49, v[8:9], off nt
	v_add_co_u32_e32 v8, vcc, 0x6000, v6
	s_nop 1
	v_addc_co_u32_e32 v9, vcc, 0, v7, vcc
	global_load_dword v50, v[8:9], off nt
	v_add_co_u32_e32 v8, vcc, 0x7000, v6
	s_nop 1
	v_addc_co_u32_e32 v9, vcc, 0, v7, vcc
	global_load_dword v51, v[8:9], off nt
	v_add_u32_e32 v11, 0x400, v5
	s_add_u32 s6, s6, 0x8000
	s_addc_u32 s7, s7, 0
	s_waitcnt vmcnt(6)
	ds_write2_b32 v5, v44, v45 offset1:65
	s_waitcnt vmcnt(4)
	ds_write2_b32 v5, v46, v47 offset0:130 offset1:195
	s_waitcnt vmcnt(2)
	ds_write2_b32 v11, v48, v49 offset0:4 offset1:69
	s_waitcnt vmcnt(0)
	ds_write2_b32 v11, v50, v51 offset0:134 offset1:199
	v_add_u32_e32 v5, 0x820, v5
	s_cmp_eq_u32 s6, 0x40000
	s_cbranch_scc0 .LBB0_811
	s_waitcnt lgkmcnt(0)
	ds_read2_b32 v[6:7], v4 offset1:65
	ds_read2_b32 v[8:9], v4 offset0:130 offset1:195
	s_and_b32 s5, s8, 15
	s_lshl_b32 s4, s4, 4
	s_or_b32 s4, s4, s5
	s_ashr_i32 s6, s4, 31
	v_lshl_or_b32 v5, s4, 6, v102
	v_mov_b64_e32 v[2:3], s[0:1]
	s_movk_i32 s4, 0x1080
	v_mad_u64_u32 v[2:3], s[4:5], v5, s4, v[2:3]
	v_add_u32_e32 v5, 0x400, v4
	s_waitcnt lgkmcnt(0)
	v_cvt_pk_bf16_f32 v6, v6, v7
	v_cvt_pk_bf16_f32 v7, v8, v9
	ds_read2_b32 v[8:9], v5 offset0:4 offset1:69
	ds_read2_b32 v[10:11], v5 offset0:134 offset1:199
	s_lshl_b32 s4, s12, 7
	v_mad_i32_i24 v3, s6, v237, v3
	s_and_b32 s8, s4, 0xf80
	v_lshl_add_u64 v[2:3], v[2:3], 0, s[8:9]
	s_waitcnt lgkmcnt(1)
	v_cvt_pk_bf16_f32 v8, v8, v9
	s_waitcnt lgkmcnt(0)
	v_cvt_pk_bf16_f32 v9, v10, v11
	global_store_dwordx4 v[2:3], v[6:9], off
	v_add_u32_e32 v5, 0x800, v4
	ds_read2_b32 v[6:7], v5 offset0:8 offset1:73
	ds_read2_b32 v[8:9], v5 offset0:138 offset1:203
	v_add_u32_e32 v5, 0xc00, v4
	ds_read2_b32 v[10:11], v5 offset0:142 offset1:207
	s_add_i32 s12, s12, s37
	s_waitcnt lgkmcnt(0)
	v_cvt_pk_bf16_f32 v6, v6, v7
	v_cvt_pk_bf16_f32 v7, v8, v9
	ds_read2_b32 v[8:9], v5 offset0:12 offset1:77
	v_add_u32_e32 v5, 0x1000, v4
	s_add_i32 s10, s10, s44
	s_cmpk_gt_i32 s12, 0xfff
	s_waitcnt lgkmcnt(0)
	v_cvt_pk_bf16_f32 v8, v8, v9
	v_cvt_pk_bf16_f32 v9, v10, v11
	global_store_dwordx4 v[2:3], v[6:9], off offset:16
	ds_read2_b32 v[6:7], v5 offset0:16 offset1:81
	ds_read2_b32 v[8:9], v5 offset0:146 offset1:211
	v_add_u32_e32 v5, 0x1400, v4
	ds_read2_b32 v[10:11], v5 offset0:150 offset1:215
	s_waitcnt lgkmcnt(0)
	v_cvt_pk_bf16_f32 v6, v6, v7
	v_cvt_pk_bf16_f32 v7, v8, v9
	ds_read2_b32 v[8:9], v5 offset0:20 offset1:85
	v_add_u32_e32 v5, 0x1800, v4
	s_waitcnt lgkmcnt(0)
	v_cvt_pk_bf16_f32 v8, v8, v9
	v_cvt_pk_bf16_f32 v9, v10, v11
	global_store_dwordx4 v[2:3], v[6:9], off offset:32
	ds_read2_b32 v[6:7], v5 offset0:24 offset1:89
	ds_read2_b32 v[8:9], v5 offset0:154 offset1:219
	v_add_u32_e32 v5, 0x1c00, v4
	ds_read2_b32 v[10:11], v5 offset0:158 offset1:223
	s_waitcnt lgkmcnt(0)
	v_cvt_pk_bf16_f32 v6, v6, v7
	v_cvt_pk_bf16_f32 v7, v8, v9
	ds_read2_b32 v[8:9], v5 offset0:28 offset1:93
	v_add_u32_e32 v5, 0x2000, v4
	s_waitcnt lgkmcnt(0)
	v_cvt_pk_bf16_f32 v8, v8, v9
	v_cvt_pk_bf16_f32 v9, v10, v11
	global_store_dwordx4 v[2:3], v[6:9], off offset:48
	ds_read2_b32 v[6:7], v5 offset0:32 offset1:97
	ds_read2_b32 v[8:9], v5 offset0:162 offset1:227
	v_add_u32_e32 v5, 0x2400, v4
	ds_read2_b32 v[10:11], v5 offset0:166 offset1:231
	s_waitcnt lgkmcnt(0)
	v_cvt_pk_bf16_f32 v6, v6, v7
	v_cvt_pk_bf16_f32 v7, v8, v9
	ds_read2_b32 v[8:9], v5 offset0:36 offset1:101
	v_add_u32_e32 v5, 0x2800, v4
	s_waitcnt lgkmcnt(0)
	v_cvt_pk_bf16_f32 v8, v8, v9
	v_cvt_pk_bf16_f32 v9, v10, v11
	global_store_dwordx4 v[2:3], v[6:9], off offset:64
	ds_read2_b32 v[6:7], v5 offset0:40 offset1:105
	ds_read2_b32 v[8:9], v5 offset0:170 offset1:235
	v_add_u32_e32 v5, 0x2c00, v4
	ds_read2_b32 v[10:11], v5 offset0:174 offset1:239
	s_waitcnt lgkmcnt(0)
	v_cvt_pk_bf16_f32 v6, v6, v7
	v_cvt_pk_bf16_f32 v7, v8, v9
	ds_read2_b32 v[8:9], v5 offset0:44 offset1:109
	v_add_u32_e32 v5, 0x3000, v4
	s_waitcnt lgkmcnt(0)
	v_cvt_pk_bf16_f32 v8, v8, v9
	v_cvt_pk_bf16_f32 v9, v10, v11
	global_store_dwordx4 v[2:3], v[6:9], off offset:80
	ds_read2_b32 v[6:7], v5 offset0:48 offset1:113
	ds_read2_b32 v[8:9], v5 offset0:178 offset1:243
	v_add_u32_e32 v5, 0x3400, v4
	ds_read2_b32 v[10:11], v5 offset0:182 offset1:247
	s_waitcnt lgkmcnt(0)
	v_cvt_pk_bf16_f32 v6, v6, v7
	v_cvt_pk_bf16_f32 v7, v8, v9
	ds_read2_b32 v[8:9], v5 offset0:52 offset1:117
	v_add_u32_e32 v5, 0x3800, v4
	s_waitcnt lgkmcnt(0)
	v_cvt_pk_bf16_f32 v8, v8, v9
	v_cvt_pk_bf16_f32 v9, v10, v11
	global_store_dwordx4 v[2:3], v[6:9], off offset:96
	ds_read2_b32 v[6:7], v5 offset0:56 offset1:121
	ds_read2_b32 v[8:9], v5 offset0:186 offset1:251
	v_add_u32_e32 v5, 0x3c00, v4
	ds_read2_b32 v[10:11], v5 offset0:190 offset1:255
	s_waitcnt lgkmcnt(0)
	v_cvt_pk_bf16_f32 v6, v6, v7
	v_cvt_pk_bf16_f32 v7, v8, v9
	ds_read2_b32 v[8:9], v5 offset0:60 offset1:125
	s_waitcnt lgkmcnt(0)
	v_cvt_pk_bf16_f32 v8, v8, v9
	v_cvt_pk_bf16_f32 v9, v10, v11
	global_store_dwordx4 v[2:3], v[6:9], off offset:112
	s_waitcnt lgkmcnt(0)
	s_cbranch_scc0 .LBB0_810

; DI void dn_intra(const Params& p, LAS unsigned char* L, int tid_in, int wave, int bid, int G, bool dry) {
;     ...
;     u32x4 xr[3][4][2];
;     if ((bid >> 3) < NSEG) DN_PREFETCH(bid >> 3, tid_in);
.LBB0_883:
	v_mov_b64_e32 v[4:5], s[26:27]
	v_mad_i64_i32 v[4:5], s[6:7], v1, s3, v[4:5]
	v_lshl_add_u64 v[4:5], v[4:5], 0, v[64:65]
	s_waitcnt lgkmcnt(0)
	global_load_dwordx4 v[76:79], v[4:5], off
	global_load_dwordx4 v[80:83], v[4:5], off offset:16
.LBB0_884:
	s_or_b64 exec, exec, s[4:5]
	v_or_b32_e32 v3, 0x800, v10
	v_readlane_b32 s52, v253, 47
	v_lshlrev_b32_e32 v64, 1, v3
	v_lshlrev_b32_e32 v4, 2, v3
	v_mov_b32_e32 v5, v65
	v_readlane_b32 s58, v253, 53
	v_readlane_b32 s59, v253, 54
	v_lshl_add_u64 v[6:7], s[46:47], 0, v[64:65]
	v_readlane_b32 s53, v253, 48
	v_lshl_add_u64 v[4:5], s[58:59], 0, v[4:5]
	v_readlane_b32 s54, v253, 49
	v_readlane_b32 s55, v253, 50
	v_readlane_b32 s56, v253, 51
	v_readlane_b32 s57, v253, 52
	v_readlane_b32 s60, v253, 55
	v_readlane_b32 s61, v253, 56
	v_readlane_b32 s62, v253, 57
	v_readlane_b32 s63, v253, 58
	v_readlane_b32 s64, v253, 59
	v_readlane_b32 s65, v253, 60
	v_readlane_b32 s66, v253, 61
	v_readlane_b32 s67, v253, 62
	s_and_saveexec_b64 s[4:5], s[40:41]
	s_xor_b64 s[4:5], exec, s[4:5]
	s_cbranch_execz .LBB0_887
	s_and_b64 vcc, exec, s[36:37]
	s_cbranch_vccnz .LBB0_1671
	v_ashrrev_i32_e32 v3, 31, v2
	v_lshl_add_u64 v[8:9], s[48:49], 0, v[2:3]
	v_mad_u64_u32 v[10:11], s[6:7], v8, s3, v[6:7]
	v_mad_i32_i24 v11, v9, s3, v11
	s_waitcnt lgkmcnt(0)
	global_load_dwordx4 v[84:87], v[10:11], off
	global_load_dwordx4 v[88:91], v[10:11], off offset:16
	s_cbranch_execz .LBB0_1672
	s_branch .LBB0_1674

; DI void dn_intra(const Params& p, LAS unsigned char* L, int tid_in, int wave, int bid, int G, bool dry) {
;     ...
;     u32x4 xr[3][4][2];
;     if ((bid >> 3) < NSEG) DN_PREFETCH(bid >> 3, tid_in);
.LBB0_888:
	v_mad_i64_i32 v[10:11], s[6:7], v11, s3, v[8:9]
	s_waitcnt lgkmcnt(0)
	global_load_dwordx4 v[84:87], v[10:11], off
	global_load_dwordx4 v[88:91], v[10:11], off offset:16
.LBB0_889:
	s_or_b64 exec, exec, s[4:5]
	s_and_saveexec_b64 s[4:5], s[42:43]
	s_xor_b64 s[4:5], exec, s[4:5]
	s_cbranch_execz .LBB0_894
	s_and_b64 vcc, exec, s[36:37]
	s_cbranch_vccnz .LBB0_1675
	v_add_u32_e32 v10, 1, v2
	v_ashrrev_i32_e32 v11, 31, v10
	v_lshl_add_u64 v[10:11], s[48:49], 0, v[10:11]
	v_mad_u64_u32 v[14:15], s[6:7], v10, s3, v[6:7]
	v_mad_i32_i24 v15, v11, s3, v15
	s_waitcnt lgkmcnt(0)
	global_load_dwordx4 v[92:95], v[14:15], off
	global_load_dwordx4 v[96:99], v[14:15], off offset:16
	s_cbranch_execnz .LBB0_1676

; DI void dn_intra(const Params& p, LAS unsigned char* L, int tid_in, int wave, int bid, int G, bool dry) {
;     ...
;     u32x4 xr[3][4][2];
;     if ((bid >> 3) < NSEG) DN_PREFETCH(bid >> 3, tid_in);
.LBB0_895:
	v_mad_i64_i32 v[10:11], s[6:7], v12, s3, v[8:9]
	s_waitcnt lgkmcnt(0)
	global_load_dwordx4 v[92:95], v[10:11], off
	global_load_dwordx4 v[96:99], v[10:11], off offset:16
.LBB0_896:
	s_or_b64 exec, exec, s[4:5]
	s_and_saveexec_b64 s[4:5], s[44:45]
	s_xor_b64 s[4:5], exec, s[4:5]
	s_cbranch_execz .LBB0_901
	s_and_b64 vcc, exec, s[36:37]
	s_cbranch_vccnz .LBB0_1677
	v_add_u32_e32 v10, 2, v2
	v_ashrrev_i32_e32 v11, 31, v10
	v_lshl_add_u64 v[10:11], s[48:49], 0, v[10:11]
	v_mad_u64_u32 v[12:13], s[6:7], v10, s3, v[6:7]
	v_mad_i32_i24 v13, v11, s3, v13
	s_waitcnt lgkmcnt(0)
	global_load_dwordx4 v[100:103], v[12:13], off
	global_load_dwordx4 v[104:107], v[12:13], off offset:16
	s_cbranch_execnz .LBB0_1678

; DI void dn_intra(const Params& p, LAS unsigned char* L, int tid_in, int wave, int bid, int G, bool dry) {
;     ...
;     u32x4 xr[3][4][2];
;     if ((bid >> 3) < NSEG) DN_PREFETCH(bid >> 3, tid_in);
.LBB0_902:
	v_mad_i64_i32 v[10:11], s[6:7], v13, s3, v[8:9]
	s_waitcnt lgkmcnt(0)
	global_load_dwordx4 v[100:103], v[10:11], off
	global_load_dwordx4 v[104:107], v[10:11], off offset:16
.LBB0_903:
	s_or_b64 exec, exec, s[4:5]
	s_and_saveexec_b64 s[4:5], s[38:39]
	s_xor_b64 s[4:5], exec, s[4:5]
	s_cbranch_execz .LBB0_906
	s_and_b64 vcc, exec, s[36:37]
	s_cbranch_vccnz .LBB0_1679
	v_add_u32_e32 v2, 3, v2
	v_ashrrev_i32_e32 v3, 31, v2
	v_lshl_add_u64 v[2:3], s[48:49], 0, v[2:3]
	v_mad_u64_u32 v[6:7], s[6:7], v2, s3, v[6:7]
	v_mad_i32_i24 v7, v3, s3, v7
	s_waitcnt lgkmcnt(0)
	global_load_dwordx4 v[108:111], v[6:7], off
	global_load_dwordx4 v[112:115], v[6:7], off offset:16
	s_cbranch_execz .LBB0_1680
	s_branch .LBB0_1682

; DI void dn_intra(const Params& p, LAS unsigned char* L, int tid_in, int wave, int bid, int G, bool dry) {
;     ...
;     u32x4 xr[3][4][2];
;     if ((bid >> 3) < NSEG) DN_PREFETCH(bid >> 3, tid_in);
.LBB0_907:
	v_mad_i64_i32 v[0:1], s[6:7], v1, s3, v[8:9]
	s_waitcnt lgkmcnt(0)
	global_load_dwordx4 v[108:111], v[0:1], off
	global_load_dwordx4 v[112:115], v[0:1], off offset:16

; DI void rowinfo(int row, int& s, int& b, int& t) { if (row < MP) { s = 0; b = row >> 12; t = row & 4095; } else { const int r = row - MP; s = 1; b = r >> 6; t = r & 63; } }
; DI void dn_intra(const Params& p, LAS unsigned char* L, int tid_in, int wave, int bid, int G, bool dry) {
;     ...
;     if ((bid >> 3) < NSEG) DN_PREFETCH(bid >> 3, tid_in);
;     for (int seg = (bid >> 3); seg < NSEG; seg += ngrp) {
;         if ((G >> 3) == 0 && (bid != 0)) break;
;         const int u = seg * 8 + h, row0 = seg * 64;
;         int s, b, t0; rowinfo(row0, s, b, t0);
;         int tid = tid_in; asm volatile("" : "+v"(tid)); int lane = tid & 63;
;         const int r = tid >> 3, sub = tid & 7;
;         if (wave == 0) {
;             const float a = AB[(size_t)(row0 + lane) * 16 + h], bq = AB[(size_t)(row0 + lane) * 16 + 8 + h];
.LBB0_909:
	s_waitcnt vmcnt(0)
	s_andn2_b64 vcc, exec, s[0:1]
	s_cbranch_vccnz .LBB0_1112
	s_cmp_lg_u32 s14, 0
	v_readlane_b32 s4, v253, 15
	s_cselect_b64 s[0:1], -1, 0
	v_readlane_b32 s5, v253, 16
	s_and_b64 s[0:1], s[4:5], s[0:1]
	s_and_b64 vcc, exec, s[0:1]
	s_cbranch_vccnz .LBB0_1112
	s_lshl_b32 s4, s12, 2
	s_add_u32 s0, s28, s4
	s_addc_u32 s1, s29, 0
	s_add_u32 s50, s0, 0x1c00000
	s_addc_u32 s51, s1, 0
	s_lshl_b32 s14, s12, 7
	s_lshl_b32 s5, s12, 8
	v_and_b32_e64 v0, s15, 1
	v_and_b32_e64 v1, 2, s15
	s_add_u32 s52, s26, s5
	v_cmp_ne_u32_e32 vcc, 0, v1
	v_cmp_eq_u32_e64 s[0:1], 0, v0
	s_addc_u32 s53, s27, 0
	s_or_b64 s[54:55], s[0:1], vcc
	s_add_u32 s58, s28, s5
	v_cmp_lt_u32_e64 vcc, s15, 4
	v_mov_b32_e32 v1, 0x4400
	v_mov_b32_e32 v2, 0xcc00
	v_lshlrev_b32_e32 v183, 5, v0
	v_mov_b32_e32 v0, s85
	s_addc_u32 s59, s29, 0
	v_cmp_ne_u32_e64 s[48:49], s15, 0
	v_cmp_gt_u32_e64 s[56:57], s15, 3
	v_cndmask_b32_e32 v1, v1, v2, vcc
	v_lshlrev_b32_e64 v2, 4, s15
	v_lshl_add_u32 v186, s15, 7, v0
	s_add_u32 s15, s30, 0x10e70000
	s_addc_u32 s16, s31, 0
	s_add_u32 s17, s28, 0x1f00000
	s_addc_u32 s18, s29, 0
	v_readlane_b32 s60, v253, 27
	v_readlane_b32 s61, v253, 28
	v_readlane_b32 s62, v253, 29
	v_readlane_b32 s63, v253, 30
	v_readlane_b32 s64, v253, 31
	v_readlane_b32 s65, v253, 32
	v_readlane_b32 s66, v253, 33
	v_readlane_b32 s67, v253, 34
	v_readlane_b32 s68, v253, 35
	v_readlane_b32 s69, v253, 36
	v_readlane_b32 s70, v253, 37
	v_readlane_b32 s71, v253, 38
	v_readlane_b32 s72, v253, 39
	v_readlane_b32 s73, v253, 40
	v_readlane_b32 s74, v253, 41
	v_readlane_b32 s75, v253, 42
	s_add_u32 s22, s60, s4
	s_addc_u32 s23, s61, 0
	v_readlane_b32 s60, v254, 7
	v_readlane_b32 s74, v254, 21
	v_readlane_b32 s76, v254, 40
	v_readlane_b32 s75, v254, 22
	s_add_u32 s34, s74, s4
	v_and_b32_e32 v149, 32, v2
	v_add_u32_e32 v185, 0, v1
	v_readlane_b32 s88, v254, 42
	v_readlane_b32 s77, v254, 41
	s_addc_u32 s35, s75, 0
	v_readlane_b32 s61, v254, 8
	v_readlane_b32 s62, v254, 9
	v_readlane_b32 s63, v254, 10
	v_readlane_b32 s64, v254, 11
	v_readlane_b32 s65, v254, 12
	v_readlane_b32 s66, v254, 13
	v_readlane_b32 s67, v254, 14
	v_readlane_b32 s68, v254, 15
	v_readlane_b32 s69, v254, 16
	v_readlane_b32 s70, v254, 17
	v_readlane_b32 s71, v254, 18
	v_readlane_b32 s72, v254, 19
	v_readlane_b32 s73, v254, 20
	s_branch .LBB0_913

; DI void dn_intra(const Params& p, LAS unsigned char* L, int tid_in, int wave, int bid, int G, bool dry) {
;     ...
;         if (seg + ngrp < NSEG) DN_PREFETCH(seg + ngrp, tid);
.LBB0_995:
	s_or_saveexec_b64 s[4:5], s[4:5]
	v_add_u32_e32 v1, -3, v0
	v_lshl_add_u64 v[6:7], s[26:27], 0, v[64:65]
	v_add_u32_e32 v10, s10, v1
	s_xor_b64 exec, exec, s[4:5]
	s_cbranch_execz .LBB0_997
	v_mad_i64_i32 v[12:13], s[6:7], v10, s3, v[6:7]
	s_waitcnt lgkmcnt(0)
	global_load_dwordx4 v[16:19], v[12:13], off
	global_load_dwordx4 v[20:23], v[12:13], off offset:16

; DI void dn_intra(const Params& p, LAS unsigned char* L, int tid_in, int wave, int bid, int G, bool dry) {
;     ...
;         if (seg + ngrp < NSEG) DN_PREFETCH(seg + ngrp, tid);
.LBB0_1004:
	s_or_saveexec_b64 s[4:5], s[4:5]
	v_add_u32_e32 v1, -2, v0
	v_add_u32_e32 v11, s10, v1
	s_xor_b64 exec, exec, s[4:5]
	s_cbranch_execz .LBB0_1006
	v_mad_i64_i32 v[12:13], s[6:7], v11, s3, v[6:7]
	s_waitcnt lgkmcnt(0)
	global_load_dwordx4 v[24:27], v[12:13], off
	global_load_dwordx4 v[28:31], v[12:13], off offset:16

; DI void dn_intra(const Params& p, LAS unsigned char* L, int tid_in, int wave, int bid, int G, bool dry) {
;     ...
;         if (seg + ngrp < NSEG) DN_PREFETCH(seg + ngrp, tid);
.LBB0_1013:
	s_or_saveexec_b64 s[4:5], s[4:5]
	v_add_u32_e32 v1, -1, v0
	v_add_u32_e32 v12, s10, v1
	s_xor_b64 exec, exec, s[4:5]
	s_cbranch_execz .LBB0_1015
	v_mad_i64_i32 v[14:15], s[6:7], v12, s3, v[6:7]
	s_waitcnt lgkmcnt(0)
	global_load_dwordx4 v[32:35], v[14:15], off
	global_load_dwordx4 v[36:39], v[14:15], off offset:16

; DI void dn_intra(const Params& p, LAS unsigned char* L, int tid_in, int wave, int bid, int G, bool dry) {
;     ...
;         if (seg + ngrp < NSEG) DN_PREFETCH(seg + ngrp, tid);
.LBB0_1023:
	v_mad_i64_i32 v[2:3], s[6:7], v9, s3, v[6:7]
	s_waitcnt lgkmcnt(0)
	global_load_dwordx4 v[40:43], v[2:3], off
	global_load_dwordx4 v[44:47], v[2:3], off offset:16

; DI void dn_intra(const Params& p, LAS unsigned char* L, int tid_in, int wave, int bid, int G, bool dry) {
;     ...
;         if (seg + ngrp < NSEG) DN_PREFETCH(seg + ngrp, tid);
.LBB0_1028:
	v_mov_b64_e32 v[4:5], s[26:27]
	v_mad_i64_i32 v[4:5], s[6:7], v10, s3, v[4:5]
	v_lshl_add_u64 v[4:5], v[4:5], 0, v[64:65]
	s_waitcnt lgkmcnt(0)
	global_load_dwordx4 v[48:51], v[4:5], off
	global_load_dwordx4 v[52:55], v[4:5], off offset:16

; DI void dn_intra(const Params& p, LAS unsigned char* L, int tid_in, int wave, int bid, int G, bool dry) {
;     ...
;         if (seg + ngrp < NSEG) DN_PREFETCH(seg + ngrp, tid);
.LBB0_1033:
	v_mov_b64_e32 v[4:5], s[26:27]
	v_mad_i64_i32 v[4:5], s[6:7], v11, s3, v[4:5]
	v_lshl_add_u64 v[4:5], v[4:5], 0, v[64:65]
	s_waitcnt lgkmcnt(0)
	global_load_dwordx4 v[56:59], v[4:5], off
	global_load_dwordx4 v[60:63], v[4:5], off offset:16

; DI void dn_intra(const Params& p, LAS unsigned char* L, int tid_in, int wave, int bid, int G, bool dry) {
;     ...
;         if (seg + ngrp < NSEG) DN_PREFETCH(seg + ngrp, tid);
.LBB0_1038:
	v_mov_b64_e32 v[4:5], s[26:27]
	v_mad_i64_i32 v[4:5], s[6:7], v12, s3, v[4:5]
	v_lshl_add_u64 v[4:5], v[4:5], 0, v[64:65]
	s_waitcnt lgkmcnt(0)
	global_load_dwordx4 v[68:71], v[4:5], off
	global_load_dwordx4 v[72:75], v[4:5], off offset:16

; DI void dn_intra(const Params& p, LAS unsigned char* L, int tid_in, int wave, int bid, int G, bool dry) {
;     ...
;         if (seg + ngrp < NSEG) DN_PREFETCH(seg + ngrp, tid);
.LBB0_1043:
	v_mov_b64_e32 v[2:3], s[26:27]
	v_mad_i64_i32 v[2:3], s[6:7], v9, s3, v[2:3]
	v_lshl_add_u64 v[2:3], v[2:3], 0, v[64:65]
	s_waitcnt lgkmcnt(0)
	global_load_dwordx4 v[76:79], v[2:3], off
	global_load_dwordx4 v[80:83], v[2:3], off offset:16

; DI void dn_intra(const Params& p, LAS unsigned char* L, int tid_in, int wave, int bid, int G, bool dry) {
;     ...
;         if (seg + ngrp < NSEG) DN_PREFETCH(seg + ngrp, tid);
.LBB0_1048:
	v_mad_i64_i32 v[14:15], s[6:7], v10, s3, v[6:7]
	s_waitcnt lgkmcnt(0)
	global_load_dwordx4 v[84:87], v[14:15], off
	global_load_dwordx4 v[88:91], v[14:15], off offset:16

; DI void dn_intra(const Params& p, LAS unsigned char* L, int tid_in, int wave, int bid, int G, bool dry) {
;     ...
;         if (seg + ngrp < NSEG) DN_PREFETCH(seg + ngrp, tid);
.LBB0_1055:
	v_mad_i64_i32 v[10:11], s[6:7], v11, s3, v[6:7]
	s_waitcnt lgkmcnt(0)
	global_load_dwordx4 v[92:95], v[10:11], off
	global_load_dwordx4 v[96:99], v[10:11], off offset:16

; DI void dn_intra(const Params& p, LAS unsigned char* L, int tid_in, int wave, int bid, int G, bool dry) {
;     ...
;         if (seg + ngrp < NSEG) DN_PREFETCH(seg + ngrp, tid);
.LBB0_1062:
	v_mad_i64_i32 v[10:11], s[6:7], v12, s3, v[6:7]
	s_waitcnt lgkmcnt(0)
	global_load_dwordx4 v[100:103], v[10:11], off
	global_load_dwordx4 v[104:107], v[10:11], off offset:16

; DI void dn_intra(const Params& p, LAS unsigned char* L, int tid_in, int wave, int bid, int G, bool dry) {
;     ...
;         if (seg + ngrp < NSEG) DN_PREFETCH(seg + ngrp, tid);
.LBB0_1067:
	v_mad_i64_i32 v[0:1], s[4:5], v9, s3, v[6:7]
	s_waitcnt lgkmcnt(0)
	global_load_dwordx4 v[108:111], v[0:1], off
	global_load_dwordx4 v[112:115], v[0:1], off offset:16

; #define LAS __attribute__((address_space(3)))
; DI void dn_intra(const Params& p, LAS unsigned char* L, int tid_in, int wave, int bid, int G, bool dry) {
;     ...
;         if (tid < 256) {
;             float x[32];
; #pragma unroll
;             for (int i = 0; i < 32; ++i) {
;                 float a = RHS[i * DN_RST + tid];
; #pragma unroll
;                 for (int j4 = 0; j4 < (i + 3) / 4; ++j4) { const f32x4 m4 = *(const LAS f32x4*)(Mm + i * DN_MST + 4 * j4);
; #pragma unroll
;                     for (int e = 0; e < 4; ++e) if (4 * j4 + e < i) a -= m4[e] * x[4 * j4 + e]; }
;                 x[i] = a; RHS[i * DN_RST + tid] = a; if ((i & 1) == 1) __builtin_amdgcn_sched_barrier(0);
;             }
;         }
.LBB0_1069:
	s_waitcnt vmcnt(0)
	v_cmp_gt_i32_e32 vcc, s86, v187
	s_and_saveexec_b64 s[0:1], vcc
	s_cbranch_execz .LBB0_1071
	v_lshl_add_u32 v0, v187, 2, 0
	v_add_u32_e32 v0, 0x11000, v0
	ds_read_b32 v1, v0
	ds_read_b32 v6, v0 offset:1040
	ds_read_b128 v[2:5], v65 offset:272
	s_waitcnt lgkmcnt(0)
	v_fma_f32 v2, -v1, v2, v6
	ds_write_b32 v0, v2 offset:1040
	ds_read_b32 v3, v0 offset:2080
	ds_read_b128 v[4:7], v65 offset:544
	s_waitcnt lgkmcnt(0)
	v_fma_f32 v3, -v1, v4, v3
	v_fma_f32 v3, -v2, v5, v3
	ds_write_b32 v0, v3 offset:2080
	ds_read_b32 v8, v0 offset:3120
	ds_read_b128 v[4:7], v65 offset:816
	s_waitcnt lgkmcnt(0)
	v_fma_f32 v4, -v1, v4, v8
	v_fma_f32 v4, -v2, v5, v4
	v_fma_f32 v4, -v6, v3, v4
	ds_write_b32 v0, v4 offset:3120
	ds_read_b32 v5, v0 offset:4160
	ds_read_b32 v14, v0 offset:5200
	ds_read_b128 v[6:9], v65 offset:1088
	s_waitcnt lgkmcnt(0)
	v_fma_f32 v5, -v1, v6, v5
	v_fma_f32 v5, -v2, v7, v5
	v_fma_f32 v5, -v3, v8, v5
	v_fma_f32 v5, -v9, v4, v5
	ds_write_b32 v0, v5 offset:4160
	ds_read_b128 v[6:9], v65 offset:1360
	ds_read_b128 v[10:13], v65 offset:1376
	s_waitcnt lgkmcnt(0)
	v_fma_f32 v6, -v1, v6, v14
	v_fma_f32 v6, -v2, v7, v6
	v_fma_f32 v6, -v3, v8, v6
	v_fma_f32 v6, -v4, v9, v6
	v_fma_f32 v6, -v10, v5, v6
	ds_write_b32 v0, v6 offset:5200
	ds_read_b32 v7, v0 offset:6240
	ds_read_b128 v[8:11], v65 offset:1632
	ds_read_b128 v[12:15], v65 offset:1648
	ds_read_b32 v64, v0 offset:7280
	s_waitcnt lgkmcnt(0)
	v_fma_f32 v7, -v1, v8, v7
	v_fma_f32 v7, -v2, v9, v7
	v_fma_f32 v7, -v3, v10, v7
	v_fma_f32 v7, -v4, v11, v7
	v_fma_f32 v7, -v5, v12, v7
	v_fma_f32 v7, -v13, v6, v7
	ds_write_b32 v0, v7 offset:6240
	ds_read_b128 v[8:11], v65 offset:1904
	ds_read_b128 v[12:15], v65 offset:1920
	s_waitcnt lgkmcnt(0)
	v_fma_f32 v8, -v1, v8, v64
	v_fma_f32 v8, -v2, v9, v8
	v_fma_f32 v8, -v3, v10, v8
	v_fma_f32 v8, -v4, v11, v8
	v_fma_f32 v8, -v5, v12, v8
	v_fma_f32 v8, -v6, v13, v8
	v_fma_f32 v8, -v14, v7, v8
	ds_write_b32 v0, v8 offset:7280
	ds_read_b32 v9, v0 offset:8320
	ds_read_b128 v[10:13], v65 offset:2176
	ds_read_b128 v[116:119], v65 offset:2192
	s_waitcnt lgkmcnt(0)
	v_fma_f32 v9, -v1, v10, v9
	v_fma_f32 v9, -v2, v11, v9
	v_fma_f32 v9, -v3, v12, v9
	v_fma_f32 v9, -v4, v13, v9
	v_fma_f32 v9, -v5, v116, v9
	v_fma_f32 v9, -v6, v117, v9
	v_fma_f32 v9, -v7, v118, v9
	v_fma_f32 v9, -v119, v8, v9
	ds_write_b32 v0, v9 offset:8320
	ds_read_b32 v14, v0 offset:9360
	ds_read_b128 v[10:13], v65 offset:2448
	ds_read_b128 v[116:119], v65 offset:2464
	ds_read_b128 v[120:123], v65 offset:2480
	s_waitcnt lgkmcnt(0)
	v_fma_f32 v10, -v1, v10, v14
	v_fma_f32 v10, -v2, v11, v10
	v_fma_f32 v10, -v3, v12, v10
	v_fma_f32 v10, -v4, v13, v10
	v_fma_f32 v10, -v5, v116, v10
	v_fma_f32 v10, -v6, v117, v10
	v_fma_f32 v10, -v7, v118, v10
	v_fma_f32 v10, -v8, v119, v10
	v_fma_f32 v10, -v120, v9, v10
	ds_write_b32 v0, v10 offset:9360
	ds_read_b32 v11, v0 offset:10400
	ds_read_b128 v[12:15], v65 offset:2720
	ds_read_b128 v[116:119], v65 offset:2736
	ds_read_b128 v[120:123], v65 offset:2752
	s_waitcnt lgkmcnt(0)
	v_fma_f32 v11, -v1, v12, v11
	v_fma_f32 v11, -v2, v13, v11
	v_fma_f32 v11, -v3, v14, v11
	v_fma_f32 v11, -v4, v15, v11
	v_fma_f32 v11, -v5, v116, v11
	v_fma_f32 v11, -v6, v117, v11
	v_fma_f32 v11, -v7, v118, v11
	v_fma_f32 v11, -v8, v119, v11
	v_fma_f32 v11, -v9, v120, v11
	v_fma_f32 v11, -v121, v10, v11
	ds_write_b32 v0, v11 offset:10400
	ds_read_b32 v64, v0 offset:11440
	ds_read_b128 v[12:15], v65 offset:2992
	ds_read_b128 v[116:119], v65 offset:3008
	ds_read_b128 v[120:123], v65 offset:3024
	s_waitcnt lgkmcnt(0)
	v_fma_f32 v12, -v1, v12, v64
	v_fma_f32 v12, -v2, v13, v12
	v_fma_f32 v12, -v3, v14, v12
	v_fma_f32 v12, -v4, v15, v12
	v_fma_f32 v12, -v5, v116, v12
	v_fma_f32 v12, -v6, v117, v12
	v_fma_f32 v12, -v7, v118, v12
	v_fma_f32 v12, -v8, v119, v12
	v_fma_f32 v12, -v9, v120, v12
	v_fma_f32 v12, -v10, v121, v12
	v_fma_f32 v12, -v122, v11, v12
	ds_write_b32 v0, v12 offset:11440
	ds_read_b32 v13, v0 offset:12480
	ds_read_b128 v[116:119], v65 offset:3264
	ds_read_b128 v[120:123], v65 offset:3280
	ds_read_b32 v14, v0 offset:13520
	ds_read_b128 v[124:127], v65 offset:3296
	s_waitcnt lgkmcnt(0)
	v_fma_f32 v13, -v1, v116, v13
	v_fma_f32 v13, -v2, v117, v13
	v_fma_f32 v13, -v3, v118, v13
	v_fma_f32 v13, -v4, v119, v13
	v_fma_f32 v13, -v5, v120, v13
	v_fma_f32 v13, -v6, v121, v13
	v_fma_f32 v13, -v7, v122, v13
	v_fma_f32 v13, -v8, v123, v13
	v_fma_f32 v13, -v9, v124, v13
	v_fma_f32 v13, -v10, v125, v13
	v_fma_f32 v13, -v11, v126, v13
	v_fma_f32 v13, -v127, v12, v13
	ds_write_b32 v0, v13 offset:12480
	ds_read_b128 v[116:119], v65 offset:3536
	ds_read_b128 v[120:123], v65 offset:3552
	ds_read_b128 v[124:127], v65 offset:3568
	ds_read_b128 v[128:131], v65 offset:3584
	s_waitcnt lgkmcnt(0)
	v_fma_f32 v14, -v1, v116, v14
	v_fma_f32 v14, -v2, v117, v14
	v_fma_f32 v14, -v3, v118, v14
	v_fma_f32 v14, -v4, v119, v14
	v_fma_f32 v14, -v5, v120, v14
	v_fma_f32 v14, -v6, v121, v14
	v_fma_f32 v14, -v7, v122, v14
	v_fma_f32 v14, -v8, v123, v14
	v_fma_f32 v14, -v9, v124, v14
	v_fma_f32 v14, -v10, v125, v14
	v_fma_f32 v14, -v11, v126, v14
	v_fma_f32 v14, -v12, v127, v14
	v_fma_f32 v14, -v128, v13, v14
	ds_write_b32 v0, v14 offset:13520
	ds_read_b32 v15, v0 offset:14560
	ds_read_b128 v[116:119], v65 offset:3808
	ds_read_b128 v[120:123], v65 offset:3824
	ds_read_b128 v[124:127], v65 offset:3840
	ds_read_b128 v[128:131], v65 offset:3856
	ds_read_b32 v64, v0 offset:15600
	s_waitcnt lgkmcnt(0)
; #define LAS __attribute__((address_space(3)))
; DI void dn_intra(const Params& p, LAS unsigned char* L, int tid_in, int wave, int bid, int G, bool dry) {
;     ...
;         if (tid < 256) {
;             float x[32];
; #pragma unroll
;             for (int i = 0; i < 32; ++i) {
;                 float a = RHS[i * DN_RST + tid];
; #pragma unroll
;                 for (int j4 = 0; j4 < (i + 3) / 4; ++j4) { const f32x4 m4 = *(const LAS f32x4*)(Mm + i * DN_MST + 4 * j4);
; #pragma unroll
;                     for (int e = 0; e < 4; ++e) if (4 * j4 + e < i) a -= m4[e] * x[4 * j4 + e]; }
;                 x[i] = a; RHS[i * DN_RST + tid] = a; if ((i & 1) == 1) __builtin_amdgcn_sched_barrier(0);
;             }
;         }
	v_fma_f32 v15, -v1, v116, v15
	v_fma_f32 v15, -v2, v117, v15
	v_fma_f32 v15, -v3, v118, v15
	v_fma_f32 v15, -v4, v119, v15
	v_fma_f32 v15, -v5, v120, v15
	v_fma_f32 v15, -v6, v121, v15
	v_fma_f32 v15, -v7, v122, v15
	v_fma_f32 v15, -v8, v123, v15
	v_fma_f32 v15, -v9, v124, v15
	v_fma_f32 v15, -v10, v125, v15
	v_fma_f32 v15, -v11, v126, v15
	v_fma_f32 v15, -v12, v127, v15
	v_fma_f32 v15, -v13, v128, v15
	v_fma_f32 v15, -v129, v14, v15
	ds_write_b32 v0, v15 offset:14560
	ds_read_b128 v[116:119], v65 offset:4080
	ds_read_b128 v[120:123], v65 offset:4096
	ds_read_b128 v[124:127], v65 offset:4112
	ds_read_b128 v[128:131], v65 offset:4128
	s_waitcnt lgkmcnt(0)
	v_fma_f32 v64, -v1, v116, v64
	v_fma_f32 v64, -v2, v117, v64
	v_fma_f32 v64, -v3, v118, v64
	v_fma_f32 v64, -v4, v119, v64
	v_fma_f32 v64, -v5, v120, v64
	v_fma_f32 v64, -v6, v121, v64
	v_fma_f32 v64, -v7, v122, v64
	v_fma_f32 v64, -v8, v123, v64
	v_fma_f32 v64, -v9, v124, v64
	v_fma_f32 v64, -v10, v125, v64
	v_fma_f32 v64, -v11, v126, v64
	v_fma_f32 v64, -v12, v127, v64
	v_fma_f32 v64, -v13, v128, v64
	v_fma_f32 v64, -v14, v129, v64
	v_fma_f32 v64, -v130, v15, v64
	ds_write_b32 v0, v64 offset:15600
	ds_read_b32 v66, v0 offset:16640
	ds_read_b128 v[116:119], v65 offset:4352
	ds_read_b128 v[120:123], v65 offset:4368
	ds_read_b128 v[124:127], v65 offset:4384
	ds_read_b128 v[128:131], v65 offset:4400
	s_waitcnt lgkmcnt(0)
	v_fma_f32 v66, -v1, v116, v66
	v_fma_f32 v66, -v2, v117, v66
	v_fma_f32 v66, -v3, v118, v66
	v_fma_f32 v66, -v4, v119, v66
	v_fma_f32 v66, -v5, v120, v66
	v_fma_f32 v66, -v6, v121, v66
	v_fma_f32 v66, -v7, v122, v66
	v_fma_f32 v66, -v8, v123, v66
	v_fma_f32 v66, -v9, v124, v66
	v_fma_f32 v66, -v10, v125, v66
	v_fma_f32 v66, -v11, v126, v66
	v_fma_f32 v66, -v12, v127, v66
	v_fma_f32 v66, -v13, v128, v66
	v_fma_f32 v66, -v14, v129, v66
	v_fma_f32 v66, -v15, v130, v66
	v_fma_f32 v66, -v131, v64, v66
	ds_write_b32 v0, v66 offset:16640
	ds_read_b32 v67, v0 offset:17680
	ds_read_b128 v[116:119], v65 offset:4624
	ds_read_b128 v[120:123], v65 offset:4640
	ds_read_b128 v[124:127], v65 offset:4656
	ds_read_b128 v[128:131], v65 offset:4672
	s_waitcnt lgkmcnt(0)
	v_fma_f32 v67, -v1, v116, v67
	v_fma_f32 v67, -v2, v117, v67
	v_fma_f32 v67, -v3, v118, v67
	v_fma_f32 v67, -v4, v119, v67
	v_fma_f32 v67, -v5, v120, v67
	v_fma_f32 v67, -v6, v121, v67
	v_fma_f32 v67, -v7, v122, v67
	v_fma_f32 v67, -v8, v123, v67
	v_fma_f32 v67, -v9, v124, v67
	v_fma_f32 v67, -v10, v125, v67
	v_fma_f32 v67, -v11, v126, v67
	v_fma_f32 v67, -v12, v127, v67
	ds_read_b128 v[116:119], v65 offset:4688
	v_fma_f32 v67, -v13, v128, v67
	v_fma_f32 v67, -v14, v129, v67
	v_fma_f32 v67, -v15, v130, v67
	v_fma_f32 v67, -v131, v64, v67
	s_waitcnt lgkmcnt(0)
	v_fma_f32 v67, -v116, v66, v67
	ds_write_b32 v0, v67 offset:17680
	ds_read_b32 v132, v0 offset:18720
	ds_read_b128 v[116:119], v65 offset:4896
	ds_read_b128 v[120:123], v65 offset:4912
	ds_read_b128 v[124:127], v65 offset:4928
	ds_read_b128 v[128:131], v65 offset:4944
	s_waitcnt lgkmcnt(0)
	v_fma_f32 v116, -v1, v116, v132
	v_fma_f32 v116, -v2, v117, v116
	v_fma_f32 v116, -v3, v118, v116
	v_fma_f32 v116, -v4, v119, v116
	v_fma_f32 v116, -v5, v120, v116
	v_fma_f32 v116, -v6, v121, v116
	v_fma_f32 v116, -v7, v122, v116
	v_fma_f32 v116, -v8, v123, v116
	v_fma_f32 v116, -v9, v124, v116
	v_fma_f32 v116, -v10, v125, v116
	v_fma_f32 v116, -v11, v126, v116
	v_fma_f32 v116, -v12, v127, v116
	v_fma_f32 v116, -v13, v128, v116
	v_fma_f32 v116, -v14, v129, v116
	v_fma_f32 v116, -v15, v130, v116
	v_fma_f32 v120, -v64, v131, v116
	ds_read_b128 v[116:119], v65 offset:4960
	s_waitcnt lgkmcnt(0)
	v_fma_f32 v116, -v66, v116, v120
	v_fma_f32 v116, -v117, v67, v116
	ds_write_b32 v0, v116 offset:18720
	ds_read_b32 v117, v0 offset:19760
	ds_read_b128 v[118:121], v65 offset:5168
	ds_read_b128 v[122:125], v65 offset:5184
	ds_read_b128 v[126:129], v65 offset:5200
	ds_read_b128 v[130:133], v65 offset:5216
	s_waitcnt lgkmcnt(0)
	v_fma_f32 v117, -v1, v118, v117
	v_fma_f32 v117, -v2, v119, v117
	v_fma_f32 v117, -v3, v120, v117
	v_fma_f32 v117, -v4, v121, v117
	v_fma_f32 v117, -v5, v122, v117
	v_fma_f32 v117, -v6, v123, v117
	v_fma_f32 v117, -v7, v124, v117
	v_fma_f32 v117, -v8, v125, v117
	v_fma_f32 v117, -v9, v126, v117
	v_fma_f32 v117, -v10, v127, v117
	v_fma_f32 v117, -v11, v128, v117
	v_fma_f32 v117, -v12, v129, v117
	ds_read_b128 v[118:121], v65 offset:5232
	v_fma_f32 v117, -v13, v130, v117
	v_fma_f32 v117, -v14, v131, v117
	v_fma_f32 v117, -v15, v132, v117
	v_fma_f32 v117, -v64, v133, v117
	s_waitcnt lgkmcnt(0)
	v_fma_f32 v117, -v66, v118, v117
	v_fma_f32 v117, -v67, v119, v117
	v_fma_f32 v117, -v120, v116, v117
	ds_write_b32 v0, v117 offset:19760
	ds_read_b32 v134, v0 offset:20800
	ds_read_b128 v[118:121], v65 offset:5440
	ds_read_b128 v[122:125], v65 offset:5456
	ds_read_b128 v[126:129], v65 offset:5472
	ds_read_b128 v[130:133], v65 offset:5488
	s_waitcnt lgkmcnt(0)
	v_fma_f32 v118, -v1, v118, v134
	v_fma_f32 v118, -v2, v119, v118
	v_fma_f32 v118, -v3, v120, v118
	v_fma_f32 v118, -v4, v121, v118
	v_fma_f32 v118, -v5, v122, v118
	v_fma_f32 v118, -v6, v123, v118
	v_fma_f32 v118, -v7, v124, v118
	v_fma_f32 v118, -v8, v125, v118
	v_fma_f32 v118, -v9, v126, v118
	v_fma_f32 v118, -v10, v127, v118
	v_fma_f32 v118, -v11, v128, v118
	v_fma_f32 v118, -v12, v129, v118
	v_fma_f32 v118, -v13, v130, v118
	v_fma_f32 v118, -v14, v131, v118
	v_fma_f32 v118, -v15, v132, v118
	v_fma_f32 v122, -v64, v133, v118
	ds_read_b128 v[118:121], v65 offset:5504
	s_waitcnt lgkmcnt(0)
; #define LAS __attribute__((address_space(3)))
; DI void dn_intra(const Params& p, LAS unsigned char* L, int tid_in, int wave, int bid, int G, bool dry) {
;     ...
;         if (tid < 256) {
;             float x[32];
; #pragma unroll
;             for (int i = 0; i < 32; ++i) {
;                 float a = RHS[i * DN_RST + tid];
; #pragma unroll
;                 for (int j4 = 0; j4 < (i + 3) / 4; ++j4) { const f32x4 m4 = *(const LAS f32x4*)(Mm + i * DN_MST + 4 * j4);
; #pragma unroll
;                     for (int e = 0; e < 4; ++e) if (4 * j4 + e < i) a -= m4[e] * x[4 * j4 + e]; }
;                 x[i] = a; RHS[i * DN_RST + tid] = a; if ((i & 1) == 1) __builtin_amdgcn_sched_barrier(0);
;             }
;         }
	v_fma_f32 v118, -v66, v118, v122
	v_fma_f32 v118, -v67, v119, v118
	v_fma_f32 v118, -v120, v116, v118
	v_fma_f32 v118, -v121, v117, v118
	ds_write_b32 v0, v118 offset:20800
	ds_read_b32 v119, v0 offset:21840
	ds_read_b128 v[120:123], v65 offset:5712
	ds_read_b128 v[124:127], v65 offset:5728
	ds_read_b128 v[128:131], v65 offset:5744
	ds_read_b128 v[132:135], v65 offset:5760
	s_waitcnt lgkmcnt(0)
	v_fma_f32 v119, -v1, v120, v119
	v_fma_f32 v119, -v2, v121, v119
	v_fma_f32 v119, -v3, v122, v119
	v_fma_f32 v119, -v4, v123, v119
	v_fma_f32 v119, -v5, v124, v119
	v_fma_f32 v119, -v6, v125, v119
	v_fma_f32 v119, -v7, v126, v119
	v_fma_f32 v119, -v8, v127, v119
	v_fma_f32 v119, -v9, v128, v119
	v_fma_f32 v119, -v10, v129, v119
	v_fma_f32 v119, -v11, v130, v119
	v_fma_f32 v119, -v12, v131, v119
	ds_read_b128 v[120:123], v65 offset:5776
	v_fma_f32 v119, -v13, v132, v119
	v_fma_f32 v119, -v14, v133, v119
	v_fma_f32 v119, -v15, v134, v119
	v_fma_f32 v119, -v64, v135, v119
	s_waitcnt lgkmcnt(0)
	v_fma_f32 v119, -v66, v120, v119
	v_fma_f32 v119, -v67, v121, v119
	v_fma_f32 v119, -v116, v122, v119
	v_fma_f32 v119, -v123, v117, v119
	ds_read_b128 v[120:123], v65 offset:5792
	s_waitcnt lgkmcnt(0)
	v_fma_f32 v119, -v120, v118, v119
	ds_write_b32 v0, v119 offset:21840
	ds_read_b32 v136, v0 offset:22880
	ds_read_b128 v[120:123], v65 offset:5984
	ds_read_b128 v[124:127], v65 offset:6000
	ds_read_b128 v[128:131], v65 offset:6016
	ds_read_b128 v[132:135], v65 offset:6032
	ds_read_b32 v138, v0 offset:23920
	s_waitcnt lgkmcnt(0)
	v_fma_f32 v120, -v1, v120, v136
	v_fma_f32 v120, -v2, v121, v120
	v_fma_f32 v120, -v3, v122, v120
	v_fma_f32 v120, -v4, v123, v120
	v_fma_f32 v120, -v5, v124, v120
	v_fma_f32 v120, -v6, v125, v120
	v_fma_f32 v120, -v7, v126, v120
	v_fma_f32 v120, -v8, v127, v120
	v_fma_f32 v120, -v9, v128, v120
	v_fma_f32 v120, -v10, v129, v120
	v_fma_f32 v120, -v11, v130, v120
	v_fma_f32 v120, -v12, v131, v120
	v_fma_f32 v124, -v13, v132, v120
	ds_read_b128 v[120:123], v65 offset:6048
	v_fma_f32 v124, -v14, v133, v124
	v_fma_f32 v124, -v15, v134, v124
	v_fma_f32 v128, -v64, v135, v124
	ds_read_b128 v[124:127], v65 offset:6064
	s_waitcnt lgkmcnt(0)
	v_fma_f32 v120, -v66, v120, v128
	v_fma_f32 v120, -v67, v121, v120
	v_fma_f32 v120, -v116, v122, v120
	v_fma_f32 v120, -v117, v123, v120
	v_fma_f32 v120, -v124, v118, v120
	v_fma_f32 v120, -v125, v119, v120
	ds_write_b32 v0, v120 offset:22880
	ds_read_b128 v[122:125], v65 offset:6256
	ds_read_b128 v[126:129], v65 offset:6272
	ds_read_b128 v[130:133], v65 offset:6288
	ds_read_b128 v[134:137], v65 offset:6304
	s_waitcnt lgkmcnt(0)
	v_fma_f32 v121, -v1, v122, v138
	v_fma_f32 v121, -v2, v123, v121
	v_fma_f32 v121, -v3, v124, v121
	v_fma_f32 v121, -v4, v125, v121
	v_fma_f32 v121, -v5, v126, v121
	v_fma_f32 v121, -v6, v127, v121
	v_fma_f32 v121, -v7, v128, v121
	v_fma_f32 v121, -v8, v129, v121
	v_fma_f32 v121, -v9, v130, v121
	v_fma_f32 v121, -v10, v131, v121
	v_fma_f32 v121, -v11, v132, v121
	v_fma_f32 v121, -v12, v133, v121
	ds_read_b128 v[122:125], v65 offset:6320
	ds_read_b128 v[126:129], v65 offset:6336
	v_fma_f32 v121, -v13, v134, v121
	v_fma_f32 v121, -v14, v135, v121
	v_fma_f32 v121, -v15, v136, v121
	v_fma_f32 v121, -v64, v137, v121
	s_waitcnt lgkmcnt(0)
	v_fma_f32 v121, -v66, v122, v121
	v_fma_f32 v121, -v67, v123, v121
	v_fma_f32 v121, -v116, v124, v121
	v_fma_f32 v121, -v117, v125, v121
	v_fma_f32 v121, -v118, v126, v121
	v_fma_f32 v121, -v127, v119, v121
	v_fma_f32 v121, -v128, v120, v121
	ds_write_b32 v0, v121 offset:23920
	ds_read_b32 v138, v0 offset:24960
	ds_read_b128 v[122:125], v65 offset:6528
	ds_read_b128 v[126:129], v65 offset:6544
	ds_read_b128 v[130:133], v65 offset:6560
	ds_read_b128 v[134:137], v65 offset:6576
	s_waitcnt lgkmcnt(0)
	v_fma_f32 v122, -v1, v122, v138
	v_fma_f32 v122, -v2, v123, v122
	v_fma_f32 v122, -v3, v124, v122
	v_fma_f32 v122, -v4, v125, v122
	v_fma_f32 v122, -v5, v126, v122
	v_fma_f32 v122, -v6, v127, v122
	v_fma_f32 v122, -v7, v128, v122
	v_fma_f32 v122, -v8, v129, v122
	v_fma_f32 v122, -v9, v130, v122
	v_fma_f32 v122, -v10, v131, v122
	v_fma_f32 v122, -v11, v132, v122
	v_fma_f32 v122, -v12, v133, v122
	v_fma_f32 v122, -v13, v134, v122
	v_fma_f32 v122, -v14, v135, v122
	v_fma_f32 v122, -v15, v136, v122
	v_fma_f32 v126, -v64, v137, v122
	ds_read_b128 v[122:125], v65 offset:6592
	s_waitcnt lgkmcnt(0)
	v_fma_f32 v122, -v66, v122, v126
	v_fma_f32 v122, -v67, v123, v122
	v_fma_f32 v122, -v116, v124, v122
	v_fma_f32 v126, -v117, v125, v122
	ds_read_b128 v[122:125], v65 offset:6608
	s_waitcnt lgkmcnt(0)
	v_fma_f32 v122, -v118, v122, v126
	v_fma_f32 v122, -v119, v123, v122
	v_fma_f32 v122, -v124, v120, v122
	v_fma_f32 v122, -v125, v121, v122
	ds_write_b32 v0, v122 offset:24960
	ds_read_b32 v123, v0 offset:26000
	ds_read_b128 v[124:127], v65 offset:6800
	ds_read_b128 v[128:131], v65 offset:6816
	ds_read_b128 v[132:135], v65 offset:6832
	ds_read_b128 v[136:139], v65 offset:6848
	s_waitcnt lgkmcnt(0)
	v_fma_f32 v123, -v1, v124, v123
	v_fma_f32 v123, -v2, v125, v123
	v_fma_f32 v123, -v3, v126, v123
	v_fma_f32 v123, -v4, v127, v123
	v_fma_f32 v123, -v5, v128, v123
	v_fma_f32 v123, -v6, v129, v123
	v_fma_f32 v123, -v7, v130, v123
	v_fma_f32 v123, -v8, v131, v123
	v_fma_f32 v123, -v9, v132, v123
	v_fma_f32 v123, -v10, v133, v123
	v_fma_f32 v123, -v11, v134, v123
	v_fma_f32 v123, -v12, v135, v123
	ds_read_b128 v[124:127], v65 offset:6864
	v_fma_f32 v123, -v13, v136, v123
	v_fma_f32 v123, -v14, v137, v123
	v_fma_f32 v123, -v15, v138, v123
	v_fma_f32 v123, -v64, v139, v123
	s_waitcnt lgkmcnt(0)
; #define LAS __attribute__((address_space(3)))
; DI void dn_intra(const Params& p, LAS unsigned char* L, int tid_in, int wave, int bid, int G, bool dry) {
;     ...
;         if (tid < 256) {
;             float x[32];
; #pragma unroll
;             for (int i = 0; i < 32; ++i) {
;                 float a = RHS[i * DN_RST + tid];
; #pragma unroll
;                 for (int j4 = 0; j4 < (i + 3) / 4; ++j4) { const f32x4 m4 = *(const LAS f32x4*)(Mm + i * DN_MST + 4 * j4);
; #pragma unroll
;                     for (int e = 0; e < 4; ++e) if (4 * j4 + e < i) a -= m4[e] * x[4 * j4 + e]; }
;                 x[i] = a; RHS[i * DN_RST + tid] = a; if ((i & 1) == 1) __builtin_amdgcn_sched_barrier(0);
;             }
;         }
	v_fma_f32 v123, -v66, v124, v123
	v_fma_f32 v123, -v67, v125, v123
	v_fma_f32 v123, -v116, v126, v123
	v_fma_f32 v123, -v117, v127, v123
	ds_read_b128 v[124:127], v65 offset:6880
	s_waitcnt lgkmcnt(0)
	v_fma_f32 v123, -v118, v124, v123
	v_fma_f32 v123, -v119, v125, v123
	v_fma_f32 v123, -v120, v126, v123
	v_fma_f32 v123, -v127, v121, v123
	ds_read_b128 v[124:127], v65 offset:6896
	s_waitcnt lgkmcnt(0)
	v_fma_f32 v123, -v124, v122, v123
	ds_write_b32 v0, v123 offset:26000
	ds_read_b32 v140, v0 offset:27040
	ds_read_b128 v[124:127], v65 offset:7072
	ds_read_b128 v[128:131], v65 offset:7088
	ds_read_b128 v[132:135], v65 offset:7104
	ds_read_b128 v[136:139], v65 offset:7120
	s_waitcnt lgkmcnt(0)
	v_fma_f32 v124, -v1, v124, v140
	v_fma_f32 v124, -v2, v125, v124
	v_fma_f32 v124, -v3, v126, v124
	v_fma_f32 v124, -v4, v127, v124
	v_fma_f32 v124, -v5, v128, v124
	v_fma_f32 v124, -v6, v129, v124
	v_fma_f32 v124, -v7, v130, v124
	v_fma_f32 v124, -v8, v131, v124
	v_fma_f32 v124, -v9, v132, v124
	v_fma_f32 v124, -v10, v133, v124
	v_fma_f32 v124, -v11, v134, v124
	v_fma_f32 v124, -v12, v135, v124
	v_fma_f32 v124, -v13, v136, v124
	v_fma_f32 v124, -v14, v137, v124
	v_fma_f32 v124, -v15, v138, v124
	v_fma_f32 v128, -v64, v139, v124
	ds_read_b128 v[124:127], v65 offset:7136
	s_waitcnt lgkmcnt(0)
	v_fma_f32 v124, -v66, v124, v128
	v_fma_f32 v124, -v67, v125, v124
	v_fma_f32 v124, -v116, v126, v124
	v_fma_f32 v128, -v117, v127, v124
	ds_read_b128 v[124:127], v65 offset:7152
	s_waitcnt lgkmcnt(0)
	v_fma_f32 v124, -v118, v124, v128
	v_fma_f32 v124, -v119, v125, v124
	v_fma_f32 v124, -v120, v126, v124
	v_fma_f32 v128, -v121, v127, v124
	ds_read_b128 v[124:127], v65 offset:7168
	s_waitcnt lgkmcnt(0)
	v_fma_f32 v124, -v124, v122, v128
	v_fma_f32 v124, -v125, v123, v124
	ds_write_b32 v0, v124 offset:27040
	ds_read_b32 v125, v0 offset:28080
	ds_read_b128 v[126:129], v65 offset:7344
	ds_read_b128 v[130:133], v65 offset:7360
	ds_read_b128 v[134:137], v65 offset:7376
	ds_read_b128 v[138:141], v65 offset:7392
	s_waitcnt lgkmcnt(0)
	v_fma_f32 v125, -v1, v126, v125
	v_fma_f32 v125, -v2, v127, v125
	v_fma_f32 v125, -v3, v128, v125
	v_fma_f32 v125, -v4, v129, v125
	v_fma_f32 v125, -v5, v130, v125
	v_fma_f32 v125, -v6, v131, v125
	v_fma_f32 v125, -v7, v132, v125
	v_fma_f32 v125, -v8, v133, v125
	v_fma_f32 v125, -v9, v134, v125
	v_fma_f32 v125, -v10, v135, v125
	v_fma_f32 v125, -v11, v136, v125
	v_fma_f32 v125, -v12, v137, v125
	ds_read_b128 v[126:129], v65 offset:7408
	v_fma_f32 v125, -v13, v138, v125
	v_fma_f32 v125, -v14, v139, v125
	v_fma_f32 v125, -v15, v140, v125
	v_fma_f32 v125, -v64, v141, v125
	s_waitcnt lgkmcnt(0)
	v_fma_f32 v125, -v66, v126, v125
	v_fma_f32 v125, -v67, v127, v125
	v_fma_f32 v125, -v116, v128, v125
	v_fma_f32 v125, -v117, v129, v125
	ds_read_b128 v[126:129], v65 offset:7424
	s_waitcnt lgkmcnt(0)
	v_fma_f32 v125, -v118, v126, v125
	v_fma_f32 v125, -v119, v127, v125
	v_fma_f32 v125, -v120, v128, v125
	v_fma_f32 v125, -v121, v129, v125
	ds_read_b128 v[126:129], v65 offset:7440
	s_waitcnt lgkmcnt(0)
	v_fma_f32 v125, -v122, v126, v125
	v_fma_f32 v125, -v127, v123, v125
	v_fma_f32 v125, -v128, v124, v125
	ds_write_b32 v0, v125 offset:28080
	ds_read_b32 v142, v0 offset:29120
	ds_read_b128 v[126:129], v65 offset:7616
	ds_read_b128 v[130:133], v65 offset:7632
	ds_read_b128 v[134:137], v65 offset:7648
	ds_read_b128 v[138:141], v65 offset:7664
	s_waitcnt lgkmcnt(0)
	v_fma_f32 v126, -v1, v126, v142
	v_fma_f32 v126, -v2, v127, v126
	v_fma_f32 v126, -v3, v128, v126
	v_fma_f32 v126, -v4, v129, v126
	v_fma_f32 v126, -v5, v130, v126
	v_fma_f32 v126, -v6, v131, v126
	v_fma_f32 v126, -v7, v132, v126
	v_fma_f32 v126, -v8, v133, v126
	v_fma_f32 v126, -v9, v134, v126
	v_fma_f32 v126, -v10, v135, v126
	v_fma_f32 v126, -v11, v136, v126
	v_fma_f32 v126, -v12, v137, v126
	v_fma_f32 v126, -v13, v138, v126
	v_fma_f32 v126, -v14, v139, v126
	v_fma_f32 v126, -v15, v140, v126
	v_fma_f32 v130, -v64, v141, v126
	ds_read_b128 v[126:129], v65 offset:7680
	s_waitcnt lgkmcnt(0)
	v_fma_f32 v126, -v66, v126, v130
	v_fma_f32 v126, -v67, v127, v126
	v_fma_f32 v126, -v116, v128, v126
	v_fma_f32 v130, -v117, v129, v126
	ds_read_b128 v[126:129], v65 offset:7696
	s_waitcnt lgkmcnt(0)
	v_fma_f32 v126, -v118, v126, v130
	v_fma_f32 v126, -v119, v127, v126
	v_fma_f32 v126, -v120, v128, v126
	v_fma_f32 v130, -v121, v129, v126
	ds_read_b128 v[126:129], v65 offset:7712
	s_waitcnt lgkmcnt(0)
; #define LAS __attribute__((address_space(3)))
; DI void dn_intra(const Params& p, LAS unsigned char* L, int tid_in, int wave, int bid, int G, bool dry) {
;     ...
;         if (tid < 256) {
;             float x[32];
; #pragma unroll
;             for (int i = 0; i < 32; ++i) {
;                 float a = RHS[i * DN_RST + tid];
; #pragma unroll
;                 for (int j4 = 0; j4 < (i + 3) / 4; ++j4) { const f32x4 m4 = *(const LAS f32x4*)(Mm + i * DN_MST + 4 * j4);
; #pragma unroll
;                     for (int e = 0; e < 4; ++e) if (4 * j4 + e < i) a -= m4[e] * x[4 * j4 + e]; }
;                 x[i] = a; RHS[i * DN_RST + tid] = a; if ((i & 1) == 1) __builtin_amdgcn_sched_barrier(0);
;             }
;         }
	v_fma_f32 v126, -v122, v126, v130
	v_fma_f32 v126, -v123, v127, v126
	v_fma_f32 v126, -v128, v124, v126
	v_fma_f32 v142, -v129, v125, v126
	ds_write_b32 v0, v142 offset:29120
	ds_read_b32 v143, v0 offset:30160
	ds_read_b128 v[126:129], v65 offset:7888
	ds_read_b128 v[130:133], v65 offset:7904
	ds_read_b128 v[134:137], v65 offset:7920
	ds_read_b128 v[138:141], v65 offset:7936
	s_waitcnt lgkmcnt(0)
	v_fma_f32 v126, -v1, v126, v143
	v_fma_f32 v126, -v2, v127, v126
	v_fma_f32 v126, -v3, v128, v126
	v_fma_f32 v126, -v4, v129, v126
	v_fma_f32 v126, -v5, v130, v126
	v_fma_f32 v126, -v6, v131, v126
	v_fma_f32 v126, -v7, v132, v126
	v_fma_f32 v126, -v8, v133, v126
	v_fma_f32 v126, -v9, v134, v126
	v_fma_f32 v126, -v10, v135, v126
	v_fma_f32 v126, -v11, v136, v126
	v_fma_f32 v126, -v12, v137, v126
	v_fma_f32 v126, -v13, v138, v126
	v_fma_f32 v126, -v14, v139, v126
	v_fma_f32 v126, -v15, v140, v126
	v_fma_f32 v130, -v64, v141, v126
	ds_read_b128 v[126:129], v65 offset:7952
	s_waitcnt lgkmcnt(0)
	v_fma_f32 v126, -v66, v126, v130
	v_fma_f32 v126, -v67, v127, v126
	v_fma_f32 v126, -v116, v128, v126
	v_fma_f32 v130, -v117, v129, v126
	ds_read_b128 v[126:129], v65 offset:7968
	s_waitcnt lgkmcnt(0)
	v_fma_f32 v126, -v118, v126, v130
	v_fma_f32 v126, -v119, v127, v126
	v_fma_f32 v126, -v120, v128, v126
	v_fma_f32 v130, -v121, v129, v126
	ds_read_b128 v[126:129], v65 offset:7984
	s_waitcnt lgkmcnt(0)
	v_fma_f32 v126, -v122, v126, v130
	v_fma_f32 v126, -v123, v127, v126
	v_fma_f32 v126, -v124, v128, v126
	v_fma_f32 v130, -v129, v125, v126
	ds_read_b128 v[126:129], v65 offset:8000
	s_waitcnt lgkmcnt(0)
	v_fma_f32 v143, -v126, v142, v130
	ds_write_b32 v0, v143 offset:30160
	ds_read_b32 v144, v0 offset:31200
	ds_read_b128 v[126:129], v65 offset:8160
	ds_read_b128 v[130:133], v65 offset:8176
	ds_read_b128 v[134:137], v65 offset:8192
	ds_read_b128 v[138:141], v65 offset:8208
	ds_read_b32 v145, v0 offset:32240
	s_waitcnt lgkmcnt(0)
	v_fma_f32 v126, -v1, v126, v144
	v_fma_f32 v126, -v2, v127, v126
	v_fma_f32 v126, -v3, v128, v126
	v_fma_f32 v126, -v4, v129, v126
	v_fma_f32 v126, -v5, v130, v126
	v_fma_f32 v126, -v6, v131, v126
	v_fma_f32 v126, -v7, v132, v126
	v_fma_f32 v126, -v8, v133, v126
	v_fma_f32 v126, -v9, v134, v126
	v_fma_f32 v126, -v10, v135, v126
	v_fma_f32 v126, -v11, v136, v126
	v_fma_f32 v126, -v12, v137, v126
	v_fma_f32 v130, -v13, v138, v126
	ds_read_b128 v[126:129], v65 offset:8224
	v_fma_f32 v130, -v14, v139, v130
	v_fma_f32 v130, -v15, v140, v130
	v_fma_f32 v134, -v64, v141, v130
	ds_read_b128 v[130:133], v65 offset:8240
	s_waitcnt lgkmcnt(0)
	v_fma_f32 v126, -v66, v126, v134
	v_fma_f32 v126, -v67, v127, v126
	v_fma_f32 v126, -v116, v128, v126
	v_fma_f32 v126, -v117, v129, v126
	v_fma_f32 v130, -v118, v130, v126
	ds_read_b128 v[126:129], v65 offset:8256
	v_fma_f32 v130, -v119, v131, v130
	v_fma_f32 v130, -v120, v132, v130
	v_fma_f32 v134, -v121, v133, v130
	ds_read_b128 v[130:133], v65 offset:8272
	s_waitcnt lgkmcnt(0)
	v_fma_f32 v126, -v122, v126, v134
	v_fma_f32 v126, -v123, v127, v126
	v_fma_f32 v126, -v124, v128, v126
	v_fma_f32 v126, -v125, v129, v126
	v_fma_f32 v126, -v130, v142, v126
	v_fma_f32 v144, -v131, v143, v126
	ds_write_b32 v0, v144 offset:31200
	ds_read_b128 v[126:129], v65 offset:8432
	ds_read_b128 v[130:133], v65 offset:8448
	ds_read_b128 v[134:137], v65 offset:8464
	ds_read_b128 v[138:141], v65 offset:8480
	s_waitcnt lgkmcnt(0)
	v_fma_f32 v1, -v1, v126, v145
	v_fma_f32 v1, -v2, v127, v1
	v_fma_f32 v1, -v3, v128, v1
	v_fma_f32 v1, -v4, v129, v1
	v_fma_f32 v1, -v5, v130, v1
	v_fma_f32 v1, -v6, v131, v1
	v_fma_f32 v1, -v7, v132, v1
	v_fma_f32 v1, -v8, v133, v1
	v_fma_f32 v1, -v9, v134, v1
	v_fma_f32 v1, -v10, v135, v1
	v_fma_f32 v1, -v11, v136, v1
	v_fma_f32 v1, -v12, v137, v1
	ds_read_b128 v[2:5], v65 offset:8496
	ds_read_b128 v[6:9], v65 offset:8512
	v_fma_f32 v1, -v13, v138, v1
	v_fma_f32 v1, -v14, v139, v1
	v_fma_f32 v1, -v15, v140, v1
	v_fma_f32 v1, -v64, v141, v1
	s_waitcnt lgkmcnt(0)
	v_fma_f32 v1, -v66, v2, v1
	v_fma_f32 v1, -v67, v3, v1
	v_fma_f32 v1, -v116, v4, v1
	v_fma_f32 v1, -v117, v5, v1
	ds_read_b128 v[2:5], v65 offset:8528
	v_fma_f32 v1, -v118, v6, v1
	v_fma_f32 v1, -v119, v7, v1
	v_fma_f32 v1, -v120, v8, v1
	v_fma_f32 v1, -v121, v9, v1
	ds_read_b128 v[6:9], v65 offset:8544
	s_waitcnt lgkmcnt(0)
	v_fma_f32 v1, -v122, v2, v1
	v_fma_f32 v1, -v123, v3, v1
	v_fma_f32 v1, -v124, v4, v1
	v_fma_f32 v1, -v125, v5, v1
	v_fma_f32 v1, -v142, v6, v1
	v_fma_f32 v1, -v7, v143, v1
	v_fma_f32 v1, -v8, v144, v1
	ds_write_b32 v0, v1 offset:32240

; #define POOL_LD(tt, dst) do { const int _t = (tt); if (_t >= 0) dst = v8_ldbf(XN + (seq0 + _t) * D + c0); else if (s) dst = v8_ldf(sp + ((size_t)b * 15 + 15 + _t) * D + c0); else dst = v8zero(); } while (0)
; DI void pool_diff(const Params& p, int pool_j, int gtid, int NT) {
;     ...
;         for (int j = win - 1; j >= 1; --j) { V8 v; POOL_LD(t0 - j, v); sum.a += v.a; sum.b += v.b; }
.LBB0_1403:
	v_mov_b32_e32 v61, v64
	v_cmp_lt_i32_e32 vcc, 1, v36
	s_cbranch_vccz .Lpw_end0
	v_cmp_lt_i32_e32 vcc, 1, v36
	s_and_saveexec_b64 s[26:27], vcc
	s_cbranch_execz .Lpw_s0
	v_cmp_gt_i32_e32 vcc, 0, v64
	s_and_saveexec_b64 s[18:19], vcc
	s_xor_b64 s[18:19], exec, s[18:19]
	s_cbranch_execz .Lpw_a0
	v_mov_b32_e32 v130, 0
	v_mov_b32_e32 v131, 0
	v_mov_b32_e32 v132, 0
	v_mov_b32_e32 v133, 0
	v_mov_b32_e32 v134, 0
	v_mov_b32_e32 v135, 0
	v_mov_b32_e32 v136, 0
	v_mov_b32_e32 v137, 0
	s_and_saveexec_b64 s[16:17], s[0:1]
	global_load_dwordx4 v[130:133], v[32:33], off
	global_load_dwordx4 v[134:137], v[32:33], off offset:16
	s_or_b64 exec, exec, s[16:17]
.Lpw_a0:
	s_andn2_saveexec_b64 s[18:19], s[18:19]
	v_lshl_add_u64 v[56:57], v[64:65], 0, v[10:11]
	v_lshlrev_b64 v[56:57], 11, v[56:57]
	v_lshl_add_u64 v[56:57], v[12:13], 0, v[56:57]
	global_load_dwordx4 v[98:101], v[56:57], off
.Lpw_s0:
	s_mov_b64 exec, s[26:27]
	v_add_u32_e32 v64, 1, v64
	v_lshl_add_u64 v[32:33], v[32:33], 0, s[96:97]
	v_cmp_lt_i32_e32 vcc, 2, v36
	s_and_saveexec_b64 s[26:27], vcc
	s_cbranch_execz .Lpw_s1
	v_cmp_gt_i32_e32 vcc, 0, v64
	s_and_saveexec_b64 s[18:19], vcc
	s_xor_b64 s[18:19], exec, s[18:19]
	s_cbranch_execz .Lpw_a1
	v_mov_b32_e32 v138, 0
	v_mov_b32_e32 v139, 0
	v_mov_b32_e32 v140, 0
	v_mov_b32_e32 v141, 0
	v_mov_b32_e32 v142, 0
	v_mov_b32_e32 v143, 0
	v_mov_b32_e32 v144, 0
	v_mov_b32_e32 v145, 0
	s_and_saveexec_b64 s[16:17], s[0:1]
	global_load_dwordx4 v[138:141], v[32:33], off
	global_load_dwordx4 v[142:145], v[32:33], off offset:16
	s_or_b64 exec, exec, s[16:17]
.Lpw_a1:
	s_andn2_saveexec_b64 s[18:19], s[18:19]
	v_lshl_add_u64 v[56:57], v[64:65], 0, v[10:11]
	v_lshlrev_b64 v[56:57], 11, v[56:57]
	v_lshl_add_u64 v[56:57], v[12:13], 0, v[56:57]
	global_load_dwordx4 v[102:105], v[56:57], off
.Lpw_s1:
	s_mov_b64 exec, s[26:27]
	v_add_u32_e32 v64, 1, v64
	v_lshl_add_u64 v[32:33], v[32:33], 0, s[96:97]
	v_cmp_lt_i32_e32 vcc, 3, v36
	s_and_saveexec_b64 s[26:27], vcc
	s_cbranch_execz .Lpw_s2
	v_cmp_gt_i32_e32 vcc, 0, v64
	s_and_saveexec_b64 s[18:19], vcc
	s_xor_b64 s[18:19], exec, s[18:19]
	s_cbranch_execz .Lpw_a2
	v_mov_b32_e32 v146, 0
	v_mov_b32_e32 v147, 0
	v_mov_b32_e32 v148, 0
	v_mov_b32_e32 v149, 0
	v_mov_b32_e32 v150, 0
	v_mov_b32_e32 v151, 0
	v_mov_b32_e32 v152, 0
	v_mov_b32_e32 v153, 0
	s_and_saveexec_b64 s[16:17], s[0:1]
	global_load_dwordx4 v[146:149], v[32:33], off
	global_load_dwordx4 v[150:153], v[32:33], off offset:16
	s_or_b64 exec, exec, s[16:17]
.Lpw_a2:
	s_andn2_saveexec_b64 s[18:19], s[18:19]
	v_lshl_add_u64 v[56:57], v[64:65], 0, v[10:11]
	v_lshlrev_b64 v[56:57], 11, v[56:57]
	v_lshl_add_u64 v[56:57], v[12:13], 0, v[56:57]
	global_load_dwordx4 v[106:109], v[56:57], off
.Lpw_s2:
	s_mov_b64 exec, s[26:27]
	v_add_u32_e32 v64, 1, v64
	v_lshl_add_u64 v[32:33], v[32:33], 0, s[96:97]
	v_cmp_lt_i32_e32 vcc, 4, v36
	s_and_saveexec_b64 s[26:27], vcc
	s_cbranch_execz .Lpw_s3
	v_cmp_gt_i32_e32 vcc, 0, v64
	s_and_saveexec_b64 s[18:19], vcc
	s_xor_b64 s[18:19], exec, s[18:19]
	s_cbranch_execz .Lpw_a3
	v_mov_b32_e32 v154, 0
	v_mov_b32_e32 v155, 0
	v_mov_b32_e32 v156, 0
	v_mov_b32_e32 v157, 0
	v_mov_b32_e32 v158, 0
	v_mov_b32_e32 v159, 0
	v_mov_b32_e32 v160, 0
	v_mov_b32_e32 v161, 0
	s_and_saveexec_b64 s[16:17], s[0:1]
	global_load_dwordx4 v[154:157], v[32:33], off
	global_load_dwordx4 v[158:161], v[32:33], off offset:16
	s_or_b64 exec, exec, s[16:17]
.Lpw_a3:
	s_andn2_saveexec_b64 s[18:19], s[18:19]
	v_lshl_add_u64 v[56:57], v[64:65], 0, v[10:11]
	v_lshlrev_b64 v[56:57], 11, v[56:57]
	v_lshl_add_u64 v[56:57], v[12:13], 0, v[56:57]
	global_load_dwordx4 v[110:113], v[56:57], off
.Lpw_s3:
	s_mov_b64 exec, s[26:27]
	v_add_u32_e32 v64, 1, v64
	v_lshl_add_u64 v[32:33], v[32:33], 0, s[96:97]
	v_cmp_lt_i32_e32 vcc, 5, v36
	s_and_saveexec_b64 s[26:27], vcc
	s_cbranch_execz .Lpw_s4
	v_cmp_gt_i32_e32 vcc, 0, v64
	s_and_saveexec_b64 s[18:19], vcc
	s_xor_b64 s[18:19], exec, s[18:19]
	s_cbranch_execz .Lpw_a4
	v_mov_b32_e32 v162, 0
	v_mov_b32_e32 v163, 0
	v_mov_b32_e32 v164, 0
	v_mov_b32_e32 v165, 0
	v_mov_b32_e32 v166, 0
	v_mov_b32_e32 v167, 0
	v_mov_b32_e32 v168, 0
	v_mov_b32_e32 v169, 0
	s_and_saveexec_b64 s[16:17], s[0:1]
	global_load_dwordx4 v[162:165], v[32:33], off
	global_load_dwordx4 v[166:169], v[32:33], off offset:16
	s_or_b64 exec, exec, s[16:17]
.Lpw_a4:
	s_andn2_saveexec_b64 s[18:19], s[18:19]
	v_lshl_add_u64 v[56:57], v[64:65], 0, v[10:11]
	v_lshlrev_b64 v[56:57], 11, v[56:57]
	v_lshl_add_u64 v[56:57], v[12:13], 0, v[56:57]
	global_load_dwordx4 v[114:117], v[56:57], off
.Lpw_s4:
	s_mov_b64 exec, s[26:27]
	v_add_u32_e32 v64, 1, v64
	v_lshl_add_u64 v[32:33], v[32:33], 0, s[96:97]
	v_cmp_lt_i32_e32 vcc, 6, v36
	s_and_saveexec_b64 s[26:27], vcc
	s_cbranch_execz .Lpw_s5
	v_cmp_gt_i32_e32 vcc, 0, v64
	s_and_saveexec_b64 s[18:19], vcc
	s_xor_b64 s[18:19], exec, s[18:19]
	s_cbranch_execz .Lpw_a5
	v_mov_b32_e32 v170, 0
	v_mov_b32_e32 v171, 0
	v_mov_b32_e32 v172, 0
	v_mov_b32_e32 v173, 0
	v_mov_b32_e32 v174, 0
	v_mov_b32_e32 v175, 0
	v_mov_b32_e32 v176, 0
	v_mov_b32_e32 v177, 0
	s_and_saveexec_b64 s[16:17], s[0:1]
	global_load_dwordx4 v[170:173], v[32:33], off
	global_load_dwordx4 v[174:177], v[32:33], off offset:16
	s_or_b64 exec, exec, s[16:17]
.Lpw_a5:
	s_andn2_saveexec_b64 s[18:19], s[18:19]
	v_lshl_add_u64 v[56:57], v[64:65], 0, v[10:11]
	v_lshlrev_b64 v[56:57], 11, v[56:57]
	v_lshl_add_u64 v[56:57], v[12:13], 0, v[56:57]
	global_load_dwordx4 v[118:121], v[56:57], off
; #define POOL_LD(tt, dst) do { const int _t = (tt); if (_t >= 0) dst = v8_ldbf(XN + (seq0 + _t) * D + c0); else if (s) dst = v8_ldf(sp + ((size_t)b * 15 + 15 + _t) * D + c0); else dst = v8zero(); } while (0)
; DI void pool_diff(const Params& p, int pool_j, int gtid, int NT) {
;     ...
;         for (int j = win - 1; j >= 1; --j) { V8 v; POOL_LD(t0 - j, v); sum.a += v.a; sum.b += v.b; }
.Lpw_s5:
	s_mov_b64 exec, s[26:27]
	v_add_u32_e32 v64, 1, v64
	v_lshl_add_u64 v[32:33], v[32:33], 0, s[96:97]
	v_cmp_lt_i32_e32 vcc, 7, v36
	s_and_saveexec_b64 s[26:27], vcc
	s_cbranch_execz .Lpw_s6
	v_cmp_gt_i32_e32 vcc, 0, v64
	s_and_saveexec_b64 s[18:19], vcc
	s_xor_b64 s[18:19], exec, s[18:19]
	s_cbranch_execz .Lpw_a6
	v_mov_b32_e32 v178, 0
	v_mov_b32_e32 v179, 0
	v_mov_b32_e32 v180, 0
	v_mov_b32_e32 v181, 0
	v_mov_b32_e32 v182, 0
	v_mov_b32_e32 v183, 0
	v_mov_b32_e32 v184, 0
	v_mov_b32_e32 v185, 0
	s_and_saveexec_b64 s[16:17], s[0:1]
	global_load_dwordx4 v[178:181], v[32:33], off
	global_load_dwordx4 v[182:185], v[32:33], off offset:16
	s_or_b64 exec, exec, s[16:17]
.Lpw_a6:
	s_andn2_saveexec_b64 s[18:19], s[18:19]
	v_lshl_add_u64 v[56:57], v[64:65], 0, v[10:11]
	v_lshlrev_b64 v[56:57], 11, v[56:57]
	v_lshl_add_u64 v[56:57], v[12:13], 0, v[56:57]
	global_load_dwordx4 v[122:125], v[56:57], off
.Lpw_s6:
	s_mov_b64 exec, s[26:27]
	v_add_u32_e32 v64, 1, v64
	v_lshl_add_u64 v[32:33], v[32:33], 0, s[96:97]
	v_cmp_lt_i32_e32 vcc, 8, v36
	s_and_saveexec_b64 s[26:27], vcc
	s_cbranch_execz .Lpw_s7
	v_cmp_gt_i32_e32 vcc, 0, v64
	s_and_saveexec_b64 s[18:19], vcc
	s_xor_b64 s[18:19], exec, s[18:19]
	s_cbranch_execz .Lpw_a7
	v_mov_b32_e32 v186, 0
	v_mov_b32_e32 v187, 0
	v_mov_b32_e32 v188, 0
	v_mov_b32_e32 v189, 0
	v_mov_b32_e32 v190, 0
	v_mov_b32_e32 v191, 0
	v_mov_b32_e32 v192, 0
	v_mov_b32_e32 v193, 0
	s_and_saveexec_b64 s[16:17], s[0:1]
	global_load_dwordx4 v[186:189], v[32:33], off
	global_load_dwordx4 v[190:193], v[32:33], off offset:16
	s_or_b64 exec, exec, s[16:17]
.Lpw_a7:
	s_andn2_saveexec_b64 s[18:19], s[18:19]
	v_lshl_add_u64 v[56:57], v[64:65], 0, v[10:11]
	v_lshlrev_b64 v[56:57], 11, v[56:57]
	v_lshl_add_u64 v[56:57], v[12:13], 0, v[56:57]
	global_load_dwordx4 v[126:129], v[56:57], off
.Lpw_s7:
	s_mov_b64 exec, s[26:27]
	v_add_u32_e32 v64, 1, v64
	v_lshl_add_u64 v[32:33], v[32:33], 0, s[96:97]
	s_waitcnt vmcnt(0)
	v_cmp_lt_i32_e32 vcc, 1, v36
	s_and_saveexec_b64 s[26:27], vcc
	s_cbranch_execz .Lpw_t0
	v_add_u32_e32 v60, 0, v61
	v_cmp_le_i32_e32 vcc, 0, v60
	s_and_saveexec_b64 s[18:19], vcc
	v_lshlrev_b32_e32 v130, 16, v98
	v_and_b32_e32 v131, 0xffff0000, v98
	v_lshlrev_b32_e32 v132, 16, v99
	v_and_b32_e32 v133, 0xffff0000, v99
	v_lshlrev_b32_e32 v134, 16, v100
	v_and_b32_e32 v135, 0xffff0000, v100
	v_lshlrev_b32_e32 v136, 16, v101
	v_and_b32_e32 v137, 0xffff0000, v101
	s_or_b64 exec, exec, s[18:19]
	v_pk_add_f32 v[18:19], v[18:19], v[130:131]
	v_pk_add_f32 v[20:21], v[20:21], v[132:133]
	v_pk_add_f32 v[16:17], v[16:17], v[134:135]
	v_pk_add_f32 v[22:23], v[22:23], v[136:137]
.Lpw_t0:
	s_mov_b64 exec, s[26:27]
	v_cmp_lt_i32_e32 vcc, 2, v36
	s_and_saveexec_b64 s[26:27], vcc
	s_cbranch_execz .Lpw_t1
	v_add_u32_e32 v60, 1, v61
	v_cmp_le_i32_e32 vcc, 0, v60
	s_and_saveexec_b64 s[18:19], vcc
	v_lshlrev_b32_e32 v138, 16, v102
	v_and_b32_e32 v139, 0xffff0000, v102
	v_lshlrev_b32_e32 v140, 16, v103
	v_and_b32_e32 v141, 0xffff0000, v103
	v_lshlrev_b32_e32 v142, 16, v104
	v_and_b32_e32 v143, 0xffff0000, v104
	v_lshlrev_b32_e32 v144, 16, v105
	v_and_b32_e32 v145, 0xffff0000, v105
	s_or_b64 exec, exec, s[18:19]
	v_pk_add_f32 v[18:19], v[18:19], v[138:139]
	v_pk_add_f32 v[20:21], v[20:21], v[140:141]
	v_pk_add_f32 v[16:17], v[16:17], v[142:143]
	v_pk_add_f32 v[22:23], v[22:23], v[144:145]
.Lpw_t1:
	s_mov_b64 exec, s[26:27]
	v_cmp_lt_i32_e32 vcc, 3, v36
	s_and_saveexec_b64 s[26:27], vcc
	s_cbranch_execz .Lpw_t2
	v_add_u32_e32 v60, 2, v61
	v_cmp_le_i32_e32 vcc, 0, v60
	s_and_saveexec_b64 s[18:19], vcc
	v_lshlrev_b32_e32 v146, 16, v106
	v_and_b32_e32 v147, 0xffff0000, v106
	v_lshlrev_b32_e32 v148, 16, v107
	v_and_b32_e32 v149, 0xffff0000, v107
	v_lshlrev_b32_e32 v150, 16, v108
	v_and_b32_e32 v151, 0xffff0000, v108
	v_lshlrev_b32_e32 v152, 16, v109
	v_and_b32_e32 v153, 0xffff0000, v109
	s_or_b64 exec, exec, s[18:19]
	v_pk_add_f32 v[18:19], v[18:19], v[146:147]
	v_pk_add_f32 v[20:21], v[20:21], v[148:149]
	v_pk_add_f32 v[16:17], v[16:17], v[150:151]
	v_pk_add_f32 v[22:23], v[22:23], v[152:153]
; #define POOL_LD(tt, dst) do { const int _t = (tt); if (_t >= 0) dst = v8_ldbf(XN + (seq0 + _t) * D + c0); else if (s) dst = v8_ldf(sp + ((size_t)b * 15 + 15 + _t) * D + c0); else dst = v8zero(); } while (0)
; DI void pool_diff(const Params& p, int pool_j, int gtid, int NT) {
;     ...
;         for (int j = win - 1; j >= 1; --j) { V8 v; POOL_LD(t0 - j, v); sum.a += v.a; sum.b += v.b; }
.Lpw_t2:
	s_mov_b64 exec, s[26:27]
	v_cmp_lt_i32_e32 vcc, 4, v36
	s_and_saveexec_b64 s[26:27], vcc
	s_cbranch_execz .Lpw_t3
	v_add_u32_e32 v60, 3, v61
	v_cmp_le_i32_e32 vcc, 0, v60
	s_and_saveexec_b64 s[18:19], vcc
	v_lshlrev_b32_e32 v154, 16, v110
	v_and_b32_e32 v155, 0xffff0000, v110
	v_lshlrev_b32_e32 v156, 16, v111
	v_and_b32_e32 v157, 0xffff0000, v111
	v_lshlrev_b32_e32 v158, 16, v112
	v_and_b32_e32 v159, 0xffff0000, v112
	v_lshlrev_b32_e32 v160, 16, v113
	v_and_b32_e32 v161, 0xffff0000, v113
	s_or_b64 exec, exec, s[18:19]
	v_pk_add_f32 v[18:19], v[18:19], v[154:155]
	v_pk_add_f32 v[20:21], v[20:21], v[156:157]
	v_pk_add_f32 v[16:17], v[16:17], v[158:159]
	v_pk_add_f32 v[22:23], v[22:23], v[160:161]
.Lpw_t3:
	s_mov_b64 exec, s[26:27]
	v_cmp_lt_i32_e32 vcc, 5, v36
	s_and_saveexec_b64 s[26:27], vcc
	s_cbranch_execz .Lpw_t4
	v_add_u32_e32 v60, 4, v61
	v_cmp_le_i32_e32 vcc, 0, v60
	s_and_saveexec_b64 s[18:19], vcc
	v_lshlrev_b32_e32 v162, 16, v114
	v_and_b32_e32 v163, 0xffff0000, v114
	v_lshlrev_b32_e32 v164, 16, v115
	v_and_b32_e32 v165, 0xffff0000, v115
	v_lshlrev_b32_e32 v166, 16, v116
	v_and_b32_e32 v167, 0xffff0000, v116
	v_lshlrev_b32_e32 v168, 16, v117
	v_and_b32_e32 v169, 0xffff0000, v117
	s_or_b64 exec, exec, s[18:19]
	v_pk_add_f32 v[18:19], v[18:19], v[162:163]
	v_pk_add_f32 v[20:21], v[20:21], v[164:165]
	v_pk_add_f32 v[16:17], v[16:17], v[166:167]
	v_pk_add_f32 v[22:23], v[22:23], v[168:169]
.Lpw_t4:
	s_mov_b64 exec, s[26:27]
	v_cmp_lt_i32_e32 vcc, 6, v36
	s_and_saveexec_b64 s[26:27], vcc
	s_cbranch_execz .Lpw_t5
	v_add_u32_e32 v60, 5, v61
	v_cmp_le_i32_e32 vcc, 0, v60
	s_and_saveexec_b64 s[18:19], vcc
	v_lshlrev_b32_e32 v170, 16, v118
	v_and_b32_e32 v171, 0xffff0000, v118
	v_lshlrev_b32_e32 v172, 16, v119
	v_and_b32_e32 v173, 0xffff0000, v119
	v_lshlrev_b32_e32 v174, 16, v120
	v_and_b32_e32 v175, 0xffff0000, v120
	v_lshlrev_b32_e32 v176, 16, v121
	v_and_b32_e32 v177, 0xffff0000, v121
	s_or_b64 exec, exec, s[18:19]
	v_pk_add_f32 v[18:19], v[18:19], v[170:171]
	v_pk_add_f32 v[20:21], v[20:21], v[172:173]
	v_pk_add_f32 v[16:17], v[16:17], v[174:175]
	v_pk_add_f32 v[22:23], v[22:23], v[176:177]
.Lpw_t5:
	s_mov_b64 exec, s[26:27]
	v_cmp_lt_i32_e32 vcc, 7, v36
	s_and_saveexec_b64 s[26:27], vcc
	s_cbranch_execz .Lpw_t6
	v_add_u32_e32 v60, 6, v61
	v_cmp_le_i32_e32 vcc, 0, v60
	s_and_saveexec_b64 s[18:19], vcc
	v_lshlrev_b32_e32 v178, 16, v122
	v_and_b32_e32 v179, 0xffff0000, v122
	v_lshlrev_b32_e32 v180, 16, v123
	v_and_b32_e32 v181, 0xffff0000, v123
	v_lshlrev_b32_e32 v182, 16, v124
	v_and_b32_e32 v183, 0xffff0000, v124
	v_lshlrev_b32_e32 v184, 16, v125
	v_and_b32_e32 v185, 0xffff0000, v125
	s_or_b64 exec, exec, s[18:19]
	v_pk_add_f32 v[18:19], v[18:19], v[178:179]
	v_pk_add_f32 v[20:21], v[20:21], v[180:181]
	v_pk_add_f32 v[16:17], v[16:17], v[182:183]
	v_pk_add_f32 v[22:23], v[22:23], v[184:185]
.Lpw_t6:
	s_mov_b64 exec, s[26:27]
	v_cmp_lt_i32_e32 vcc, 8, v36
	s_and_saveexec_b64 s[26:27], vcc
	s_cbranch_execz .Lpw_t7
	v_add_u32_e32 v60, 7, v61
	v_cmp_le_i32_e32 vcc, 0, v60
	s_and_saveexec_b64 s[18:19], vcc
	v_lshlrev_b32_e32 v186, 16, v126
	v_and_b32_e32 v187, 0xffff0000, v126
	v_lshlrev_b32_e32 v188, 16, v127
	v_and_b32_e32 v189, 0xffff0000, v127
	v_lshlrev_b32_e32 v190, 16, v128
	v_and_b32_e32 v191, 0xffff0000, v128
	v_lshlrev_b32_e32 v192, 16, v129
	v_and_b32_e32 v193, 0xffff0000, v129
	s_or_b64 exec, exec, s[18:19]
	v_pk_add_f32 v[18:19], v[18:19], v[186:187]
	v_pk_add_f32 v[20:21], v[20:21], v[188:189]
	v_pk_add_f32 v[16:17], v[16:17], v[190:191]
	v_pk_add_f32 v[22:23], v[22:23], v[192:193]
.Lpw_t7:
	s_mov_b64 exec, s[26:27]
.Lpw_end0:
	v_mov_b32_e32 v61, v64
	v_cmp_lt_i32_e32 vcc, 9, v36
	s_cbranch_vccz .Lpw_end1
	v_cmp_lt_i32_e32 vcc, 9, v36
	s_and_saveexec_b64 s[26:27], vcc
	s_cbranch_execz .Lpw_s8
	v_cmp_gt_i32_e32 vcc, 0, v64
	s_and_saveexec_b64 s[18:19], vcc
	s_xor_b64 s[18:19], exec, s[18:19]
	s_cbranch_execz .Lpw_a8
	v_mov_b32_e32 v130, 0
	v_mov_b32_e32 v131, 0
	v_mov_b32_e32 v132, 0
	v_mov_b32_e32 v133, 0
	v_mov_b32_e32 v134, 0
	v_mov_b32_e32 v135, 0
	v_mov_b32_e32 v136, 0
	v_mov_b32_e32 v137, 0
	s_and_saveexec_b64 s[16:17], s[0:1]
	global_load_dwordx4 v[130:133], v[32:33], off
	global_load_dwordx4 v[134:137], v[32:33], off offset:16
	s_or_b64 exec, exec, s[16:17]

; #define POOL_LD(tt, dst) do { const int _t = (tt); if (_t >= 0) dst = v8_ldbf(XN + (seq0 + _t) * D + c0); else if (s) dst = v8_ldf(sp + ((size_t)b * 15 + 15 + _t) * D + c0); else dst = v8zero(); } while (0)
; DI void pool_diff(const Params& p, int pool_j, int gtid, int NT) {
;     ...
;         for (int j = win - 1; j >= 1; --j) { V8 v; POOL_LD(t0 - j, v); sum.a += v.a; sum.b += v.b; }
.Lpw_s8:
	s_mov_b64 exec, s[26:27]
	v_add_u32_e32 v64, 1, v64
	v_lshl_add_u64 v[32:33], v[32:33], 0, s[96:97]
	v_cmp_lt_i32_e32 vcc, 10, v36
	s_and_saveexec_b64 s[26:27], vcc
	s_cbranch_execz .Lpw_s9
	v_cmp_gt_i32_e32 vcc, 0, v64
	s_and_saveexec_b64 s[18:19], vcc
	s_xor_b64 s[18:19], exec, s[18:19]
	s_cbranch_execz .Lpw_a9
	v_mov_b32_e32 v138, 0
	v_mov_b32_e32 v139, 0
	v_mov_b32_e32 v140, 0
	v_mov_b32_e32 v141, 0
	v_mov_b32_e32 v142, 0
	v_mov_b32_e32 v143, 0
	v_mov_b32_e32 v144, 0
	v_mov_b32_e32 v145, 0
	s_and_saveexec_b64 s[16:17], s[0:1]
	global_load_dwordx4 v[138:141], v[32:33], off
	global_load_dwordx4 v[142:145], v[32:33], off offset:16
	s_or_b64 exec, exec, s[16:17]

; #define POOL_LD(tt, dst) do { const int _t = (tt); if (_t >= 0) dst = v8_ldbf(XN + (seq0 + _t) * D + c0); else if (s) dst = v8_ldf(sp + ((size_t)b * 15 + 15 + _t) * D + c0); else dst = v8zero(); } while (0)
; DI void pool_diff(const Params& p, int pool_j, int gtid, int NT) {
;     ...
;         for (int j = win - 1; j >= 1; --j) { V8 v; POOL_LD(t0 - j, v); sum.a += v.a; sum.b += v.b; }
.Lpw_s9:
	s_mov_b64 exec, s[26:27]
	v_add_u32_e32 v64, 1, v64
	v_lshl_add_u64 v[32:33], v[32:33], 0, s[96:97]
	v_cmp_lt_i32_e32 vcc, 11, v36
	s_and_saveexec_b64 s[26:27], vcc
	s_cbranch_execz .Lpw_s10
	v_cmp_gt_i32_e32 vcc, 0, v64
	s_and_saveexec_b64 s[18:19], vcc
	s_xor_b64 s[18:19], exec, s[18:19]
	s_cbranch_execz .Lpw_a10
	v_mov_b32_e32 v146, 0
	v_mov_b32_e32 v147, 0
	v_mov_b32_e32 v148, 0
	v_mov_b32_e32 v149, 0
	v_mov_b32_e32 v150, 0
	v_mov_b32_e32 v151, 0
	v_mov_b32_e32 v152, 0
	v_mov_b32_e32 v153, 0
	s_and_saveexec_b64 s[16:17], s[0:1]
	global_load_dwordx4 v[146:149], v[32:33], off
	global_load_dwordx4 v[150:153], v[32:33], off offset:16
	s_or_b64 exec, exec, s[16:17]

; #define POOL_LD(tt, dst) do { const int _t = (tt); if (_t >= 0) dst = v8_ldbf(XN + (seq0 + _t) * D + c0); else if (s) dst = v8_ldf(sp + ((size_t)b * 15 + 15 + _t) * D + c0); else dst = v8zero(); } while (0)
; DI void pool_diff(const Params& p, int pool_j, int gtid, int NT) {
;     ...
;         for (int j = win - 1; j >= 1; --j) { V8 v; POOL_LD(t0 - j, v); sum.a += v.a; sum.b += v.b; }
.Lpw_s10:
	s_mov_b64 exec, s[26:27]
	v_add_u32_e32 v64, 1, v64
	v_lshl_add_u64 v[32:33], v[32:33], 0, s[96:97]
	v_cmp_lt_i32_e32 vcc, 12, v36
	s_and_saveexec_b64 s[26:27], vcc
	s_cbranch_execz .Lpw_s11
	v_cmp_gt_i32_e32 vcc, 0, v64
	s_and_saveexec_b64 s[18:19], vcc
	s_xor_b64 s[18:19], exec, s[18:19]
	s_cbranch_execz .Lpw_a11
	v_mov_b32_e32 v154, 0
	v_mov_b32_e32 v155, 0
	v_mov_b32_e32 v156, 0
	v_mov_b32_e32 v157, 0
	v_mov_b32_e32 v158, 0
	v_mov_b32_e32 v159, 0
	v_mov_b32_e32 v160, 0
	v_mov_b32_e32 v161, 0
	s_and_saveexec_b64 s[16:17], s[0:1]
	global_load_dwordx4 v[154:157], v[32:33], off
	global_load_dwordx4 v[158:161], v[32:33], off offset:16
	s_or_b64 exec, exec, s[16:17]

; #define POOL_LD(tt, dst) do { const int _t = (tt); if (_t >= 0) dst = v8_ldbf(XN + (seq0 + _t) * D + c0); else if (s) dst = v8_ldf(sp + ((size_t)b * 15 + 15 + _t) * D + c0); else dst = v8zero(); } while (0)
; DI void pool_diff(const Params& p, int pool_j, int gtid, int NT) {
;     ...
;         for (int j = win - 1; j >= 1; --j) { V8 v; POOL_LD(t0 - j, v); sum.a += v.a; sum.b += v.b; }
.Lpw_s11:
	s_mov_b64 exec, s[26:27]
	v_add_u32_e32 v64, 1, v64
	v_lshl_add_u64 v[32:33], v[32:33], 0, s[96:97]
	v_cmp_lt_i32_e32 vcc, 13, v36
	s_and_saveexec_b64 s[26:27], vcc
	s_cbranch_execz .Lpw_s12
	v_cmp_gt_i32_e32 vcc, 0, v64
	s_and_saveexec_b64 s[18:19], vcc
	s_xor_b64 s[18:19], exec, s[18:19]
	s_cbranch_execz .Lpw_a12
	v_mov_b32_e32 v162, 0
	v_mov_b32_e32 v163, 0
	v_mov_b32_e32 v164, 0
	v_mov_b32_e32 v165, 0
	v_mov_b32_e32 v166, 0
	v_mov_b32_e32 v167, 0
	v_mov_b32_e32 v168, 0
	v_mov_b32_e32 v169, 0
	s_and_saveexec_b64 s[16:17], s[0:1]
	global_load_dwordx4 v[162:165], v[32:33], off
	global_load_dwordx4 v[166:169], v[32:33], off offset:16
	s_or_b64 exec, exec, s[16:17]

; #define POOL_LD(tt, dst) do { const int _t = (tt); if (_t >= 0) dst = v8_ldbf(XN + (seq0 + _t) * D + c0); else if (s) dst = v8_ldf(sp + ((size_t)b * 15 + 15 + _t) * D + c0); else dst = v8zero(); } while (0)
; DI void pool_diff(const Params& p, int pool_j, int gtid, int NT) {
;     ...
;         for (int j = win - 1; j >= 1; --j) { V8 v; POOL_LD(t0 - j, v); sum.a += v.a; sum.b += v.b; }
.Lpw_s12:
	s_mov_b64 exec, s[26:27]
	v_add_u32_e32 v64, 1, v64
	v_lshl_add_u64 v[32:33], v[32:33], 0, s[96:97]
	v_cmp_lt_i32_e32 vcc, 14, v36
	s_and_saveexec_b64 s[26:27], vcc
	s_cbranch_execz .Lpw_s13
	v_cmp_gt_i32_e32 vcc, 0, v64
	s_and_saveexec_b64 s[18:19], vcc
	s_xor_b64 s[18:19], exec, s[18:19]
	s_cbranch_execz .Lpw_a13
	v_mov_b32_e32 v170, 0
	v_mov_b32_e32 v171, 0
	v_mov_b32_e32 v172, 0
	v_mov_b32_e32 v173, 0
	v_mov_b32_e32 v174, 0
	v_mov_b32_e32 v175, 0
	v_mov_b32_e32 v176, 0
	v_mov_b32_e32 v177, 0
	s_and_saveexec_b64 s[16:17], s[0:1]
	global_load_dwordx4 v[170:173], v[32:33], off
	global_load_dwordx4 v[174:177], v[32:33], off offset:16
	s_or_b64 exec, exec, s[16:17]

; #define POOL_LD(tt, dst) do { const int _t = (tt); if (_t >= 0) dst = v8_ldbf(XN + (seq0 + _t) * D + c0); else if (s) dst = v8_ldf(sp + ((size_t)b * 15 + 15 + _t) * D + c0); else dst = v8zero(); } while (0)
; DI void pool_diff(const Params& p, int pool_j, int gtid, int NT) {
;     ...
;         for (int j = win - 1; j >= 1; --j) { V8 v; POOL_LD(t0 - j, v); sum.a += v.a; sum.b += v.b; }
.Lpw_s13:
	s_mov_b64 exec, s[26:27]
	v_add_u32_e32 v64, 1, v64
	v_lshl_add_u64 v[32:33], v[32:33], 0, s[96:97]
	v_cmp_lt_i32_e32 vcc, 15, v36
	s_and_saveexec_b64 s[26:27], vcc
	s_cbranch_execz .Lpw_s14
	v_cmp_gt_i32_e32 vcc, 0, v64
	s_and_saveexec_b64 s[18:19], vcc
	s_xor_b64 s[18:19], exec, s[18:19]
	s_cbranch_execz .Lpw_a14
	v_mov_b32_e32 v178, 0
	v_mov_b32_e32 v179, 0
	v_mov_b32_e32 v180, 0
	v_mov_b32_e32 v181, 0
	v_mov_b32_e32 v182, 0
	v_mov_b32_e32 v183, 0
	v_mov_b32_e32 v184, 0
	v_mov_b32_e32 v185, 0
	s_and_saveexec_b64 s[16:17], s[0:1]
	global_load_dwordx4 v[178:181], v[32:33], off
	global_load_dwordx4 v[182:185], v[32:33], off offset:16
	s_or_b64 exec, exec, s[16:17]

; #define POOL_LD(tt, dst) do { const int _t = (tt); if (_t >= 0) dst = v8_ldbf(XN + (seq0 + _t) * D + c0); else if (s) dst = v8_ldf(sp + ((size_t)b * 15 + 15 + _t) * D + c0); else dst = v8zero(); } while (0)
; DI void pool_diff(const Params& p, int pool_j, int gtid, int NT) {
;     ...
;         for (int j = win - 1; j >= 1; --j) { V8 v; POOL_LD(t0 - j, v); sum.a += v.a; sum.b += v.b; }
.Lpw_s14:
	s_mov_b64 exec, s[26:27]
	v_add_u32_e32 v64, 1, v64
	v_lshl_add_u64 v[32:33], v[32:33], 0, s[96:97]
	s_waitcnt vmcnt(0)
	v_cmp_lt_i32_e32 vcc, 9, v36
	s_and_saveexec_b64 s[26:27], vcc
	s_cbranch_execz .Lpw_t8
	v_add_u32_e32 v60, 0, v61
	v_cmp_le_i32_e32 vcc, 0, v60
	s_and_saveexec_b64 s[18:19], vcc
	v_lshlrev_b32_e32 v130, 16, v98
	v_and_b32_e32 v131, 0xffff0000, v98
	v_lshlrev_b32_e32 v132, 16, v99
	v_and_b32_e32 v133, 0xffff0000, v99
	v_lshlrev_b32_e32 v134, 16, v100
	v_and_b32_e32 v135, 0xffff0000, v100
	v_lshlrev_b32_e32 v136, 16, v101
	v_and_b32_e32 v137, 0xffff0000, v101
	s_or_b64 exec, exec, s[18:19]
	v_pk_add_f32 v[18:19], v[18:19], v[130:131]
	v_pk_add_f32 v[20:21], v[20:21], v[132:133]
	v_pk_add_f32 v[16:17], v[16:17], v[134:135]
	v_pk_add_f32 v[22:23], v[22:23], v[136:137]
.Lpw_t8:
	s_mov_b64 exec, s[26:27]
	v_cmp_lt_i32_e32 vcc, 10, v36
	s_and_saveexec_b64 s[26:27], vcc
	s_cbranch_execz .Lpw_t9
	v_add_u32_e32 v60, 1, v61
	v_cmp_le_i32_e32 vcc, 0, v60
	s_and_saveexec_b64 s[18:19], vcc
	v_lshlrev_b32_e32 v138, 16, v102
	v_and_b32_e32 v139, 0xffff0000, v102
	v_lshlrev_b32_e32 v140, 16, v103
	v_and_b32_e32 v141, 0xffff0000, v103
	v_lshlrev_b32_e32 v142, 16, v104
	v_and_b32_e32 v143, 0xffff0000, v104
	v_lshlrev_b32_e32 v144, 16, v105
	v_and_b32_e32 v145, 0xffff0000, v105
	s_or_b64 exec, exec, s[18:19]
	v_pk_add_f32 v[18:19], v[18:19], v[138:139]
	v_pk_add_f32 v[20:21], v[20:21], v[140:141]
	v_pk_add_f32 v[16:17], v[16:17], v[142:143]
	v_pk_add_f32 v[22:23], v[22:23], v[144:145]
.Lpw_t9:
	s_mov_b64 exec, s[26:27]
	v_cmp_lt_i32_e32 vcc, 11, v36
	s_and_saveexec_b64 s[26:27], vcc
	s_cbranch_execz .Lpw_t10
	v_add_u32_e32 v60, 2, v61
	v_cmp_le_i32_e32 vcc, 0, v60
	s_and_saveexec_b64 s[18:19], vcc
	v_lshlrev_b32_e32 v146, 16, v106
	v_and_b32_e32 v147, 0xffff0000, v106
	v_lshlrev_b32_e32 v148, 16, v107
	v_and_b32_e32 v149, 0xffff0000, v107
	v_lshlrev_b32_e32 v150, 16, v108
	v_and_b32_e32 v151, 0xffff0000, v108
	v_lshlrev_b32_e32 v152, 16, v109
	v_and_b32_e32 v153, 0xffff0000, v109
	s_or_b64 exec, exec, s[18:19]
	v_pk_add_f32 v[18:19], v[18:19], v[146:147]
	v_pk_add_f32 v[20:21], v[20:21], v[148:149]
	v_pk_add_f32 v[16:17], v[16:17], v[150:151]
	v_pk_add_f32 v[22:23], v[22:23], v[152:153]
.Lpw_t10:
	s_mov_b64 exec, s[26:27]
	v_cmp_lt_i32_e32 vcc, 12, v36
	s_and_saveexec_b64 s[26:27], vcc
	s_cbranch_execz .Lpw_t11
	v_add_u32_e32 v60, 3, v61
	v_cmp_le_i32_e32 vcc, 0, v60
	s_and_saveexec_b64 s[18:19], vcc
	v_lshlrev_b32_e32 v154, 16, v110
	v_and_b32_e32 v155, 0xffff0000, v110
	v_lshlrev_b32_e32 v156, 16, v111
	v_and_b32_e32 v157, 0xffff0000, v111
	v_lshlrev_b32_e32 v158, 16, v112
	v_and_b32_e32 v159, 0xffff0000, v112
	v_lshlrev_b32_e32 v160, 16, v113
	v_and_b32_e32 v161, 0xffff0000, v113
	s_or_b64 exec, exec, s[18:19]
	v_pk_add_f32 v[18:19], v[18:19], v[154:155]
	v_pk_add_f32 v[20:21], v[20:21], v[156:157]
	v_pk_add_f32 v[16:17], v[16:17], v[158:159]
	v_pk_add_f32 v[22:23], v[22:23], v[160:161]
.Lpw_t11:
	s_mov_b64 exec, s[26:27]
	v_cmp_lt_i32_e32 vcc, 13, v36
	s_and_saveexec_b64 s[26:27], vcc
	s_cbranch_execz .Lpw_t12
	v_add_u32_e32 v60, 4, v61
	v_cmp_le_i32_e32 vcc, 0, v60
	s_and_saveexec_b64 s[18:19], vcc
	v_lshlrev_b32_e32 v162, 16, v114
	v_and_b32_e32 v163, 0xffff0000, v114
	v_lshlrev_b32_e32 v164, 16, v115
	v_and_b32_e32 v165, 0xffff0000, v115
	v_lshlrev_b32_e32 v166, 16, v116
	v_and_b32_e32 v167, 0xffff0000, v116
	v_lshlrev_b32_e32 v168, 16, v117
	v_and_b32_e32 v169, 0xffff0000, v117
	s_or_b64 exec, exec, s[18:19]
	v_pk_add_f32 v[18:19], v[18:19], v[162:163]
	v_pk_add_f32 v[20:21], v[20:21], v[164:165]
	v_pk_add_f32 v[16:17], v[16:17], v[166:167]
	v_pk_add_f32 v[22:23], v[22:23], v[168:169]
.Lpw_t12:
	s_mov_b64 exec, s[26:27]
	v_cmp_lt_i32_e32 vcc, 14, v36
	s_and_saveexec_b64 s[26:27], vcc
	s_cbranch_execz .Lpw_t13
	v_add_u32_e32 v60, 5, v61
	v_cmp_le_i32_e32 vcc, 0, v60
	s_and_saveexec_b64 s[18:19], vcc
	v_lshlrev_b32_e32 v170, 16, v118
	v_and_b32_e32 v171, 0xffff0000, v118
	v_lshlrev_b32_e32 v172, 16, v119
	v_and_b32_e32 v173, 0xffff0000, v119
	v_lshlrev_b32_e32 v174, 16, v120
	v_and_b32_e32 v175, 0xffff0000, v120
	v_lshlrev_b32_e32 v176, 16, v121
	v_and_b32_e32 v177, 0xffff0000, v121
	s_or_b64 exec, exec, s[18:19]
	v_pk_add_f32 v[18:19], v[18:19], v[170:171]
	v_pk_add_f32 v[20:21], v[20:21], v[172:173]
	v_pk_add_f32 v[16:17], v[16:17], v[174:175]
	v_pk_add_f32 v[22:23], v[22:23], v[176:177]
.Lpw_t13:
	s_mov_b64 exec, s[26:27]
	v_cmp_lt_i32_e32 vcc, 15, v36
	s_and_saveexec_b64 s[26:27], vcc
	s_cbranch_execz .Lpw_t14
	v_add_u32_e32 v60, 6, v61
	v_cmp_le_i32_e32 vcc, 0, v60
	s_and_saveexec_b64 s[18:19], vcc
	v_lshlrev_b32_e32 v178, 16, v122
	v_and_b32_e32 v179, 0xffff0000, v122
	v_lshlrev_b32_e32 v180, 16, v123
	v_and_b32_e32 v181, 0xffff0000, v123
	v_lshlrev_b32_e32 v182, 16, v124
	v_and_b32_e32 v183, 0xffff0000, v124
	v_lshlrev_b32_e32 v184, 16, v125
	v_and_b32_e32 v185, 0xffff0000, v125
	s_or_b64 exec, exec, s[18:19]
	v_pk_add_f32 v[18:19], v[18:19], v[178:179]
	v_pk_add_f32 v[20:21], v[20:21], v[180:181]
	v_pk_add_f32 v[16:17], v[16:17], v[182:183]
	v_pk_add_f32 v[22:23], v[22:23], v[184:185]

; #define POOL_LD(tt, dst) do { const int _t = (tt); if (_t >= 0) dst = v8_ldbf(XN + (seq0 + _t) * D + c0); else if (s) dst = v8_ldf(sp + ((size_t)b * 15 + 15 + _t) * D + c0); else dst = v8zero(); } while (0)
; DI void pool_diff(const Params& p, int pool_j, int gtid, int NT) {
;     ...
;         for (int j = win - 1; j >= 1; --j) { V8 v; POOL_LD(t0 - j, v); sum.a += v.a; sum.b += v.b; }
.Lpw_end1:
	s_mov_b64 s[16:17], exec

; DI u32x4 v8_pack(const V8& v) { u32x4 w; w.x = pk2(v.a.x, v.a.y); w.y = pk2(v.a.z, v.a.w); w.z = pk2(v.b.x, v.b.y); w.w = pk2(v.b.z, v.b.w); return w; }
; #define POOL_LD(tt, dst) do { const int _t = (tt); if (_t >= 0) dst = v8_ldbf(XN + (seq0 + _t) * D + c0); else if (s) dst = v8_ldf(sp + ((size_t)b * 15 + 15 + _t) * D + c0); else dst = v8zero(); } while (0)
; DI void pool_diff(const Params& p, int pool_j, int gtid, int NT) {
;     ...
;         for (int r = 0; r < 32; ++r) {
;             const int t = t0 + r; V8 cur; POOL_LD(t, cur); sum.a += cur.a; sum.b += cur.b;
;             const float cnt = s ? (float)win : (float)((t + 1) < win ? (t + 1) : win); const float inv = 1.f / cnt;
;             V8 d; d.a = sum.a * inv - cur.a; d.b = sum.b * inv - cur.b;
;             *(u32x4*)(Dd + (size_t)(row0 + r) * D + c0) = v8_pack(d);
;             V8 old; POOL_LD(t - win + 1, old); sum.a -= old.a; sum.b -= old.b;
;         }
.LBB0_1411:
	v_add_co_u32_e32 v54, vcc, 0xfbf00000, v24
	s_nop 1
	v_addc_co_u32_e32 v55, vcc, -1, v25, vcc
	s_mov_b64 s[16:17], 0x800
	global_load_dwordx4 v[66:69], v[54:55], off
	v_lshl_add_u64 v[54:55], v[54:55], 0, s[16:17]
	global_load_dwordx4 v[70:73], v[54:55], off
	v_lshl_add_u64 v[54:55], v[54:55], 0, s[16:17]
	global_load_dwordx4 v[74:77], v[54:55], off
	v_lshl_add_u64 v[54:55], v[54:55], 0, s[16:17]
	global_load_dwordx4 v[78:81], v[54:55], off
	v_lshl_add_u64 v[54:55], v[54:55], 0, s[16:17]
	global_load_dwordx4 v[82:85], v[54:55], off
	v_lshl_add_u64 v[54:55], v[54:55], 0, s[16:17]
	global_load_dwordx4 v[86:89], v[54:55], off
	v_lshl_add_u64 v[54:55], v[54:55], 0, s[16:17]
	global_load_dwordx4 v[90:93], v[54:55], off
	v_lshl_add_u64 v[54:55], v[54:55], 0, s[16:17]
	global_load_dwordx4 v[94:97], v[54:55], off
	v_mov_b32_e32 v58, v26
	v_mov_b32_e32 v59, v27
	s_add_i32 s26, s8, 0
	v_add_u32_e32 v60, s26, v14
	v_cmp_gt_i32_e32 vcc, -1, v60
	s_and_saveexec_b64 s[16:17], vcc
	s_xor_b64 s[16:17], exec, s[16:17]
	s_cbranch_execz .Lpdk_a0
	v_mov_b32_e32 v130, 0
	v_mov_b32_e32 v131, 0
	v_mov_b32_e32 v132, 0
	v_mov_b32_e32 v133, 0
	v_mov_b32_e32 v134, 0
	v_mov_b32_e32 v135, 0
	v_mov_b32_e32 v136, 0
	v_mov_b32_e32 v137, 0
	s_and_saveexec_b64 s[18:19], s[0:1]
	global_load_dwordx4 v[134:137], v[58:59], off offset:16
	global_load_dwordx4 v[130:133], v[58:59], off
	s_or_b64 exec, exec, s[18:19]
.Lpdk_a0:
	s_andn2_saveexec_b64 s[16:17], s[16:17]
	v_add_u32_e32 v64, 1, v60
	v_lshl_add_u64 v[56:57], v[64:65], 0, v[10:11]
	v_lshlrev_b64 v[56:57], 11, v[56:57]
	v_lshl_add_u64 v[56:57], v[12:13], 0, v[56:57]
	global_load_dwordx4 v[98:101], v[56:57], off
	s_or_b64 exec, exec, s[16:17]
	v_lshl_add_u64 v[58:59], v[58:59], 0, s[96:97]
	s_add_i32 s26, s8, 1
	v_add_u32_e32 v60, s26, v14
	v_cmp_gt_i32_e32 vcc, -1, v60
	s_and_saveexec_b64 s[16:17], vcc
	s_xor_b64 s[16:17], exec, s[16:17]
	s_cbranch_execz .Lpdk_a1
	v_mov_b32_e32 v138, 0
	v_mov_b32_e32 v139, 0
	v_mov_b32_e32 v140, 0
	v_mov_b32_e32 v141, 0
	v_mov_b32_e32 v142, 0
	v_mov_b32_e32 v143, 0
	v_mov_b32_e32 v144, 0
	v_mov_b32_e32 v145, 0
	s_and_saveexec_b64 s[18:19], s[0:1]
	global_load_dwordx4 v[142:145], v[58:59], off offset:16
	global_load_dwordx4 v[138:141], v[58:59], off
	s_or_b64 exec, exec, s[18:19]
.Lpdk_a1:
	s_andn2_saveexec_b64 s[16:17], s[16:17]
	v_add_u32_e32 v64, 1, v60
	v_lshl_add_u64 v[56:57], v[64:65], 0, v[10:11]
	v_lshlrev_b64 v[56:57], 11, v[56:57]
	v_lshl_add_u64 v[56:57], v[12:13], 0, v[56:57]
	global_load_dwordx4 v[102:105], v[56:57], off
	s_or_b64 exec, exec, s[16:17]
	v_lshl_add_u64 v[58:59], v[58:59], 0, s[96:97]
	s_add_i32 s26, s8, 2
	v_add_u32_e32 v60, s26, v14
	v_cmp_gt_i32_e32 vcc, -1, v60
	s_and_saveexec_b64 s[16:17], vcc
	s_xor_b64 s[16:17], exec, s[16:17]
	s_cbranch_execz .Lpdk_a2
	v_mov_b32_e32 v146, 0
	v_mov_b32_e32 v147, 0
	v_mov_b32_e32 v148, 0
	v_mov_b32_e32 v149, 0
	v_mov_b32_e32 v150, 0
	v_mov_b32_e32 v151, 0
	v_mov_b32_e32 v152, 0
	v_mov_b32_e32 v153, 0
	s_and_saveexec_b64 s[18:19], s[0:1]
	global_load_dwordx4 v[150:153], v[58:59], off offset:16
	global_load_dwordx4 v[146:149], v[58:59], off
	s_or_b64 exec, exec, s[18:19]
.Lpdk_a2:
	s_andn2_saveexec_b64 s[16:17], s[16:17]
	v_add_u32_e32 v64, 1, v60
	v_lshl_add_u64 v[56:57], v[64:65], 0, v[10:11]
	v_lshlrev_b64 v[56:57], 11, v[56:57]
	v_lshl_add_u64 v[56:57], v[12:13], 0, v[56:57]
	global_load_dwordx4 v[106:109], v[56:57], off
	s_or_b64 exec, exec, s[16:17]
	v_lshl_add_u64 v[58:59], v[58:59], 0, s[96:97]
	s_add_i32 s26, s8, 3
	v_add_u32_e32 v60, s26, v14
	v_cmp_gt_i32_e32 vcc, -1, v60
	s_and_saveexec_b64 s[16:17], vcc
	s_xor_b64 s[16:17], exec, s[16:17]
	s_cbranch_execz .Lpdk_a3
	v_mov_b32_e32 v154, 0
	v_mov_b32_e32 v155, 0
	v_mov_b32_e32 v156, 0
	v_mov_b32_e32 v157, 0
	v_mov_b32_e32 v158, 0
	v_mov_b32_e32 v159, 0
	v_mov_b32_e32 v160, 0
	v_mov_b32_e32 v161, 0
	s_and_saveexec_b64 s[18:19], s[0:1]
	global_load_dwordx4 v[158:161], v[58:59], off offset:16
	global_load_dwordx4 v[154:157], v[58:59], off
	s_or_b64 exec, exec, s[18:19]
.Lpdk_a3:
	s_andn2_saveexec_b64 s[16:17], s[16:17]
	v_add_u32_e32 v64, 1, v60
	v_lshl_add_u64 v[56:57], v[64:65], 0, v[10:11]
	v_lshlrev_b64 v[56:57], 11, v[56:57]
	v_lshl_add_u64 v[56:57], v[12:13], 0, v[56:57]
	global_load_dwordx4 v[110:113], v[56:57], off
	s_or_b64 exec, exec, s[16:17]
	v_lshl_add_u64 v[58:59], v[58:59], 0, s[96:97]
	s_add_i32 s26, s8, 4
	v_add_u32_e32 v60, s26, v14
	v_cmp_gt_i32_e32 vcc, -1, v60
	s_and_saveexec_b64 s[16:17], vcc
	s_xor_b64 s[16:17], exec, s[16:17]
	s_cbranch_execz .Lpdk_a4
	v_mov_b32_e32 v162, 0
	v_mov_b32_e32 v163, 0
	v_mov_b32_e32 v164, 0
	v_mov_b32_e32 v165, 0
	v_mov_b32_e32 v166, 0
	v_mov_b32_e32 v167, 0
	v_mov_b32_e32 v168, 0
	v_mov_b32_e32 v169, 0
	s_and_saveexec_b64 s[18:19], s[0:1]
	global_load_dwordx4 v[166:169], v[58:59], off offset:16
	global_load_dwordx4 v[162:165], v[58:59], off
	s_or_b64 exec, exec, s[18:19]
.Lpdk_a4:
	s_andn2_saveexec_b64 s[16:17], s[16:17]
	v_add_u32_e32 v64, 1, v60
	v_lshl_add_u64 v[56:57], v[64:65], 0, v[10:11]
	v_lshlrev_b64 v[56:57], 11, v[56:57]
	v_lshl_add_u64 v[56:57], v[12:13], 0, v[56:57]
	global_load_dwordx4 v[114:117], v[56:57], off
	s_or_b64 exec, exec, s[16:17]
	v_lshl_add_u64 v[58:59], v[58:59], 0, s[96:97]
	s_add_i32 s26, s8, 5
	v_add_u32_e32 v60, s26, v14
	v_cmp_gt_i32_e32 vcc, -1, v60
	s_and_saveexec_b64 s[16:17], vcc
	s_xor_b64 s[16:17], exec, s[16:17]
	s_cbranch_execz .Lpdk_a5
	v_mov_b32_e32 v170, 0
	v_mov_b32_e32 v171, 0
	v_mov_b32_e32 v172, 0
	v_mov_b32_e32 v173, 0
	v_mov_b32_e32 v174, 0
	v_mov_b32_e32 v175, 0
	v_mov_b32_e32 v176, 0
	v_mov_b32_e32 v177, 0
	s_and_saveexec_b64 s[18:19], s[0:1]
	global_load_dwordx4 v[174:177], v[58:59], off offset:16
	global_load_dwordx4 v[170:173], v[58:59], off
	s_or_b64 exec, exec, s[18:19]
; DI u32x4 v8_pack(const V8& v) { u32x4 w; w.x = pk2(v.a.x, v.a.y); w.y = pk2(v.a.z, v.a.w); w.z = pk2(v.b.x, v.b.y); w.w = pk2(v.b.z, v.b.w); return w; }
; #define POOL_LD(tt, dst) do { const int _t = (tt); if (_t >= 0) dst = v8_ldbf(XN + (seq0 + _t) * D + c0); else if (s) dst = v8_ldf(sp + ((size_t)b * 15 + 15 + _t) * D + c0); else dst = v8zero(); } while (0)
; DI void pool_diff(const Params& p, int pool_j, int gtid, int NT) {
;     ...
;         for (int r = 0; r < 32; ++r) {
;             const int t = t0 + r; V8 cur; POOL_LD(t, cur); sum.a += cur.a; sum.b += cur.b;
;             const float cnt = s ? (float)win : (float)((t + 1) < win ? (t + 1) : win); const float inv = 1.f / cnt;
;             V8 d; d.a = sum.a * inv - cur.a; d.b = sum.b * inv - cur.b;
;             *(u32x4*)(Dd + (size_t)(row0 + r) * D + c0) = v8_pack(d);
;             V8 old; POOL_LD(t - win + 1, old); sum.a -= old.a; sum.b -= old.b;
;         }
.Lpdk_a5:
	s_andn2_saveexec_b64 s[16:17], s[16:17]
	v_add_u32_e32 v64, 1, v60
	v_lshl_add_u64 v[56:57], v[64:65], 0, v[10:11]
	v_lshlrev_b64 v[56:57], 11, v[56:57]
	v_lshl_add_u64 v[56:57], v[12:13], 0, v[56:57]
	global_load_dwordx4 v[118:121], v[56:57], off
	s_or_b64 exec, exec, s[16:17]
	v_lshl_add_u64 v[58:59], v[58:59], 0, s[96:97]
	s_add_i32 s26, s8, 6
	v_add_u32_e32 v60, s26, v14
	v_cmp_gt_i32_e32 vcc, -1, v60
	s_and_saveexec_b64 s[16:17], vcc
	s_xor_b64 s[16:17], exec, s[16:17]
	s_cbranch_execz .Lpdk_a6
	v_mov_b32_e32 v178, 0
	v_mov_b32_e32 v179, 0
	v_mov_b32_e32 v180, 0
	v_mov_b32_e32 v181, 0
	v_mov_b32_e32 v182, 0
	v_mov_b32_e32 v183, 0
	v_mov_b32_e32 v184, 0
	v_mov_b32_e32 v185, 0
	s_and_saveexec_b64 s[18:19], s[0:1]
	global_load_dwordx4 v[182:185], v[58:59], off offset:16
	global_load_dwordx4 v[178:181], v[58:59], off
	s_or_b64 exec, exec, s[18:19]
.Lpdk_a6:
	s_andn2_saveexec_b64 s[16:17], s[16:17]
	v_add_u32_e32 v64, 1, v60
	v_lshl_add_u64 v[56:57], v[64:65], 0, v[10:11]
	v_lshlrev_b64 v[56:57], 11, v[56:57]
	v_lshl_add_u64 v[56:57], v[12:13], 0, v[56:57]
	global_load_dwordx4 v[122:125], v[56:57], off
	s_or_b64 exec, exec, s[16:17]
	v_lshl_add_u64 v[58:59], v[58:59], 0, s[96:97]
	s_add_i32 s26, s8, 7
	v_add_u32_e32 v60, s26, v14
	v_cmp_gt_i32_e32 vcc, -1, v60
	s_and_saveexec_b64 s[16:17], vcc
	s_xor_b64 s[16:17], exec, s[16:17]
	s_cbranch_execz .Lpdk_a7
	v_mov_b32_e32 v186, 0
	v_mov_b32_e32 v187, 0
	v_mov_b32_e32 v188, 0
	v_mov_b32_e32 v189, 0
	v_mov_b32_e32 v190, 0
	v_mov_b32_e32 v191, 0
	v_mov_b32_e32 v192, 0
	v_mov_b32_e32 v193, 0
	s_and_saveexec_b64 s[18:19], s[0:1]
	global_load_dwordx4 v[190:193], v[58:59], off offset:16
	global_load_dwordx4 v[186:189], v[58:59], off
	s_or_b64 exec, exec, s[18:19]
.Lpdk_a7:
	s_andn2_saveexec_b64 s[16:17], s[16:17]
	v_add_u32_e32 v64, 1, v60
	v_lshl_add_u64 v[56:57], v[64:65], 0, v[10:11]
	v_lshlrev_b64 v[56:57], 11, v[56:57]
	v_lshl_add_u64 v[56:57], v[12:13], 0, v[56:57]
	global_load_dwordx4 v[126:129], v[56:57], off
	s_or_b64 exec, exec, s[16:17]
	s_waitcnt vmcnt(0) lgkmcnt(0)
	s_add_i32 s26, s8, 0
	v_add3_u32 v4, v8, s26, 1
	v_min_i32_e32 v4, v4, v36
	v_cndmask_b32_e64 v4, v36, v4, s[36:37]
	v_cvt_f32_u32_e32 v4, v4
	v_div_scale_f32 v5, s[16:17], v4, v4, 1.0
	v_rcp_f32_e32 v6, v5
	v_div_scale_f32 v7, vcc, 1.0, v4, 1.0
	v_fma_f32 v15, -v5, v6, 1.0
	v_fmac_f32_e32 v6, v15, v6
	v_mul_f32_e32 v15, v7, v6
	v_fma_f32 v28, -v5, v15, v7
	v_fmac_f32_e32 v15, v28, v6
	v_fma_f32 v5, -v5, v15, v7
	v_div_fmas_f32 v5, v5, v6, v15
	v_div_fixup_f32 v4, v5, v4, 1.0
	v_lshlrev_b32_e32 v6, 16, v66
	v_and_b32_e32 v7, 0xffff0000, v66
	v_lshlrev_b32_e32 v0, 16, v67
	v_and_b32_e32 v1, 0xffff0000, v67
	v_lshlrev_b32_e32 v28, 16, v68
	v_and_b32_e32 v29, 0xffff0000, v68
	v_lshlrev_b32_e32 v2, 16, v69
	v_and_b32_e32 v3, 0xffff0000, v69
	v_pk_add_f32 v[20:21], v[20:21], v[0:1]
	v_pk_add_f32 v[18:19], v[18:19], v[6:7]
	v_pk_add_f32 v[22:23], v[22:23], v[2:3]
	v_pk_add_f32 v[16:17], v[16:17], v[28:29]
	v_xor_b32_e32 v1, 0x80000000, v1
	v_xor_b32_e32 v0, 0x80000000, v0
	v_xor_b32_e32 v7, 0x80000000, v7
	v_xor_b32_e32 v6, 0x80000000, v6
	v_xor_b32_e32 v3, 0x80000000, v3
	v_xor_b32_e32 v2, 0x80000000, v2
	v_xor_b32_e32 v29, 0x80000000, v29
	v_xor_b32_e32 v28, 0x80000000, v28
	v_pk_fma_f32 v[30:31], v[4:5], v[20:21], v[0:1] op_sel_hi:[0,1,1]
	v_pk_fma_f32 v[0:1], v[4:5], v[18:19], v[6:7] op_sel_hi:[0,1,1]
	v_pk_fma_f32 v[6:7], v[4:5], v[22:23], v[2:3] op_sel_hi:[0,1,1]
	v_pk_fma_f32 v[2:3], v[4:5], v[16:17], v[28:29] op_sel_hi:[0,1,1]
	v_cvt_pk_bf16_f32 v0, v0, v1
	v_cvt_pk_bf16_f32 v1, v30, v31
	v_cvt_pk_bf16_f32 v2, v2, v3
	v_cvt_pk_bf16_f32 v3, v6, v7
	global_store_dwordx4 v[24:25], v[0:3], off
	v_add_u32_e32 v60, s26, v14
	v_cmp_le_i32_e32 vcc, -1, v60
	s_and_saveexec_b64 s[16:17], vcc
	v_lshlrev_b32_e32 v130, 16, v98
	v_and_b32_e32 v131, 0xffff0000, v98
	v_lshlrev_b32_e32 v132, 16, v99
	v_and_b32_e32 v133, 0xffff0000, v99
	v_lshlrev_b32_e32 v134, 16, v100
	v_and_b32_e32 v135, 0xffff0000, v100
	v_lshlrev_b32_e32 v136, 16, v101
	v_and_b32_e32 v137, 0xffff0000, v101
	s_or_b64 exec, exec, s[16:17]
	v_sub_f32_e32 v21, v21, v133
	v_sub_f32_e32 v20, v20, v132
	v_sub_f32_e32 v19, v19, v131
	v_sub_f32_e32 v18, v18, v130
	v_sub_f32_e32 v23, v23, v137
	v_sub_f32_e32 v22, v22, v136
	v_sub_f32_e32 v17, v17, v135
	v_sub_f32_e32 v16, v16, v134
	s_mov_b64 s[16:17], 0x800
	v_lshl_add_u64 v[24:25], v[24:25], 0, s[16:17]
	v_lshl_add_u64 v[26:27], v[26:27], 0, s[96:97]
	s_add_i32 s26, s8, 1
	v_add3_u32 v4, v8, s26, 1
	v_min_i32_e32 v4, v4, v36
	v_cndmask_b32_e64 v4, v36, v4, s[36:37]
	v_cvt_f32_u32_e32 v4, v4
	v_div_scale_f32 v5, s[16:17], v4, v4, 1.0
	v_rcp_f32_e32 v6, v5
	v_div_scale_f32 v7, vcc, 1.0, v4, 1.0
	v_fma_f32 v15, -v5, v6, 1.0
	v_fmac_f32_e32 v6, v15, v6
	v_mul_f32_e32 v15, v7, v6
	v_fma_f32 v28, -v5, v15, v7
	v_fmac_f32_e32 v15, v28, v6
	v_fma_f32 v5, -v5, v15, v7
	v_div_fmas_f32 v5, v5, v6, v15
	v_div_fixup_f32 v4, v5, v4, 1.0
	v_lshlrev_b32_e32 v6, 16, v70
	v_and_b32_e32 v7, 0xffff0000, v70
	v_lshlrev_b32_e32 v0, 16, v71
	v_and_b32_e32 v1, 0xffff0000, v71
	v_lshlrev_b32_e32 v28, 16, v72
	v_and_b32_e32 v29, 0xffff0000, v72
	v_lshlrev_b32_e32 v2, 16, v73
	v_and_b32_e32 v3, 0xffff0000, v73
	v_pk_add_f32 v[20:21], v[20:21], v[0:1]
	v_pk_add_f32 v[18:19], v[18:19], v[6:7]
	v_pk_add_f32 v[22:23], v[22:23], v[2:3]
	v_pk_add_f32 v[16:17], v[16:17], v[28:29]
	v_xor_b32_e32 v1, 0x80000000, v1
	v_xor_b32_e32 v0, 0x80000000, v0
	v_xor_b32_e32 v7, 0x80000000, v7
	v_xor_b32_e32 v6, 0x80000000, v6
	v_xor_b32_e32 v3, 0x80000000, v3
	v_xor_b32_e32 v2, 0x80000000, v2
	v_xor_b32_e32 v29, 0x80000000, v29
	v_xor_b32_e32 v28, 0x80000000, v28
; DI u32x4 v8_pack(const V8& v) { u32x4 w; w.x = pk2(v.a.x, v.a.y); w.y = pk2(v.a.z, v.a.w); w.z = pk2(v.b.x, v.b.y); w.w = pk2(v.b.z, v.b.w); return w; }
; #define POOL_LD(tt, dst) do { const int _t = (tt); if (_t >= 0) dst = v8_ldbf(XN + (seq0 + _t) * D + c0); else if (s) dst = v8_ldf(sp + ((size_t)b * 15 + 15 + _t) * D + c0); else dst = v8zero(); } while (0)
; DI void pool_diff(const Params& p, int pool_j, int gtid, int NT) {
;     ...
;         for (int r = 0; r < 32; ++r) {
;             const int t = t0 + r; V8 cur; POOL_LD(t, cur); sum.a += cur.a; sum.b += cur.b;
;             const float cnt = s ? (float)win : (float)((t + 1) < win ? (t + 1) : win); const float inv = 1.f / cnt;
;             V8 d; d.a = sum.a * inv - cur.a; d.b = sum.b * inv - cur.b;
;             *(u32x4*)(Dd + (size_t)(row0 + r) * D + c0) = v8_pack(d);
;             V8 old; POOL_LD(t - win + 1, old); sum.a -= old.a; sum.b -= old.b;
;         }
	v_pk_fma_f32 v[30:31], v[4:5], v[20:21], v[0:1] op_sel_hi:[0,1,1]
	v_pk_fma_f32 v[0:1], v[4:5], v[18:19], v[6:7] op_sel_hi:[0,1,1]
	v_pk_fma_f32 v[6:7], v[4:5], v[22:23], v[2:3] op_sel_hi:[0,1,1]
	v_pk_fma_f32 v[2:3], v[4:5], v[16:17], v[28:29] op_sel_hi:[0,1,1]
	v_cvt_pk_bf16_f32 v0, v0, v1
	v_cvt_pk_bf16_f32 v1, v30, v31
	v_cvt_pk_bf16_f32 v2, v2, v3
	v_cvt_pk_bf16_f32 v3, v6, v7
	global_store_dwordx4 v[24:25], v[0:3], off
	v_add_u32_e32 v60, s26, v14
	v_cmp_le_i32_e32 vcc, -1, v60
	s_and_saveexec_b64 s[16:17], vcc
	v_lshlrev_b32_e32 v138, 16, v102
	v_and_b32_e32 v139, 0xffff0000, v102
	v_lshlrev_b32_e32 v140, 16, v103
	v_and_b32_e32 v141, 0xffff0000, v103
	v_lshlrev_b32_e32 v142, 16, v104
	v_and_b32_e32 v143, 0xffff0000, v104
	v_lshlrev_b32_e32 v144, 16, v105
	v_and_b32_e32 v145, 0xffff0000, v105
	s_or_b64 exec, exec, s[16:17]
	v_sub_f32_e32 v21, v21, v141
	v_sub_f32_e32 v20, v20, v140
	v_sub_f32_e32 v19, v19, v139
	v_sub_f32_e32 v18, v18, v138
	v_sub_f32_e32 v23, v23, v145
	v_sub_f32_e32 v22, v22, v144
	v_sub_f32_e32 v17, v17, v143
	v_sub_f32_e32 v16, v16, v142
	s_mov_b64 s[16:17], 0x800
	v_lshl_add_u64 v[24:25], v[24:25], 0, s[16:17]
	v_lshl_add_u64 v[26:27], v[26:27], 0, s[96:97]
	s_add_i32 s26, s8, 2
	v_add3_u32 v4, v8, s26, 1
	v_min_i32_e32 v4, v4, v36
	v_cndmask_b32_e64 v4, v36, v4, s[36:37]
	v_cvt_f32_u32_e32 v4, v4
	v_div_scale_f32 v5, s[16:17], v4, v4, 1.0
	v_rcp_f32_e32 v6, v5
	v_div_scale_f32 v7, vcc, 1.0, v4, 1.0
	v_fma_f32 v15, -v5, v6, 1.0
	v_fmac_f32_e32 v6, v15, v6
	v_mul_f32_e32 v15, v7, v6
	v_fma_f32 v28, -v5, v15, v7
	v_fmac_f32_e32 v15, v28, v6
	v_fma_f32 v5, -v5, v15, v7
	v_div_fmas_f32 v5, v5, v6, v15
	v_div_fixup_f32 v4, v5, v4, 1.0
	v_lshlrev_b32_e32 v6, 16, v74
	v_and_b32_e32 v7, 0xffff0000, v74
	v_lshlrev_b32_e32 v0, 16, v75
	v_and_b32_e32 v1, 0xffff0000, v75
	v_lshlrev_b32_e32 v28, 16, v76
	v_and_b32_e32 v29, 0xffff0000, v76
	v_lshlrev_b32_e32 v2, 16, v77
	v_and_b32_e32 v3, 0xffff0000, v77
	v_pk_add_f32 v[20:21], v[20:21], v[0:1]
	v_pk_add_f32 v[18:19], v[18:19], v[6:7]
	v_pk_add_f32 v[22:23], v[22:23], v[2:3]
	v_pk_add_f32 v[16:17], v[16:17], v[28:29]
	v_xor_b32_e32 v1, 0x80000000, v1
	v_xor_b32_e32 v0, 0x80000000, v0
	v_xor_b32_e32 v7, 0x80000000, v7
	v_xor_b32_e32 v6, 0x80000000, v6
	v_xor_b32_e32 v3, 0x80000000, v3
	v_xor_b32_e32 v2, 0x80000000, v2
	v_xor_b32_e32 v29, 0x80000000, v29
	v_xor_b32_e32 v28, 0x80000000, v28
	v_pk_fma_f32 v[30:31], v[4:5], v[20:21], v[0:1] op_sel_hi:[0,1,1]
	v_pk_fma_f32 v[0:1], v[4:5], v[18:19], v[6:7] op_sel_hi:[0,1,1]
	v_pk_fma_f32 v[6:7], v[4:5], v[22:23], v[2:3] op_sel_hi:[0,1,1]
	v_pk_fma_f32 v[2:3], v[4:5], v[16:17], v[28:29] op_sel_hi:[0,1,1]
	v_cvt_pk_bf16_f32 v0, v0, v1
	v_cvt_pk_bf16_f32 v1, v30, v31
	v_cvt_pk_bf16_f32 v2, v2, v3
	v_cvt_pk_bf16_f32 v3, v6, v7
	global_store_dwordx4 v[24:25], v[0:3], off
	v_add_u32_e32 v60, s26, v14
	v_cmp_le_i32_e32 vcc, -1, v60
	s_and_saveexec_b64 s[16:17], vcc
	v_lshlrev_b32_e32 v146, 16, v106
	v_and_b32_e32 v147, 0xffff0000, v106
	v_lshlrev_b32_e32 v148, 16, v107
	v_and_b32_e32 v149, 0xffff0000, v107
	v_lshlrev_b32_e32 v150, 16, v108
	v_and_b32_e32 v151, 0xffff0000, v108
	v_lshlrev_b32_e32 v152, 16, v109
	v_and_b32_e32 v153, 0xffff0000, v109
	s_or_b64 exec, exec, s[16:17]
	v_sub_f32_e32 v21, v21, v149
	v_sub_f32_e32 v20, v20, v148
	v_sub_f32_e32 v19, v19, v147
	v_sub_f32_e32 v18, v18, v146
	v_sub_f32_e32 v23, v23, v153
	v_sub_f32_e32 v22, v22, v152
	v_sub_f32_e32 v17, v17, v151
	v_sub_f32_e32 v16, v16, v150
	s_mov_b64 s[16:17], 0x800
	v_lshl_add_u64 v[24:25], v[24:25], 0, s[16:17]
	v_lshl_add_u64 v[26:27], v[26:27], 0, s[96:97]
	s_add_i32 s26, s8, 3
	v_add3_u32 v4, v8, s26, 1
	v_min_i32_e32 v4, v4, v36
	v_cndmask_b32_e64 v4, v36, v4, s[36:37]
	v_cvt_f32_u32_e32 v4, v4
	v_div_scale_f32 v5, s[16:17], v4, v4, 1.0
	v_rcp_f32_e32 v6, v5
	v_div_scale_f32 v7, vcc, 1.0, v4, 1.0
	v_fma_f32 v15, -v5, v6, 1.0
	v_fmac_f32_e32 v6, v15, v6
	v_mul_f32_e32 v15, v7, v6
	v_fma_f32 v28, -v5, v15, v7
	v_fmac_f32_e32 v15, v28, v6
	v_fma_f32 v5, -v5, v15, v7
	v_div_fmas_f32 v5, v5, v6, v15
	v_div_fixup_f32 v4, v5, v4, 1.0
	v_lshlrev_b32_e32 v6, 16, v78
	v_and_b32_e32 v7, 0xffff0000, v78
	v_lshlrev_b32_e32 v0, 16, v79
	v_and_b32_e32 v1, 0xffff0000, v79
	v_lshlrev_b32_e32 v28, 16, v80
	v_and_b32_e32 v29, 0xffff0000, v80
	v_lshlrev_b32_e32 v2, 16, v81
	v_and_b32_e32 v3, 0xffff0000, v81
	v_pk_add_f32 v[20:21], v[20:21], v[0:1]
	v_pk_add_f32 v[18:19], v[18:19], v[6:7]
	v_pk_add_f32 v[22:23], v[22:23], v[2:3]
	v_pk_add_f32 v[16:17], v[16:17], v[28:29]
	v_xor_b32_e32 v1, 0x80000000, v1
	v_xor_b32_e32 v0, 0x80000000, v0
	v_xor_b32_e32 v7, 0x80000000, v7
	v_xor_b32_e32 v6, 0x80000000, v6
	v_xor_b32_e32 v3, 0x80000000, v3
	v_xor_b32_e32 v2, 0x80000000, v2
	v_xor_b32_e32 v29, 0x80000000, v29
	v_xor_b32_e32 v28, 0x80000000, v28
	v_pk_fma_f32 v[30:31], v[4:5], v[20:21], v[0:1] op_sel_hi:[0,1,1]
	v_pk_fma_f32 v[0:1], v[4:5], v[18:19], v[6:7] op_sel_hi:[0,1,1]
	v_pk_fma_f32 v[6:7], v[4:5], v[22:23], v[2:3] op_sel_hi:[0,1,1]
	v_pk_fma_f32 v[2:3], v[4:5], v[16:17], v[28:29] op_sel_hi:[0,1,1]
	v_cvt_pk_bf16_f32 v0, v0, v1
	v_cvt_pk_bf16_f32 v1, v30, v31
	v_cvt_pk_bf16_f32 v2, v2, v3
	v_cvt_pk_bf16_f32 v3, v6, v7
	global_store_dwordx4 v[24:25], v[0:3], off
	v_add_u32_e32 v60, s26, v14
	v_cmp_le_i32_e32 vcc, -1, v60
	s_and_saveexec_b64 s[16:17], vcc
	v_lshlrev_b32_e32 v154, 16, v110
	v_and_b32_e32 v155, 0xffff0000, v110
	v_lshlrev_b32_e32 v156, 16, v111
	v_and_b32_e32 v157, 0xffff0000, v111
	v_lshlrev_b32_e32 v158, 16, v112
	v_and_b32_e32 v159, 0xffff0000, v112
	v_lshlrev_b32_e32 v160, 16, v113
	v_and_b32_e32 v161, 0xffff0000, v113
	s_or_b64 exec, exec, s[16:17]
; DI u32x4 v8_pack(const V8& v) { u32x4 w; w.x = pk2(v.a.x, v.a.y); w.y = pk2(v.a.z, v.a.w); w.z = pk2(v.b.x, v.b.y); w.w = pk2(v.b.z, v.b.w); return w; }
; #define POOL_LD(tt, dst) do { const int _t = (tt); if (_t >= 0) dst = v8_ldbf(XN + (seq0 + _t) * D + c0); else if (s) dst = v8_ldf(sp + ((size_t)b * 15 + 15 + _t) * D + c0); else dst = v8zero(); } while (0)
; DI void pool_diff(const Params& p, int pool_j, int gtid, int NT) {
;     ...
;         for (int r = 0; r < 32; ++r) {
;             const int t = t0 + r; V8 cur; POOL_LD(t, cur); sum.a += cur.a; sum.b += cur.b;
;             const float cnt = s ? (float)win : (float)((t + 1) < win ? (t + 1) : win); const float inv = 1.f / cnt;
;             V8 d; d.a = sum.a * inv - cur.a; d.b = sum.b * inv - cur.b;
;             *(u32x4*)(Dd + (size_t)(row0 + r) * D + c0) = v8_pack(d);
;             V8 old; POOL_LD(t - win + 1, old); sum.a -= old.a; sum.b -= old.b;
;         }
	v_sub_f32_e32 v21, v21, v157
	v_sub_f32_e32 v20, v20, v156
	v_sub_f32_e32 v19, v19, v155
	v_sub_f32_e32 v18, v18, v154
	v_sub_f32_e32 v23, v23, v161
	v_sub_f32_e32 v22, v22, v160
	v_sub_f32_e32 v17, v17, v159
	v_sub_f32_e32 v16, v16, v158
	s_mov_b64 s[16:17], 0x800
	v_lshl_add_u64 v[24:25], v[24:25], 0, s[16:17]
	v_lshl_add_u64 v[26:27], v[26:27], 0, s[96:97]
	s_add_i32 s26, s8, 4
	v_add3_u32 v4, v8, s26, 1
	v_min_i32_e32 v4, v4, v36
	v_cndmask_b32_e64 v4, v36, v4, s[36:37]
	v_cvt_f32_u32_e32 v4, v4
	v_div_scale_f32 v5, s[16:17], v4, v4, 1.0
	v_rcp_f32_e32 v6, v5
	v_div_scale_f32 v7, vcc, 1.0, v4, 1.0
	v_fma_f32 v15, -v5, v6, 1.0
	v_fmac_f32_e32 v6, v15, v6
	v_mul_f32_e32 v15, v7, v6
	v_fma_f32 v28, -v5, v15, v7
	v_fmac_f32_e32 v15, v28, v6
	v_fma_f32 v5, -v5, v15, v7
	v_div_fmas_f32 v5, v5, v6, v15
	v_div_fixup_f32 v4, v5, v4, 1.0
	v_lshlrev_b32_e32 v6, 16, v82
	v_and_b32_e32 v7, 0xffff0000, v82
	v_lshlrev_b32_e32 v0, 16, v83
	v_and_b32_e32 v1, 0xffff0000, v83
	v_lshlrev_b32_e32 v28, 16, v84
	v_and_b32_e32 v29, 0xffff0000, v84
	v_lshlrev_b32_e32 v2, 16, v85
	v_and_b32_e32 v3, 0xffff0000, v85
	v_pk_add_f32 v[20:21], v[20:21], v[0:1]
	v_pk_add_f32 v[18:19], v[18:19], v[6:7]
	v_pk_add_f32 v[22:23], v[22:23], v[2:3]
	v_pk_add_f32 v[16:17], v[16:17], v[28:29]
	v_xor_b32_e32 v1, 0x80000000, v1
	v_xor_b32_e32 v0, 0x80000000, v0
	v_xor_b32_e32 v7, 0x80000000, v7
	v_xor_b32_e32 v6, 0x80000000, v6
	v_xor_b32_e32 v3, 0x80000000, v3
	v_xor_b32_e32 v2, 0x80000000, v2
	v_xor_b32_e32 v29, 0x80000000, v29
	v_xor_b32_e32 v28, 0x80000000, v28
	v_pk_fma_f32 v[30:31], v[4:5], v[20:21], v[0:1] op_sel_hi:[0,1,1]
	v_pk_fma_f32 v[0:1], v[4:5], v[18:19], v[6:7] op_sel_hi:[0,1,1]
	v_pk_fma_f32 v[6:7], v[4:5], v[22:23], v[2:3] op_sel_hi:[0,1,1]
	v_pk_fma_f32 v[2:3], v[4:5], v[16:17], v[28:29] op_sel_hi:[0,1,1]
	v_cvt_pk_bf16_f32 v0, v0, v1
	v_cvt_pk_bf16_f32 v1, v30, v31
	v_cvt_pk_bf16_f32 v2, v2, v3
	v_cvt_pk_bf16_f32 v3, v6, v7
	global_store_dwordx4 v[24:25], v[0:3], off
	v_add_u32_e32 v60, s26, v14
	v_cmp_le_i32_e32 vcc, -1, v60
	s_and_saveexec_b64 s[16:17], vcc
	v_lshlrev_b32_e32 v162, 16, v114
	v_and_b32_e32 v163, 0xffff0000, v114
	v_lshlrev_b32_e32 v164, 16, v115
	v_and_b32_e32 v165, 0xffff0000, v115
	v_lshlrev_b32_e32 v166, 16, v116
	v_and_b32_e32 v167, 0xffff0000, v116
	v_lshlrev_b32_e32 v168, 16, v117
	v_and_b32_e32 v169, 0xffff0000, v117
	s_or_b64 exec, exec, s[16:17]
	v_sub_f32_e32 v21, v21, v165
	v_sub_f32_e32 v20, v20, v164
	v_sub_f32_e32 v19, v19, v163
	v_sub_f32_e32 v18, v18, v162
	v_sub_f32_e32 v23, v23, v169
	v_sub_f32_e32 v22, v22, v168
	v_sub_f32_e32 v17, v17, v167
	v_sub_f32_e32 v16, v16, v166
	s_mov_b64 s[16:17], 0x800
	v_lshl_add_u64 v[24:25], v[24:25], 0, s[16:17]
	v_lshl_add_u64 v[26:27], v[26:27], 0, s[96:97]
	s_add_i32 s26, s8, 5
	v_add3_u32 v4, v8, s26, 1
	v_min_i32_e32 v4, v4, v36
	v_cndmask_b32_e64 v4, v36, v4, s[36:37]
	v_cvt_f32_u32_e32 v4, v4
	v_div_scale_f32 v5, s[16:17], v4, v4, 1.0
	v_rcp_f32_e32 v6, v5
	v_div_scale_f32 v7, vcc, 1.0, v4, 1.0
	v_fma_f32 v15, -v5, v6, 1.0
	v_fmac_f32_e32 v6, v15, v6
	v_mul_f32_e32 v15, v7, v6
	v_fma_f32 v28, -v5, v15, v7
	v_fmac_f32_e32 v15, v28, v6
	v_fma_f32 v5, -v5, v15, v7
	v_div_fmas_f32 v5, v5, v6, v15
	v_div_fixup_f32 v4, v5, v4, 1.0
	v_lshlrev_b32_e32 v6, 16, v86
	v_and_b32_e32 v7, 0xffff0000, v86
	v_lshlrev_b32_e32 v0, 16, v87
	v_and_b32_e32 v1, 0xffff0000, v87
	v_lshlrev_b32_e32 v28, 16, v88
	v_and_b32_e32 v29, 0xffff0000, v88
	v_lshlrev_b32_e32 v2, 16, v89
	v_and_b32_e32 v3, 0xffff0000, v89
	v_pk_add_f32 v[20:21], v[20:21], v[0:1]
	v_pk_add_f32 v[18:19], v[18:19], v[6:7]
	v_pk_add_f32 v[22:23], v[22:23], v[2:3]
	v_pk_add_f32 v[16:17], v[16:17], v[28:29]
	v_xor_b32_e32 v1, 0x80000000, v1
	v_xor_b32_e32 v0, 0x80000000, v0
	v_xor_b32_e32 v7, 0x80000000, v7
	v_xor_b32_e32 v6, 0x80000000, v6
	v_xor_b32_e32 v3, 0x80000000, v3
	v_xor_b32_e32 v2, 0x80000000, v2
	v_xor_b32_e32 v29, 0x80000000, v29
	v_xor_b32_e32 v28, 0x80000000, v28
	v_pk_fma_f32 v[30:31], v[4:5], v[20:21], v[0:1] op_sel_hi:[0,1,1]
	v_pk_fma_f32 v[0:1], v[4:5], v[18:19], v[6:7] op_sel_hi:[0,1,1]
	v_pk_fma_f32 v[6:7], v[4:5], v[22:23], v[2:3] op_sel_hi:[0,1,1]
	v_pk_fma_f32 v[2:3], v[4:5], v[16:17], v[28:29] op_sel_hi:[0,1,1]
	v_cvt_pk_bf16_f32 v0, v0, v1
	v_cvt_pk_bf16_f32 v1, v30, v31
	v_cvt_pk_bf16_f32 v2, v2, v3
	v_cvt_pk_bf16_f32 v3, v6, v7
	global_store_dwordx4 v[24:25], v[0:3], off
	v_add_u32_e32 v60, s26, v14
	v_cmp_le_i32_e32 vcc, -1, v60
	s_and_saveexec_b64 s[16:17], vcc
	v_lshlrev_b32_e32 v170, 16, v118
	v_and_b32_e32 v171, 0xffff0000, v118
	v_lshlrev_b32_e32 v172, 16, v119
	v_and_b32_e32 v173, 0xffff0000, v119
	v_lshlrev_b32_e32 v174, 16, v120
	v_and_b32_e32 v175, 0xffff0000, v120
	v_lshlrev_b32_e32 v176, 16, v121
	v_and_b32_e32 v177, 0xffff0000, v121
	s_or_b64 exec, exec, s[16:17]
	v_sub_f32_e32 v21, v21, v173
	v_sub_f32_e32 v20, v20, v172
	v_sub_f32_e32 v19, v19, v171
	v_sub_f32_e32 v18, v18, v170
	v_sub_f32_e32 v23, v23, v177
	v_sub_f32_e32 v22, v22, v176
	v_sub_f32_e32 v17, v17, v175
	v_sub_f32_e32 v16, v16, v174
; DI u32x4 v8_pack(const V8& v) { u32x4 w; w.x = pk2(v.a.x, v.a.y); w.y = pk2(v.a.z, v.a.w); w.z = pk2(v.b.x, v.b.y); w.w = pk2(v.b.z, v.b.w); return w; }
; #define POOL_LD(tt, dst) do { const int _t = (tt); if (_t >= 0) dst = v8_ldbf(XN + (seq0 + _t) * D + c0); else if (s) dst = v8_ldf(sp + ((size_t)b * 15 + 15 + _t) * D + c0); else dst = v8zero(); } while (0)
; DI void pool_diff(const Params& p, int pool_j, int gtid, int NT) {
;     ...
;         for (int r = 0; r < 32; ++r) {
;             const int t = t0 + r; V8 cur; POOL_LD(t, cur); sum.a += cur.a; sum.b += cur.b;
;             const float cnt = s ? (float)win : (float)((t + 1) < win ? (t + 1) : win); const float inv = 1.f / cnt;
;             V8 d; d.a = sum.a * inv - cur.a; d.b = sum.b * inv - cur.b;
;             *(u32x4*)(Dd + (size_t)(row0 + r) * D + c0) = v8_pack(d);
;             V8 old; POOL_LD(t - win + 1, old); sum.a -= old.a; sum.b -= old.b;
;         }
	s_mov_b64 s[16:17], 0x800
	v_lshl_add_u64 v[24:25], v[24:25], 0, s[16:17]
	v_lshl_add_u64 v[26:27], v[26:27], 0, s[96:97]
	s_add_i32 s26, s8, 6
	v_add3_u32 v4, v8, s26, 1
	v_min_i32_e32 v4, v4, v36
	v_cndmask_b32_e64 v4, v36, v4, s[36:37]
	v_cvt_f32_u32_e32 v4, v4
	v_div_scale_f32 v5, s[16:17], v4, v4, 1.0
	v_rcp_f32_e32 v6, v5
	v_div_scale_f32 v7, vcc, 1.0, v4, 1.0
	v_fma_f32 v15, -v5, v6, 1.0
	v_fmac_f32_e32 v6, v15, v6
	v_mul_f32_e32 v15, v7, v6
	v_fma_f32 v28, -v5, v15, v7
	v_fmac_f32_e32 v15, v28, v6
	v_fma_f32 v5, -v5, v15, v7
	v_div_fmas_f32 v5, v5, v6, v15
	v_div_fixup_f32 v4, v5, v4, 1.0
	v_lshlrev_b32_e32 v6, 16, v90
	v_and_b32_e32 v7, 0xffff0000, v90
	v_lshlrev_b32_e32 v0, 16, v91
	v_and_b32_e32 v1, 0xffff0000, v91
	v_lshlrev_b32_e32 v28, 16, v92
	v_and_b32_e32 v29, 0xffff0000, v92
	v_lshlrev_b32_e32 v2, 16, v93
	v_and_b32_e32 v3, 0xffff0000, v93
	v_pk_add_f32 v[20:21], v[20:21], v[0:1]
	v_pk_add_f32 v[18:19], v[18:19], v[6:7]
	v_pk_add_f32 v[22:23], v[22:23], v[2:3]
	v_pk_add_f32 v[16:17], v[16:17], v[28:29]
	v_xor_b32_e32 v1, 0x80000000, v1
	v_xor_b32_e32 v0, 0x80000000, v0
	v_xor_b32_e32 v7, 0x80000000, v7
	v_xor_b32_e32 v6, 0x80000000, v6
	v_xor_b32_e32 v3, 0x80000000, v3
	v_xor_b32_e32 v2, 0x80000000, v2
	v_xor_b32_e32 v29, 0x80000000, v29
	v_xor_b32_e32 v28, 0x80000000, v28
	v_pk_fma_f32 v[30:31], v[4:5], v[20:21], v[0:1] op_sel_hi:[0,1,1]
	v_pk_fma_f32 v[0:1], v[4:5], v[18:19], v[6:7] op_sel_hi:[0,1,1]
	v_pk_fma_f32 v[6:7], v[4:5], v[22:23], v[2:3] op_sel_hi:[0,1,1]
	v_pk_fma_f32 v[2:3], v[4:5], v[16:17], v[28:29] op_sel_hi:[0,1,1]
	v_cvt_pk_bf16_f32 v0, v0, v1
	v_cvt_pk_bf16_f32 v1, v30, v31
	v_cvt_pk_bf16_f32 v2, v2, v3
	v_cvt_pk_bf16_f32 v3, v6, v7
	global_store_dwordx4 v[24:25], v[0:3], off
	v_add_u32_e32 v60, s26, v14
	v_cmp_le_i32_e32 vcc, -1, v60
	s_and_saveexec_b64 s[16:17], vcc
	v_lshlrev_b32_e32 v178, 16, v122
	v_and_b32_e32 v179, 0xffff0000, v122
	v_lshlrev_b32_e32 v180, 16, v123
	v_and_b32_e32 v181, 0xffff0000, v123
	v_lshlrev_b32_e32 v182, 16, v124
	v_and_b32_e32 v183, 0xffff0000, v124
	v_lshlrev_b32_e32 v184, 16, v125
	v_and_b32_e32 v185, 0xffff0000, v125
	s_or_b64 exec, exec, s[16:17]
	v_sub_f32_e32 v21, v21, v181
	v_sub_f32_e32 v20, v20, v180
	v_sub_f32_e32 v19, v19, v179
	v_sub_f32_e32 v18, v18, v178
	v_sub_f32_e32 v23, v23, v185
	v_sub_f32_e32 v22, v22, v184
	v_sub_f32_e32 v17, v17, v183
	v_sub_f32_e32 v16, v16, v182
	s_mov_b64 s[16:17], 0x800
	v_lshl_add_u64 v[24:25], v[24:25], 0, s[16:17]
	v_lshl_add_u64 v[26:27], v[26:27], 0, s[96:97]
	s_add_i32 s26, s8, 7
	v_add3_u32 v4, v8, s26, 1
	v_min_i32_e32 v4, v4, v36
	v_cndmask_b32_e64 v4, v36, v4, s[36:37]
	v_cvt_f32_u32_e32 v4, v4
	v_div_scale_f32 v5, s[16:17], v4, v4, 1.0
	v_rcp_f32_e32 v6, v5
	v_div_scale_f32 v7, vcc, 1.0, v4, 1.0
	v_fma_f32 v15, -v5, v6, 1.0
	v_fmac_f32_e32 v6, v15, v6
	v_mul_f32_e32 v15, v7, v6
	v_fma_f32 v28, -v5, v15, v7
	v_fmac_f32_e32 v15, v28, v6
	v_fma_f32 v5, -v5, v15, v7
	v_div_fmas_f32 v5, v5, v6, v15
	v_div_fixup_f32 v4, v5, v4, 1.0
	v_lshlrev_b32_e32 v6, 16, v94
	v_and_b32_e32 v7, 0xffff0000, v94
	v_lshlrev_b32_e32 v0, 16, v95
	v_and_b32_e32 v1, 0xffff0000, v95
	v_lshlrev_b32_e32 v28, 16, v96
	v_and_b32_e32 v29, 0xffff0000, v96
	v_lshlrev_b32_e32 v2, 16, v97
	v_and_b32_e32 v3, 0xffff0000, v97
	v_pk_add_f32 v[20:21], v[20:21], v[0:1]
	v_pk_add_f32 v[18:19], v[18:19], v[6:7]
	v_pk_add_f32 v[22:23], v[22:23], v[2:3]
	v_pk_add_f32 v[16:17], v[16:17], v[28:29]
	v_xor_b32_e32 v1, 0x80000000, v1
	v_xor_b32_e32 v0, 0x80000000, v0
	v_xor_b32_e32 v7, 0x80000000, v7
	v_xor_b32_e32 v6, 0x80000000, v6
	v_xor_b32_e32 v3, 0x80000000, v3
	v_xor_b32_e32 v2, 0x80000000, v2
	v_xor_b32_e32 v29, 0x80000000, v29
	v_xor_b32_e32 v28, 0x80000000, v28
	v_pk_fma_f32 v[30:31], v[4:5], v[20:21], v[0:1] op_sel_hi:[0,1,1]
	v_pk_fma_f32 v[0:1], v[4:5], v[18:19], v[6:7] op_sel_hi:[0,1,1]
	v_pk_fma_f32 v[6:7], v[4:5], v[22:23], v[2:3] op_sel_hi:[0,1,1]
	v_pk_fma_f32 v[2:3], v[4:5], v[16:17], v[28:29] op_sel_hi:[0,1,1]
	v_cvt_pk_bf16_f32 v0, v0, v1
	v_cvt_pk_bf16_f32 v1, v30, v31
	v_cvt_pk_bf16_f32 v2, v2, v3
	v_cvt_pk_bf16_f32 v3, v6, v7
	global_store_dwordx4 v[24:25], v[0:3], off
	v_add_u32_e32 v60, s26, v14
	v_cmp_le_i32_e32 vcc, -1, v60
	s_and_saveexec_b64 s[16:17], vcc
	v_lshlrev_b32_e32 v186, 16, v126
	v_and_b32_e32 v187, 0xffff0000, v126
	v_lshlrev_b32_e32 v188, 16, v127
	v_and_b32_e32 v189, 0xffff0000, v127
	v_lshlrev_b32_e32 v190, 16, v128
	v_and_b32_e32 v191, 0xffff0000, v128
	v_lshlrev_b32_e32 v192, 16, v129
	v_and_b32_e32 v193, 0xffff0000, v129
	s_or_b64 exec, exec, s[16:17]
	v_sub_f32_e32 v21, v21, v189
	v_sub_f32_e32 v20, v20, v188
	v_sub_f32_e32 v19, v19, v187
	v_sub_f32_e32 v18, v18, v186
	v_sub_f32_e32 v23, v23, v193
	v_sub_f32_e32 v22, v22, v192
	v_sub_f32_e32 v17, v17, v191
	v_sub_f32_e32 v16, v16, v190
	s_mov_b64 s[16:17], 0x800
	v_lshl_add_u64 v[24:25], v[24:25], 0, s[16:17]
	v_lshl_add_u64 v[26:27], v[26:27], 0, s[96:97]
	s_add_i32 s8, s8, 8
	s_cmp_eq_u32 s8, 32
	s_cbranch_scc1 .LBB0_1400
	s_branch .LBB0_1411

; __device__ __forceinline__ unsigned xb_ld(unsigned* p)              { return __hip_atomic_load(p, __ATOMIC_RELAXED, __HIP_MEMORY_SCOPE_AGENT); }
; __device__ __forceinline__ void xcd_barrier_complete(unsigned* bar, unsigned x, unsigned& nloc, unsigned& nx) {
;     const unsigned G = gridDim.x * gridDim.y * gridDim.z;
;     unsigned sum, cnt, mine, sp = 0u;
;     for (;;) {
;         sum = 0u; cnt = 0u; mine = 0u;
; #pragma unroll
;         for (unsigned j = 0; j < 16; ++j) { const unsigned c = xb_ld(&bar[XB_XCNT(j)]); sum += c; cnt += (c > 0u) ? 1u : 0u; mine = (j == x) ? c : mine; }
;         if (sum == G) break;
;         __builtin_amdgcn_s_sleep(1);
;         if ((++sp & 255u) == 0u) { if (xb_ld(&bar[XB_TMO])) break; if (sp > XB_SPIN_CAP) { atomicAdd(&bar[XB_TMO], 1u); break; } }
;     }
.LBB0_1612:
	v_readlane_b32 s4, v254, 26
	v_readlane_b32 s5, v254, 27
	s_mov_b64 s[6:7], -1
	s_nop 4
	global_load_dword v0, v65, s[4:5] sc1
	v_readlane_b32 s4, v254, 28
	v_readlane_b32 s5, v254, 29
	s_nop 4
	global_load_dword v1, v65, s[4:5] sc1
	s_nop 4
	global_load_dword v2, v65, s[22:23] sc1
	s_nop 4
	global_load_dword v3, v65, s[90:91] sc1
	s_nop 4
	global_load_dword v4, v65, s[84:85] sc1
	s_nop 4
	global_load_dword v5, v65, s[30:31] sc1
	s_nop 4
	global_load_dword v6, v65, s[18:19] sc1
	s_nop 4
	global_load_dword v7, v65, s[26:27] sc1
	v_readlane_b32 s4, v252, 6
	v_readlane_b32 s5, v252, 7
	s_nop 4
	global_load_dword v8, v65, s[4:5] sc1
	v_readlane_b32 s4, v252, 8
	v_readlane_b32 s5, v252, 9
	s_nop 4
	global_load_dword v9, v65, s[4:5] sc1
	v_readlane_b32 s4, v252, 10
	v_readlane_b32 s5, v252, 11
	s_nop 4
	global_load_dword v10, v65, s[4:5] sc1
	v_readlane_b32 s4, v252, 12
	v_readlane_b32 s5, v252, 13
	s_nop 4
	global_load_dword v11, v65, s[4:5] sc1
	v_readlane_b32 s4, v252, 14
	v_readlane_b32 s5, v252, 15
	s_nop 4
	global_load_dword v12, v65, s[4:5] sc1
	v_readlane_b32 s4, v252, 16
	v_readlane_b32 s5, v252, 17
	s_nop 4
	global_load_dword v13, v65, s[4:5] sc1
	v_readlane_b32 s4, v252, 18
	v_readlane_b32 s5, v252, 19
	s_nop 4
	global_load_dword v14, v65, s[4:5] sc1
	v_readlane_b32 s4, v252, 20
	v_readlane_b32 s5, v252, 21
	s_nop 4
	global_load_dword v15, v65, s[4:5] sc1
	s_mov_b64 s[4:5], -1
	s_waitcnt vmcnt(0)
	v_add_u32_e32 v16, v1, v0
	v_add_u32_e32 v16, v16, v2
	v_add_u32_e32 v16, v16, v3
	v_add_u32_e32 v16, v16, v4
	v_add_u32_e32 v16, v16, v5
	v_add_u32_e32 v16, v16, v6
	v_add_u32_e32 v16, v16, v7
	v_add_u32_e32 v16, v16, v8
	v_add_u32_e32 v16, v16, v9
	v_add_u32_e32 v16, v16, v10
	v_add_u32_e32 v16, v16, v11
	v_add_u32_e32 v16, v16, v12
	v_add_u32_e32 v16, v16, v13
	v_add_u32_e32 v16, v16, v14
	v_add_u32_e32 v16, v16, v15
	v_cmp_eq_u32_e32 vcc, s8, v16
	s_cbranch_vccnz .LBB0_1611
	s_and_b32 s4, s12, 0xff
	s_cmp_eq_u32 s4, 0
	s_mov_b64 s[4:5], -1
	s_mov_b64 s[10:11], -1
	s_sleep 1
	s_cbranch_scc1 .LBB0_1616
	s_and_b64 vcc, exec, s[10:11]
	s_cbranch_vccz .LBB0_1611
